# all GEMM-epilogue flat_load/flat_store instructions re-encoded as global_load/global_store (same addresses, global memory only): they no longer occupy the LDS path or count on lgkmcnt
# speedup vs baseline: 1.0825x; 1.0047x over previous
.LBB0_472:
	s_add_i32 s1, s12, -16
	s_lshr_b32 s1, s1, 2
	s_mulk_i32 s1, 0xb00
	s_addk_i32 s1, 0xb00
	s_cmp_lt_i32 s12, 16
	s_cselect_b64 s[6:7], -1, 0
	v_mov_b32_e32 v64, v177
	v_mov_b32_e32 v162, v176
	s_and_b64 s[34:35], s[6:7], exec
	s_cselect_b32 s96, 0, s1
	v_lshlrev_b32_e32 v159, 3, v64
	v_add_u32_e32 v158, s61, v159
	s_lshl_b64 s[34:35], s[96:97], 2
	v_lshl_add_u32 v160, s0, 8, v158
	s_add_u32 s34, s53, s34
	s_addc_u32 s35, s79, s35
	v_ashrrev_i32_e32 v161, 31, v160
	v_lshl_add_u64 v[24:25], v[160:161], 2, s[34:35]
	global_load_dwordx4 v[40:43], v[24:25], off
	global_load_dwordx4 v[36:39], v[24:25], off offset:16
	global_load_dwordx4 v[28:31], v[24:25], off offset:512
	s_nop 0
	global_load_dwordx4 v[24:27], v[24:25], off offset:528
	s_cmp_lt_u32 s0, 11
	s_cselect_b64 s[34:35], -1, 0
	s_and_b64 s[6:7], s[6:7], s[34:35]
	s_andn2_b64 vcc, exec, s[6:7]
	s_mov_b64 s[34:35], 0
	s_cbranch_vccnz .LBB0_474
	s_lshr_b32 s1, 0x680, s0
	s_bitcmp1_b32 s1, 0
	s_cselect_b64 s[34:35], -1, 0

.LBB0_487:
	s_lshl_b32 s13, s12, 8
	v_add_u32_e32 v170, s60, v162
	v_add_u32_e32 v168, s13, v170
	v_ashrrev_i32_e32 v169, 31, v168
	v_lshlrev_b32_e32 v166, 2, v64
	v_lshlrev_b64 v[162:163], 6, v[168:169]
	v_ashrrev_i32_e32 v167, 31, v166
	v_lshl_add_u64 v[162:163], s[14:15], 0, v[162:163]
	v_lshl_add_u64 v[162:163], v[166:167], 2, v[162:163]
	global_load_dwordx4 v[162:165], v[162:163], off
	v_and_b32_e32 v169, 0x3ff, v168
	s_cmp_gt_i32 s23, 63
	s_waitcnt vmcnt(0) lgkmcnt(0)
	v_add_f32_e32 v64, v162, v163
	v_add_f32_e32 v162, v164, v165
	v_add_f32_e32 v64, v64, v162
	v_mov_b32_e32 v162, v64
	s_nop 1
	v_permlane16_swap_b32_e32 v64, v162
	v_add_f32_e32 v64, v64, v162
	v_mov_b32_e32 v162, v64
	s_nop 1
	v_permlane32_swap_b32_e32 v64, v162
	v_add_f32_e32 v64, v64, v162
	v_and_b32_e32 v163, 56, v158
	v_fmamk_f32 v171, v64, 0x3a800000, v229
	v_lshlrev_b32_e32 v64, 6, v169
	v_cmp_gt_f32_e32 vcc, s55, v171
	v_lshlrev_b32_e32 v64, 2, v64
	v_lshlrev_b32_e32 v162, 2, v163
	s_cbranch_scc0 .LBB0_489
	v_lshl_add_u64 v[164:165], s[16:17], 0, v[64:65]
	v_mov_b32_e32 v163, v65
	v_lshl_add_u64 v[164:165], v[164:165], 0, v[162:163]
	s_mov_b64 s[56:57], 0
	s_mov_b64 s[6:7], -1
	s_branch .LBB0_490

.LBB0_493:
	s_and_b64 vcc, exec, s[6:7]
	s_cbranch_vccz .LBB0_495
	global_load_dwordx4 v[184:187], v[164:165], off
	global_load_dwordx4 v[196:199], v[164:165], off offset:16
	s_waitcnt vmcnt(0) lgkmcnt(0)
	v_pk_mul_f32 v[174:175], v[142:143], v[184:185] op_sel:[1,1] op_sel_hi:[1,0]
	v_pk_mul_f32 v[164:165], v[142:143], v[184:185]
	v_pk_fma_f32 v[142:143], v[142:143], v[184:185], v[174:175] op_sel_hi:[0,1,1]
	v_mul_f32_e32 v142, v145, v187
	v_pk_fma_f32 v[184:185], v[144:145], v[186:187], v[142:143] op_sel_hi:[1,1,0] neg_lo:[0,0,1] neg_hi:[0,0,1]
	v_mul_f32_e32 v142, v145, v186
	v_pk_mul_f32 v[188:189], v[138:139], v[196:197] op_sel:[1,1] op_sel_hi:[1,0]
	v_pk_fma_f32 v[186:187], v[144:145], v[186:187], v[142:143] op_sel:[0,1,0] op_sel_hi:[1,0,0]
	v_pk_mul_f32 v[144:145], v[138:139], v[196:197]
	v_pk_fma_f32 v[138:139], v[138:139], v[196:197], v[188:189] op_sel_hi:[0,1,1]
	v_mul_f32_e32 v138, v141, v199
	v_pk_fma_f32 v[196:197], v[140:141], v[198:199], v[138:139] op_sel_hi:[1,1,0] neg_lo:[0,0,1] neg_hi:[0,0,1]
	v_mul_f32_e32 v138, v141, v198
	v_pk_fma_f32 v[198:199], v[140:141], v[198:199], v[138:139] op_sel:[0,1,0] op_sel_hi:[1,0,0]
	v_sub_f32_e32 v138, v144, v188
	v_sub_f32_e32 v142, v164, v174
	v_mov_b32_e32 v140, v196
	v_mov_b32_e32 v141, v198
	v_mov_b32_e32 v144, v184
	v_mov_b32_e32 v145, v186
.LBB0_495:
	v_lshrrev_b32_e32 v159, 1, v159
	v_and_b32_e32 v169, 12, v159
	v_lshrrev_b32_e32 v159, 1, v158
	v_mov_b64_e32 v[174:175], s[10:11]
	v_and_b32_e32 v164, 0xffffffc0, v158
	v_and_b32_e32 v181, 28, v159
	v_mad_i64_i32 v[174:175], s[6:7], v168, s93, v[174:175]
	v_cndmask_b32_e64 v159, 0, 1, s[34:35]
	v_ashrrev_i32_e32 v165, 31, v164
	v_cvt_pk_bf16_f32 v184, v142, v143
	v_cvt_pk_bf16_f32 v185, v144, v145
	v_cvt_pk_bf16_f32 v186, v138, v139
	v_cvt_pk_bf16_f32 v187, v140, v141
	v_lshl_add_u64 v[174:175], v[160:161], 1, v[174:175]
	v_cmp_ne_u32_e64 s[6:7], 1, v159
	s_andn2_b64 vcc, exec, s[34:35]
	global_store_dwordx4 v[174:175], v[184:187], off
	s_cbranch_vccnz .LBB0_506
	s_lshl_b32 s25, s12, 2
	s_add_i32 s34, s25, s74
	s_ashr_i32 s35, s34, 31
	s_mov_b64 s[66:67], -1
	s_mov_b64 s[56:57], 0
	s_cmp_lt_i32 s0, 9
	s_mov_b64 s[76:77], 0
	s_cbranch_scc1 .LBB0_502
	s_cmp_eq_u32 s0, 9
	s_mov_b64 s[76:77], -1
	s_cbranch_scc0 .LBB0_499
	s_lshl_b64 s[66:67], s[34:35], 18
	v_ashrrev_i32_e32 v171, 31, v170
	s_add_u32 s66, s48, s66
	s_addc_u32 s67, s49, s67
	v_lshlrev_b64 v[184:185], 10, v[170:171]
	v_and_b32_e32 v186, 0xffffffe0, v158
	v_lshl_add_u64 v[184:185], s[66:67], 0, v[184:185]
	v_ashrrev_i32_e32 v187, 31, v186
	v_lshl_add_u64 v[184:185], v[186:187], 2, v[184:185]
	v_lshlrev_b32_e32 v186, 2, v169
	v_mov_b32_e32 v187, v65
	v_lshl_add_u64 v[188:189], v[184:185], 0, v[186:187]
	v_mov_b32_e32 v184, v142
	v_mov_b32_e32 v185, v144
	v_mov_b32_e32 v186, v138
	v_mov_b32_e32 v187, v140
	global_store_dwordx4 v[188:189], v[184:187], off
	s_mov_b64 s[76:77], 0
	s_nop 0
	v_mov_b32_e32 v184, v143
	v_mov_b32_e32 v185, v145
	v_mov_b32_e32 v186, v139
	v_mov_b32_e32 v187, v141
	global_store_dwordx4 v[188:189], v[184:187], off offset:64

.LBB0_512:
	s_and_b64 vcc, exec, s[34:35]
	s_cbranch_vccz .LBB0_514
	global_load_dwordx4 v[140:143], v[138:139], off
	global_load_dwordx4 v[182:185], v[138:139], off offset:16
	s_waitcnt vmcnt(0) lgkmcnt(0)
	v_pk_mul_f32 v[144:145], v[134:135], v[140:141] op_sel:[1,1] op_sel_hi:[1,0]
	v_mul_f32_e32 v64, v137, v143
	v_pk_mul_f32 v[138:139], v[134:135], v[140:141]
	v_pk_fma_f32 v[134:135], v[134:135], v[140:141], v[144:145] op_sel_hi:[0,1,1]
	v_pk_fma_f32 v[140:141], v[136:137], v[142:143], v[64:65] op_sel_hi:[1,1,0] neg_lo:[0,0,1] neg_hi:[0,0,1]
	v_mul_f32_e32 v64, v137, v142
	v_pk_fma_f32 v[142:143], v[136:137], v[142:143], v[64:65] op_sel:[0,1,0] op_sel_hi:[1,0,0]
	v_pk_mul_f32 v[172:173], v[130:131], v[182:183] op_sel:[1,1] op_sel_hi:[1,0]
	v_mul_f32_e32 v64, v133, v185
	v_pk_mul_f32 v[136:137], v[130:131], v[182:183]
	v_pk_fma_f32 v[130:131], v[130:131], v[182:183], v[172:173] op_sel_hi:[0,1,1]
	v_pk_fma_f32 v[182:183], v[132:133], v[184:185], v[64:65] op_sel_hi:[1,1,0] neg_lo:[0,0,1] neg_hi:[0,0,1]
	v_mul_f32_e32 v64, v133, v184
	v_pk_fma_f32 v[184:185], v[132:133], v[184:185], v[64:65] op_sel:[0,1,0] op_sel_hi:[1,0,0]
	v_sub_f32_e32 v130, v136, v172
	v_sub_f32_e32 v134, v138, v144
	v_mov_b32_e32 v132, v182
	v_mov_b32_e32 v133, v184
	v_mov_b32_e32 v136, v140
	v_mov_b32_e32 v137, v142
.LBB0_514:
	v_add_u32_e32 v140, 0x80, v158
	v_cvt_pk_bf16_f32 v142, v134, v135
	v_cvt_pk_bf16_f32 v143, v136, v137
	v_cvt_pk_bf16_f32 v144, v130, v131
	v_cvt_pk_bf16_f32 v145, v132, v133
	s_and_b64 vcc, exec, s[6:7]
	global_store_dwordx4 v[174:175], v[142:145], off offset:256
	s_cbranch_vccnz .LBB0_523
	s_lshl_b32 s25, s12, 2
	s_add_i32 s34, s25, s74
	s_ashr_i32 s35, s34, 31
	v_ashrrev_i32_e32 v171, 31, v170
	s_mov_b64 s[66:67], -1
	s_mov_b64 s[56:57], 0
	s_cmp_lt_i32 s0, 9
	s_mov_b64 s[76:77], 0
	s_cbranch_scc1 .LBB0_525
	s_cmp_eq_u32 s0, 9
	s_mov_b64 s[76:77], -1
	s_cbranch_scc0 .LBB0_518
	s_lshl_b64 s[66:67], s[34:35], 18
	s_add_u32 s66, s48, s66
	s_addc_u32 s67, s49, s67
	v_lshlrev_b64 v[138:139], 10, v[170:171]
	v_and_b32_e32 v142, 0xffffffe0, v140
	v_lshl_add_u64 v[138:139], s[66:67], 0, v[138:139]
	v_ashrrev_i32_e32 v143, 31, v142
	v_lshl_add_u64 v[138:139], v[142:143], 2, v[138:139]
	v_lshlrev_b32_e32 v64, 2, v169
	v_lshl_add_u64 v[138:139], v[138:139], 0, v[64:65]
	v_mov_b32_e32 v142, v134
	v_mov_b32_e32 v143, v136
	v_mov_b32_e32 v144, v130
	v_mov_b32_e32 v145, v132
	global_store_dwordx4 v[138:139], v[142:145], off
	s_mov_b64 s[76:77], 0
	s_nop 0
	v_mov_b32_e32 v142, v135
	v_mov_b32_e32 v143, v137
	v_mov_b32_e32 v144, v131
	v_mov_b32_e32 v145, v133
	global_store_dwordx4 v[138:139], v[142:145], off offset:64

.LBB0_523:
	s_nop 1
	v_add_u32_e32 v130, 16, v168
	v_ashrrev_i32_e32 v131, 31, v130
	v_lshlrev_b64 v[132:133], 6, v[130:131]
	v_lshl_add_u64 v[132:133], s[14:15], 0, v[132:133]
	v_lshl_add_u64 v[132:133], v[166:167], 2, v[132:133]
	global_load_dwordx4 v[132:135], v[132:133], off
	s_cmp_gt_i32 s23, 63
	s_waitcnt vmcnt(0) lgkmcnt(0)
	v_add_f32_e32 v64, v132, v133
	v_add_f32_e32 v131, v134, v135
	v_add_f32_e32 v64, v64, v131
	v_mov_b32_e32 v131, v64
	s_nop 1
	v_permlane16_swap_b32_e32 v64, v131
	v_add_f32_e32 v64, v64, v131
	v_mov_b32_e32 v131, v64
	s_nop 1
	v_permlane32_swap_b32_e32 v64, v131
	v_add_f32_e32 v64, v64, v131
	v_and_b32_e32 v131, 0x3ff, v130
	v_fmamk_f32 v132, v64, 0x3a800000, v229
	v_lshlrev_b32_e32 v64, 6, v131
	v_cmp_gt_f32_e32 vcc, s55, v132
	v_lshlrev_b32_e32 v64, 2, v64
	s_cbranch_scc0 .LBB0_529
	v_lshl_add_u64 v[134:135], s[16:17], 0, v[64:65]
	v_mov_b32_e32 v163, v65
	v_lshl_add_u64 v[134:135], v[134:135], 0, v[162:163]
	s_mov_b64 s[56:57], 0
	s_mov_b64 s[34:35], -1
	s_branch .LBB0_530

.LBB0_533:
	s_and_b64 vcc, exec, s[34:35]
	s_cbranch_vccz .LBB0_535
	global_load_dwordx4 v[142:145], v[134:135], off
	global_load_dwordx4 v[170:173], v[134:135], off offset:16
	s_waitcnt vmcnt(0) lgkmcnt(0)
	v_pk_mul_f32 v[138:139], v[126:127], v[142:143] op_sel:[1,1] op_sel_hi:[1,0]
	v_pk_mul_f32 v[134:135], v[126:127], v[142:143]
	v_pk_fma_f32 v[126:127], v[126:127], v[142:143], v[138:139] op_sel_hi:[0,1,1]
	v_mul_f32_e32 v126, v129, v145
	v_pk_fma_f32 v[142:143], v[128:129], v[144:145], v[126:127] op_sel_hi:[1,1,0] neg_lo:[0,0,1] neg_hi:[0,0,1]
	v_mul_f32_e32 v126, v129, v144
	v_pk_mul_f32 v[174:175], v[122:123], v[170:171] op_sel:[1,1] op_sel_hi:[1,0]
	v_pk_fma_f32 v[144:145], v[128:129], v[144:145], v[126:127] op_sel:[0,1,0] op_sel_hi:[1,0,0]
	v_pk_mul_f32 v[128:129], v[122:123], v[170:171]
	v_pk_fma_f32 v[122:123], v[122:123], v[170:171], v[174:175] op_sel_hi:[0,1,1]
	v_mul_f32_e32 v122, v125, v173
	v_pk_fma_f32 v[170:171], v[124:125], v[172:173], v[122:123] op_sel_hi:[1,1,0] neg_lo:[0,0,1] neg_hi:[0,0,1]
	v_mul_f32_e32 v122, v125, v172
	v_pk_fma_f32 v[172:173], v[124:125], v[172:173], v[122:123] op_sel:[0,1,0] op_sel_hi:[1,0,0]
	v_sub_f32_e32 v122, v128, v174
	v_sub_f32_e32 v126, v134, v138
	v_mov_b32_e32 v124, v170
	v_mov_b32_e32 v125, v172
	v_mov_b32_e32 v128, v142
	v_mov_b32_e32 v129, v144
.LBB0_535:
	v_mov_b64_e32 v[134:135], s[10:11]
	v_mad_i64_i32 v[134:135], s[34:35], v130, s93, v[134:135]
	v_cvt_pk_bf16_f32 v142, v126, v127
	v_cvt_pk_bf16_f32 v143, v128, v129
	v_cvt_pk_bf16_f32 v144, v122, v123
	v_cvt_pk_bf16_f32 v145, v124, v125
	v_lshl_add_u64 v[134:135], v[160:161], 1, v[134:135]
	s_and_b64 vcc, exec, s[6:7]
	v_subrev_u32_e32 v130, s13, v130
	global_store_dwordx4 v[134:135], v[142:145], off
	s_cbranch_vccnz .LBB0_546
	s_lshl_b32 s25, s12, 2
	s_add_i32 s34, s25, s74
	s_ashr_i32 s35, s34, 31
	s_mov_b64 s[76:77], -1
	s_mov_b64 s[56:57], 0
	s_cmp_lt_i32 s0, 9
	s_mov_b64 s[66:67], 0
	s_cbranch_scc1 .LBB0_542
	s_cmp_eq_u32 s0, 9
	s_mov_b64 s[66:67], -1
	s_cbranch_scc0 .LBB0_539
	s_lshl_b64 s[66:67], s[34:35], 18
	v_ashrrev_i32_e32 v131, 31, v130
	s_add_u32 s66, s48, s66
	s_addc_u32 s67, s49, s67
	v_lshlrev_b64 v[138:139], 10, v[130:131]
	v_and_b32_e32 v142, 0xffffffe0, v158
	v_lshl_add_u64 v[138:139], s[66:67], 0, v[138:139]
	v_ashrrev_i32_e32 v143, 31, v142
	v_lshl_add_u64 v[138:139], v[142:143], 2, v[138:139]
	v_lshlrev_b32_e32 v142, 2, v169
	v_mov_b32_e32 v143, v65
	v_lshl_add_u64 v[138:139], v[138:139], 0, v[142:143]
	v_mov_b32_e32 v142, v126
	v_mov_b32_e32 v143, v128
	v_mov_b32_e32 v144, v122
	v_mov_b32_e32 v145, v124
	global_store_dwordx4 v[138:139], v[142:145], off
	s_mov_b64 s[66:67], 0
	s_nop 0
	v_mov_b32_e32 v142, v127
	v_mov_b32_e32 v143, v129
	v_mov_b32_e32 v144, v123
	v_mov_b32_e32 v145, v125
	global_store_dwordx4 v[138:139], v[142:145], off offset:64

.LBB0_552:
	s_and_b64 vcc, exec, s[34:35]
	s_cbranch_vccz .LBB0_554
	global_load_dwordx4 v[124:127], v[122:123], off
	global_load_dwordx4 v[136:139], v[122:123], off offset:16
	s_waitcnt vmcnt(0) lgkmcnt(0)
	v_pk_mul_f32 v[128:129], v[118:119], v[124:125] op_sel:[1,1] op_sel_hi:[1,0]
	v_mul_f32_e32 v64, v121, v127
	v_pk_mul_f32 v[122:123], v[118:119], v[124:125]
	v_pk_fma_f32 v[118:119], v[118:119], v[124:125], v[128:129] op_sel_hi:[0,1,1]
	v_pk_fma_f32 v[124:125], v[120:121], v[126:127], v[64:65] op_sel_hi:[1,1,0] neg_lo:[0,0,1] neg_hi:[0,0,1]
	v_mul_f32_e32 v64, v121, v126
	v_pk_fma_f32 v[126:127], v[120:121], v[126:127], v[64:65] op_sel:[0,1,0] op_sel_hi:[1,0,0]
	v_pk_mul_f32 v[132:133], v[114:115], v[136:137] op_sel:[1,1] op_sel_hi:[1,0]
	v_mul_f32_e32 v64, v117, v139
	v_pk_mul_f32 v[120:121], v[114:115], v[136:137]
	v_pk_fma_f32 v[114:115], v[114:115], v[136:137], v[132:133] op_sel_hi:[0,1,1]
	v_pk_fma_f32 v[136:137], v[116:117], v[138:139], v[64:65] op_sel_hi:[1,1,0] neg_lo:[0,0,1] neg_hi:[0,0,1]
	v_mul_f32_e32 v64, v117, v138
	v_pk_fma_f32 v[138:139], v[116:117], v[138:139], v[64:65] op_sel:[0,1,0] op_sel_hi:[1,0,0]
	v_sub_f32_e32 v114, v120, v132
	v_sub_f32_e32 v118, v122, v128
	v_mov_b32_e32 v116, v136
	v_mov_b32_e32 v117, v138
	v_mov_b32_e32 v120, v124
	v_mov_b32_e32 v121, v126
.LBB0_554:
	v_cvt_pk_bf16_f32 v122, v118, v119
	v_cvt_pk_bf16_f32 v123, v120, v121
	v_cvt_pk_bf16_f32 v124, v114, v115
	v_cvt_pk_bf16_f32 v125, v116, v117
	s_and_b64 vcc, exec, s[6:7]
	global_store_dwordx4 v[134:135], v[122:125], off offset:256
	s_cbranch_vccnz .LBB0_563
	s_lshl_b32 s25, s12, 2
	s_add_i32 s34, s25, s74
	s_ashr_i32 s35, s34, 31
	v_ashrrev_i32_e32 v131, 31, v130
	s_mov_b64 s[66:67], -1
	s_mov_b64 s[56:57], 0
	s_cmp_lt_i32 s0, 9
	s_mov_b64 s[76:77], 0
	s_cbranch_scc1 .LBB0_565
	s_cmp_eq_u32 s0, 9
	s_mov_b64 s[76:77], -1
	s_cbranch_scc0 .LBB0_558
	s_lshl_b64 s[66:67], s[34:35], 18
	s_add_u32 s66, s48, s66
	s_addc_u32 s67, s49, s67
	v_lshlrev_b64 v[122:123], 10, v[130:131]
	v_and_b32_e32 v124, 0xffffffe0, v140
	v_lshl_add_u64 v[122:123], s[66:67], 0, v[122:123]
	v_ashrrev_i32_e32 v125, 31, v124
	v_lshl_add_u64 v[122:123], v[124:125], 2, v[122:123]
	v_lshlrev_b32_e32 v64, 2, v169
	v_lshl_add_u64 v[126:127], v[122:123], 0, v[64:65]
	v_mov_b32_e32 v122, v118
	v_mov_b32_e32 v123, v120
	v_mov_b32_e32 v124, v114
	v_mov_b32_e32 v125, v116
	global_store_dwordx4 v[126:127], v[122:125], off
	s_mov_b64 s[76:77], 0
	s_nop 0
	v_mov_b32_e32 v122, v119
	v_mov_b32_e32 v123, v121
	v_mov_b32_e32 v124, v115
	v_mov_b32_e32 v125, v117
	global_store_dwordx4 v[126:127], v[122:125], off offset:64

.LBB0_563:
	s_nop 1
	v_add_u32_e32 v114, 32, v168
	v_ashrrev_i32_e32 v115, 31, v114
	v_lshlrev_b64 v[116:117], 6, v[114:115]
	v_lshl_add_u64 v[116:117], s[14:15], 0, v[116:117]
	v_lshl_add_u64 v[116:117], v[166:167], 2, v[116:117]
	global_load_dwordx4 v[116:119], v[116:117], off
	s_cmp_gt_i32 s23, 63
	s_waitcnt vmcnt(0) lgkmcnt(0)
	v_add_f32_e32 v64, v116, v117
	v_add_f32_e32 v115, v118, v119
	v_add_f32_e32 v64, v64, v115
	v_mov_b32_e32 v115, v64
	s_nop 1
	v_permlane16_swap_b32_e32 v64, v115
	v_add_f32_e32 v64, v64, v115
	v_mov_b32_e32 v115, v64
	s_nop 1
	v_permlane32_swap_b32_e32 v64, v115
	v_add_f32_e32 v64, v64, v115
	v_and_b32_e32 v115, 0x3ff, v114
	v_fmamk_f32 v116, v64, 0x3a800000, v229
	v_lshlrev_b32_e32 v64, 6, v115
	v_cmp_gt_f32_e32 vcc, s55, v116
	v_lshlrev_b32_e32 v64, 2, v64
	s_cbranch_scc0 .LBB0_569
	v_lshl_add_u64 v[118:119], s[16:17], 0, v[64:65]
	v_mov_b32_e32 v163, v65
	v_lshl_add_u64 v[118:119], v[118:119], 0, v[162:163]
	s_mov_b64 s[56:57], 0
	s_mov_b64 s[34:35], -1
	s_branch .LBB0_570

.LBB0_573:
	s_and_b64 vcc, exec, s[34:35]
	s_cbranch_vccz .LBB0_575
	global_load_dwordx4 v[122:125], v[118:119], off
	global_load_dwordx4 v[126:129], v[118:119], off offset:16
	s_waitcnt vmcnt(0) lgkmcnt(0)
	v_pk_mul_f32 v[130:131], v[110:111], v[122:123] op_sel:[1,1] op_sel_hi:[1,0]
	v_pk_mul_f32 v[118:119], v[110:111], v[122:123]
	v_pk_fma_f32 v[110:111], v[110:111], v[122:123], v[130:131] op_sel_hi:[0,1,1]
	v_mul_f32_e32 v110, v113, v125
	v_pk_fma_f32 v[122:123], v[112:113], v[124:125], v[110:111] op_sel_hi:[1,1,0] neg_lo:[0,0,1] neg_hi:[0,0,1]
	v_mul_f32_e32 v110, v113, v124
	v_pk_mul_f32 v[132:133], v[106:107], v[126:127] op_sel:[1,1] op_sel_hi:[1,0]
	v_pk_fma_f32 v[124:125], v[112:113], v[124:125], v[110:111] op_sel:[0,1,0] op_sel_hi:[1,0,0]
	v_pk_mul_f32 v[112:113], v[106:107], v[126:127]
	v_pk_fma_f32 v[106:107], v[106:107], v[126:127], v[132:133] op_sel_hi:[0,1,1]
	v_mul_f32_e32 v106, v109, v129
	v_pk_fma_f32 v[126:127], v[108:109], v[128:129], v[106:107] op_sel_hi:[1,1,0] neg_lo:[0,0,1] neg_hi:[0,0,1]
	v_mul_f32_e32 v106, v109, v128
	v_pk_fma_f32 v[128:129], v[108:109], v[128:129], v[106:107] op_sel:[0,1,0] op_sel_hi:[1,0,0]
	v_sub_f32_e32 v106, v112, v132
	v_sub_f32_e32 v110, v118, v130
	v_mov_b32_e32 v108, v126
	v_mov_b32_e32 v109, v128
	v_mov_b32_e32 v112, v122
	v_mov_b32_e32 v113, v124
.LBB0_575:
	v_mov_b64_e32 v[118:119], s[10:11]
	v_mad_i64_i32 v[118:119], s[34:35], v114, s93, v[118:119]
	v_cvt_pk_bf16_f32 v122, v110, v111
	v_cvt_pk_bf16_f32 v123, v112, v113
	v_cvt_pk_bf16_f32 v124, v106, v107
	v_cvt_pk_bf16_f32 v125, v108, v109
	v_lshl_add_u64 v[118:119], v[160:161], 1, v[118:119]
	s_and_b64 vcc, exec, s[6:7]
	v_subrev_u32_e32 v114, s13, v114
	global_store_dwordx4 v[118:119], v[122:125], off
	s_cbranch_vccnz .LBB0_586
	s_lshl_b32 s25, s12, 2
	s_add_i32 s34, s25, s74
	s_ashr_i32 s35, s34, 31
	s_mov_b64 s[76:77], -1
	s_mov_b64 s[56:57], 0
	s_cmp_lt_i32 s0, 9
	s_mov_b64 s[66:67], 0
	s_cbranch_scc1 .LBB0_582
	s_cmp_eq_u32 s0, 9
	s_mov_b64 s[66:67], -1
	s_cbranch_scc0 .LBB0_579
	s_lshl_b64 s[66:67], s[34:35], 18
	v_ashrrev_i32_e32 v115, 31, v114
	s_add_u32 s66, s48, s66
	s_addc_u32 s67, s49, s67
	v_lshlrev_b64 v[122:123], 10, v[114:115]
	v_and_b32_e32 v124, 0xffffffe0, v158
	v_lshl_add_u64 v[122:123], s[66:67], 0, v[122:123]
	v_ashrrev_i32_e32 v125, 31, v124
	v_lshl_add_u64 v[122:123], v[124:125], 2, v[122:123]
	v_lshlrev_b32_e32 v124, 2, v169
	v_mov_b32_e32 v125, v65
	v_lshl_add_u64 v[126:127], v[122:123], 0, v[124:125]
	v_mov_b32_e32 v122, v110
	v_mov_b32_e32 v123, v112
	v_mov_b32_e32 v124, v106
	v_mov_b32_e32 v125, v108
	global_store_dwordx4 v[126:127], v[122:125], off
	s_mov_b64 s[66:67], 0
	s_nop 0
	v_mov_b32_e32 v122, v111
	v_mov_b32_e32 v123, v113
	v_mov_b32_e32 v124, v107
	v_mov_b32_e32 v125, v109
	global_store_dwordx4 v[126:127], v[122:125], off offset:64

.LBB0_592:
	s_and_b64 vcc, exec, s[34:35]
	s_cbranch_vccz .LBB0_594
	global_load_dwordx4 v[108:111], v[106:107], off
	global_load_dwordx4 v[120:123], v[106:107], off offset:16
	s_waitcnt vmcnt(0) lgkmcnt(0)
	v_pk_mul_f32 v[112:113], v[102:103], v[108:109] op_sel:[1,1] op_sel_hi:[1,0]
	v_mul_f32_e32 v64, v105, v111
	v_pk_mul_f32 v[106:107], v[102:103], v[108:109]
	v_pk_fma_f32 v[102:103], v[102:103], v[108:109], v[112:113] op_sel_hi:[0,1,1]
	v_pk_fma_f32 v[108:109], v[104:105], v[110:111], v[64:65] op_sel_hi:[1,1,0] neg_lo:[0,0,1] neg_hi:[0,0,1]
	v_mul_f32_e32 v64, v105, v110
	v_pk_fma_f32 v[110:111], v[104:105], v[110:111], v[64:65] op_sel:[0,1,0] op_sel_hi:[1,0,0]
	v_pk_mul_f32 v[116:117], v[98:99], v[120:121] op_sel:[1,1] op_sel_hi:[1,0]
	v_mul_f32_e32 v64, v101, v123
	v_pk_mul_f32 v[104:105], v[98:99], v[120:121]
	v_pk_fma_f32 v[98:99], v[98:99], v[120:121], v[116:117] op_sel_hi:[0,1,1]
	v_pk_fma_f32 v[120:121], v[100:101], v[122:123], v[64:65] op_sel_hi:[1,1,0] neg_lo:[0,0,1] neg_hi:[0,0,1]
	v_mul_f32_e32 v64, v101, v122
	v_pk_fma_f32 v[122:123], v[100:101], v[122:123], v[64:65] op_sel:[0,1,0] op_sel_hi:[1,0,0]
	v_sub_f32_e32 v98, v104, v116
	v_sub_f32_e32 v102, v106, v112
	v_mov_b32_e32 v100, v120
	v_mov_b32_e32 v101, v122
	v_mov_b32_e32 v104, v108
	v_mov_b32_e32 v105, v110
.LBB0_594:
	v_cvt_pk_bf16_f32 v106, v102, v103
	v_cvt_pk_bf16_f32 v107, v104, v105
	v_cvt_pk_bf16_f32 v108, v98, v99
	v_cvt_pk_bf16_f32 v109, v100, v101
	s_and_b64 vcc, exec, s[6:7]
	global_store_dwordx4 v[118:119], v[106:109], off offset:256
	s_cbranch_vccnz .LBB0_603
	s_lshl_b32 s25, s12, 2
	s_add_i32 s34, s25, s74
	s_ashr_i32 s35, s34, 31
	v_ashrrev_i32_e32 v115, 31, v114
	s_mov_b64 s[66:67], -1
	s_mov_b64 s[56:57], 0
	s_cmp_lt_i32 s0, 9
	s_mov_b64 s[76:77], 0
	s_cbranch_scc1 .LBB0_605
	s_cmp_eq_u32 s0, 9
	s_mov_b64 s[76:77], -1
	s_cbranch_scc0 .LBB0_598
	s_lshl_b64 s[66:67], s[34:35], 18
	s_add_u32 s66, s48, s66
	s_addc_u32 s67, s49, s67
	v_lshlrev_b64 v[106:107], 10, v[114:115]
	v_and_b32_e32 v108, 0xffffffe0, v140
	v_lshl_add_u64 v[106:107], s[66:67], 0, v[106:107]
	v_ashrrev_i32_e32 v109, 31, v108
	v_lshl_add_u64 v[106:107], v[108:109], 2, v[106:107]
	v_lshlrev_b32_e32 v64, 2, v169
	v_lshl_add_u64 v[110:111], v[106:107], 0, v[64:65]
	v_mov_b32_e32 v106, v102
	v_mov_b32_e32 v107, v104
	v_mov_b32_e32 v108, v98
	v_mov_b32_e32 v109, v100
	global_store_dwordx4 v[110:111], v[106:109], off
	s_mov_b64 s[76:77], 0
	s_nop 0
	v_mov_b32_e32 v106, v103
	v_mov_b32_e32 v107, v105
	v_mov_b32_e32 v108, v99
	v_mov_b32_e32 v109, v101
	global_store_dwordx4 v[110:111], v[106:109], off offset:64

.LBB0_603:
	s_nop 1
	v_add_u32_e32 v98, 48, v168
	v_ashrrev_i32_e32 v99, 31, v98
	v_lshlrev_b64 v[100:101], 6, v[98:99]
	v_lshl_add_u64 v[100:101], s[14:15], 0, v[100:101]
	v_lshl_add_u64 v[100:101], v[166:167], 2, v[100:101]
	global_load_dwordx4 v[100:103], v[100:101], off
	s_cmp_gt_i32 s23, 63
	s_waitcnt vmcnt(0) lgkmcnt(0)
	v_add_f32_e32 v64, v100, v101
	v_add_f32_e32 v99, v102, v103
	v_add_f32_e32 v64, v64, v99
	v_mov_b32_e32 v99, v64
	s_nop 1
	v_permlane16_swap_b32_e32 v64, v99
	v_add_f32_e32 v64, v64, v99
	v_mov_b32_e32 v99, v64
	s_nop 1
	v_permlane32_swap_b32_e32 v64, v99
	v_add_f32_e32 v64, v64, v99
	v_and_b32_e32 v99, 0x3ff, v98
	v_fmamk_f32 v100, v64, 0x3a800000, v229
	v_lshlrev_b32_e32 v64, 6, v99
	v_cmp_gt_f32_e32 vcc, s55, v100
	v_lshlrev_b32_e32 v64, 2, v64
	s_cbranch_scc0 .LBB0_609
	v_lshl_add_u64 v[102:103], s[16:17], 0, v[64:65]
	v_mov_b32_e32 v163, v65
	v_lshl_add_u64 v[102:103], v[102:103], 0, v[162:163]
	s_mov_b64 s[56:57], 0
	s_mov_b64 s[34:35], -1
	s_branch .LBB0_610

.LBB0_613:
	s_and_b64 vcc, exec, s[34:35]
	s_cbranch_vccz .LBB0_615
	global_load_dwordx4 v[106:109], v[102:103], off
	global_load_dwordx4 v[110:113], v[102:103], off offset:16
	s_waitcnt vmcnt(0) lgkmcnt(0)
	v_pk_mul_f32 v[114:115], v[94:95], v[106:107] op_sel:[1,1] op_sel_hi:[1,0]
	v_pk_mul_f32 v[102:103], v[94:95], v[106:107]
	v_pk_fma_f32 v[94:95], v[94:95], v[106:107], v[114:115] op_sel_hi:[0,1,1]
	v_mul_f32_e32 v94, v97, v109
	v_pk_fma_f32 v[106:107], v[96:97], v[108:109], v[94:95] op_sel_hi:[1,1,0] neg_lo:[0,0,1] neg_hi:[0,0,1]
	v_mul_f32_e32 v94, v97, v108
	v_pk_mul_f32 v[116:117], v[90:91], v[110:111] op_sel:[1,1] op_sel_hi:[1,0]
	v_pk_fma_f32 v[108:109], v[96:97], v[108:109], v[94:95] op_sel:[0,1,0] op_sel_hi:[1,0,0]
	v_pk_mul_f32 v[96:97], v[90:91], v[110:111]
	v_pk_fma_f32 v[90:91], v[90:91], v[110:111], v[116:117] op_sel_hi:[0,1,1]
	v_mul_f32_e32 v90, v93, v113
	v_pk_fma_f32 v[110:111], v[92:93], v[112:113], v[90:91] op_sel_hi:[1,1,0] neg_lo:[0,0,1] neg_hi:[0,0,1]
	v_mul_f32_e32 v90, v93, v112
	v_pk_fma_f32 v[112:113], v[92:93], v[112:113], v[90:91] op_sel:[0,1,0] op_sel_hi:[1,0,0]
	v_sub_f32_e32 v90, v96, v116
	v_sub_f32_e32 v94, v102, v114
	v_mov_b32_e32 v92, v110
	v_mov_b32_e32 v93, v112
	v_mov_b32_e32 v96, v106
	v_mov_b32_e32 v97, v108
.LBB0_615:
	v_mov_b64_e32 v[102:103], s[10:11]
	v_mad_i64_i32 v[102:103], s[34:35], v98, s93, v[102:103]
	v_cvt_pk_bf16_f32 v106, v94, v95
	v_cvt_pk_bf16_f32 v107, v96, v97
	v_cvt_pk_bf16_f32 v108, v90, v91
	v_cvt_pk_bf16_f32 v109, v92, v93
	v_lshl_add_u64 v[102:103], v[160:161], 1, v[102:103]
	s_and_b64 vcc, exec, s[6:7]
	v_subrev_u32_e32 v98, s13, v98
	global_store_dwordx4 v[102:103], v[106:109], off
	s_cbranch_vccnz .LBB0_626
	s_lshl_b32 s25, s12, 2
	s_add_i32 s34, s25, s74
	s_ashr_i32 s35, s34, 31
	s_mov_b64 s[76:77], -1
	s_mov_b64 s[56:57], 0
	s_cmp_lt_i32 s0, 9
	s_mov_b64 s[66:67], 0
	s_cbranch_scc1 .LBB0_622
	s_cmp_eq_u32 s0, 9
	s_mov_b64 s[66:67], -1
	s_cbranch_scc0 .LBB0_619
	s_lshl_b64 s[66:67], s[34:35], 18
	v_ashrrev_i32_e32 v99, 31, v98
	s_add_u32 s66, s48, s66
	s_addc_u32 s67, s49, s67
	v_lshlrev_b64 v[106:107], 10, v[98:99]
	v_and_b32_e32 v108, 0xffffffe0, v158
	v_lshl_add_u64 v[106:107], s[66:67], 0, v[106:107]
	v_ashrrev_i32_e32 v109, 31, v108
	v_lshl_add_u64 v[106:107], v[108:109], 2, v[106:107]
	v_lshlrev_b32_e32 v108, 2, v169
	v_mov_b32_e32 v109, v65
	v_lshl_add_u64 v[110:111], v[106:107], 0, v[108:109]
	v_mov_b32_e32 v106, v94
	v_mov_b32_e32 v107, v96
	v_mov_b32_e32 v108, v90
	v_mov_b32_e32 v109, v92
	global_store_dwordx4 v[110:111], v[106:109], off
	s_mov_b64 s[66:67], 0
	s_nop 0
	v_mov_b32_e32 v106, v95
	v_mov_b32_e32 v107, v97
	v_mov_b32_e32 v108, v91
	v_mov_b32_e32 v109, v93
	global_store_dwordx4 v[110:111], v[106:109], off offset:64

.LBB0_632:
	s_and_b64 vcc, exec, s[34:35]
	s_cbranch_vccz .LBB0_634
	global_load_dwordx4 v[92:95], v[90:91], off
	global_load_dwordx4 v[104:107], v[90:91], off offset:16
	s_waitcnt vmcnt(0) lgkmcnt(0)
	v_pk_mul_f32 v[96:97], v[86:87], v[92:93] op_sel:[1,1] op_sel_hi:[1,0]
	v_mul_f32_e32 v64, v89, v95
	v_pk_mul_f32 v[90:91], v[86:87], v[92:93]
	v_pk_fma_f32 v[86:87], v[86:87], v[92:93], v[96:97] op_sel_hi:[0,1,1]
	v_pk_fma_f32 v[92:93], v[88:89], v[94:95], v[64:65] op_sel_hi:[1,1,0] neg_lo:[0,0,1] neg_hi:[0,0,1]
	v_mul_f32_e32 v64, v89, v94
	v_pk_fma_f32 v[94:95], v[88:89], v[94:95], v[64:65] op_sel:[0,1,0] op_sel_hi:[1,0,0]
	v_pk_mul_f32 v[100:101], v[82:83], v[104:105] op_sel:[1,1] op_sel_hi:[1,0]
	v_mul_f32_e32 v64, v85, v107
	v_pk_mul_f32 v[88:89], v[82:83], v[104:105]
	v_pk_fma_f32 v[82:83], v[82:83], v[104:105], v[100:101] op_sel_hi:[0,1,1]
	v_pk_fma_f32 v[104:105], v[84:85], v[106:107], v[64:65] op_sel_hi:[1,1,0] neg_lo:[0,0,1] neg_hi:[0,0,1]
	v_mul_f32_e32 v64, v85, v106
	v_pk_fma_f32 v[106:107], v[84:85], v[106:107], v[64:65] op_sel:[0,1,0] op_sel_hi:[1,0,0]
	v_sub_f32_e32 v82, v88, v100
	v_sub_f32_e32 v86, v90, v96
	v_mov_b32_e32 v84, v104
	v_mov_b32_e32 v85, v106
	v_mov_b32_e32 v88, v92
	v_mov_b32_e32 v89, v94
.LBB0_634:
	v_cvt_pk_bf16_f32 v90, v86, v87
	v_cvt_pk_bf16_f32 v91, v88, v89
	v_cvt_pk_bf16_f32 v92, v82, v83
	v_cvt_pk_bf16_f32 v93, v84, v85
	s_and_b64 vcc, exec, s[6:7]
	global_store_dwordx4 v[102:103], v[90:93], off offset:256
	s_cbranch_vccnz .LBB0_643
	s_lshl_b32 s25, s12, 2
	s_add_i32 s34, s25, s74
	s_ashr_i32 s35, s34, 31
	v_ashrrev_i32_e32 v99, 31, v98
	s_mov_b64 s[66:67], -1
	s_mov_b64 s[56:57], 0
	s_cmp_lt_i32 s0, 9
	s_mov_b64 s[76:77], 0
	s_cbranch_scc1 .LBB0_645
	s_cmp_eq_u32 s0, 9
	s_mov_b64 s[76:77], -1
	s_cbranch_scc0 .LBB0_638
	s_lshl_b64 s[66:67], s[34:35], 18
	s_add_u32 s66, s48, s66
	s_addc_u32 s67, s49, s67
	v_lshlrev_b64 v[90:91], 10, v[98:99]
	v_and_b32_e32 v92, 0xffffffe0, v140
	v_lshl_add_u64 v[90:91], s[66:67], 0, v[90:91]
	v_ashrrev_i32_e32 v93, 31, v92
	v_lshl_add_u64 v[90:91], v[92:93], 2, v[90:91]
	v_lshlrev_b32_e32 v64, 2, v169
	v_lshl_add_u64 v[94:95], v[90:91], 0, v[64:65]
	v_mov_b32_e32 v90, v86
	v_mov_b32_e32 v91, v88
	v_mov_b32_e32 v92, v82
	v_mov_b32_e32 v93, v84
	global_store_dwordx4 v[94:95], v[90:93], off
	s_mov_b64 s[76:77], 0
	s_nop 0
	v_mov_b32_e32 v90, v87
	v_mov_b32_e32 v91, v89
	v_mov_b32_e32 v92, v83
	v_mov_b32_e32 v93, v85
	global_store_dwordx4 v[94:95], v[90:93], off offset:64

.LBB0_643:
	s_nop 1
	v_add_u32_e32 v82, 0x80, v168
	v_ashrrev_i32_e32 v83, 31, v82
	v_lshlrev_b64 v[84:85], 6, v[82:83]
	v_lshl_add_u64 v[84:85], s[14:15], 0, v[84:85]
	v_lshl_add_u64 v[84:85], v[166:167], 2, v[84:85]
	global_load_dwordx4 v[84:87], v[84:85], off
	s_cmp_gt_i32 s23, 63
	s_waitcnt vmcnt(0) lgkmcnt(0)
	v_add_f32_e32 v64, v84, v85
	v_add_f32_e32 v83, v86, v87
	v_add_f32_e32 v64, v64, v83
	v_mov_b32_e32 v83, v64
	s_nop 1
	v_permlane16_swap_b32_e32 v64, v83
	v_add_f32_e32 v64, v64, v83
	v_mov_b32_e32 v83, v64
	s_nop 1
	v_permlane32_swap_b32_e32 v64, v83
	v_add_f32_e32 v64, v64, v83
	v_and_b32_e32 v83, 0x3ff, v82
	v_fmamk_f32 v84, v64, 0x3a800000, v229
	v_lshlrev_b32_e32 v64, 6, v83
	v_cmp_gt_f32_e32 vcc, s55, v84
	v_lshlrev_b32_e32 v64, 2, v64
	s_cbranch_scc0 .LBB0_649
	v_lshl_add_u64 v[86:87], s[16:17], 0, v[64:65]
	v_mov_b32_e32 v163, v65
	v_lshl_add_u64 v[86:87], v[86:87], 0, v[162:163]
	s_mov_b64 s[56:57], 0
	s_mov_b64 s[34:35], -1
	s_branch .LBB0_650

.LBB0_653:
	s_and_b64 vcc, exec, s[34:35]
	s_cbranch_vccz .LBB0_655
	global_load_dwordx4 v[90:93], v[86:87], off
	global_load_dwordx4 v[94:97], v[86:87], off offset:16
	s_waitcnt vmcnt(0) lgkmcnt(0)
	v_pk_mul_f32 v[98:99], v[78:79], v[90:91] op_sel:[1,1] op_sel_hi:[1,0]
	v_pk_mul_f32 v[86:87], v[78:79], v[90:91]
	v_pk_fma_f32 v[78:79], v[78:79], v[90:91], v[98:99] op_sel_hi:[0,1,1]
	v_mul_f32_e32 v78, v81, v93
	v_pk_fma_f32 v[90:91], v[80:81], v[92:93], v[78:79] op_sel_hi:[1,1,0] neg_lo:[0,0,1] neg_hi:[0,0,1]
	v_mul_f32_e32 v78, v81, v92
	v_pk_mul_f32 v[100:101], v[74:75], v[94:95] op_sel:[1,1] op_sel_hi:[1,0]
	v_pk_fma_f32 v[92:93], v[80:81], v[92:93], v[78:79] op_sel:[0,1,0] op_sel_hi:[1,0,0]
	v_pk_mul_f32 v[80:81], v[74:75], v[94:95]
	v_pk_fma_f32 v[74:75], v[74:75], v[94:95], v[100:101] op_sel_hi:[0,1,1]
	v_mul_f32_e32 v74, v77, v97
	v_pk_fma_f32 v[94:95], v[76:77], v[96:97], v[74:75] op_sel_hi:[1,1,0] neg_lo:[0,0,1] neg_hi:[0,0,1]
	v_mul_f32_e32 v74, v77, v96
	v_pk_fma_f32 v[96:97], v[76:77], v[96:97], v[74:75] op_sel:[0,1,0] op_sel_hi:[1,0,0]
	v_sub_f32_e32 v74, v80, v100
	v_sub_f32_e32 v78, v86, v98
	v_mov_b32_e32 v76, v94
	v_mov_b32_e32 v77, v96
	v_mov_b32_e32 v80, v90
	v_mov_b32_e32 v81, v92
.LBB0_655:
	v_mov_b64_e32 v[86:87], s[10:11]
	v_mad_i64_i32 v[86:87], s[34:35], v82, s93, v[86:87]
	v_cvt_pk_bf16_f32 v90, v78, v79
	v_cvt_pk_bf16_f32 v91, v80, v81
	v_cvt_pk_bf16_f32 v92, v74, v75
	v_cvt_pk_bf16_f32 v93, v76, v77
	v_lshl_add_u64 v[86:87], v[160:161], 1, v[86:87]
	s_and_b64 vcc, exec, s[6:7]
	v_subrev_u32_e32 v82, s13, v82
	global_store_dwordx4 v[86:87], v[90:93], off
	s_cbranch_vccnz .LBB0_666
	s_lshl_b32 s25, s12, 2
	s_add_i32 s34, s25, s74
	s_ashr_i32 s35, s34, 31
	s_mov_b64 s[76:77], -1
	s_mov_b64 s[56:57], 0
	s_cmp_lt_i32 s0, 9
	s_mov_b64 s[66:67], 0
	s_cbranch_scc1 .LBB0_662
	s_cmp_eq_u32 s0, 9
	s_mov_b64 s[66:67], -1
	s_cbranch_scc0 .LBB0_659
	s_lshl_b64 s[66:67], s[34:35], 18
	v_ashrrev_i32_e32 v83, 31, v82
	s_add_u32 s66, s48, s66
	s_addc_u32 s67, s49, s67
	v_lshlrev_b64 v[90:91], 10, v[82:83]
	v_and_b32_e32 v92, 0xffffffe0, v158
	v_lshl_add_u64 v[90:91], s[66:67], 0, v[90:91]
	v_ashrrev_i32_e32 v93, 31, v92
	v_lshl_add_u64 v[90:91], v[92:93], 2, v[90:91]
	v_lshlrev_b32_e32 v92, 2, v169
	v_mov_b32_e32 v93, v65
	v_lshl_add_u64 v[94:95], v[90:91], 0, v[92:93]
	v_mov_b32_e32 v90, v78
	v_mov_b32_e32 v91, v80
	v_mov_b32_e32 v92, v74
	v_mov_b32_e32 v93, v76
	global_store_dwordx4 v[94:95], v[90:93], off
	s_mov_b64 s[66:67], 0
	s_nop 0
	v_mov_b32_e32 v90, v79
	v_mov_b32_e32 v91, v81
	v_mov_b32_e32 v92, v75
	v_mov_b32_e32 v93, v77
	global_store_dwordx4 v[94:95], v[90:93], off offset:64

.LBB0_672:
	s_and_b64 vcc, exec, s[34:35]
	s_cbranch_vccz .LBB0_674
	global_load_dwordx4 v[76:79], v[74:75], off
	global_load_dwordx4 v[88:91], v[74:75], off offset:16
	s_waitcnt vmcnt(0) lgkmcnt(0)
	v_pk_mul_f32 v[80:81], v[70:71], v[76:77] op_sel:[1,1] op_sel_hi:[1,0]
	v_mul_f32_e32 v64, v73, v79
	v_pk_mul_f32 v[74:75], v[70:71], v[76:77]
	v_pk_fma_f32 v[70:71], v[70:71], v[76:77], v[80:81] op_sel_hi:[0,1,1]
	v_pk_fma_f32 v[76:77], v[72:73], v[78:79], v[64:65] op_sel_hi:[1,1,0] neg_lo:[0,0,1] neg_hi:[0,0,1]
	v_mul_f32_e32 v64, v73, v78
	v_pk_fma_f32 v[78:79], v[72:73], v[78:79], v[64:65] op_sel:[0,1,0] op_sel_hi:[1,0,0]
	v_pk_mul_f32 v[84:85], v[66:67], v[88:89] op_sel:[1,1] op_sel_hi:[1,0]
	v_mul_f32_e32 v64, v69, v91
	v_pk_mul_f32 v[72:73], v[66:67], v[88:89]
	v_pk_fma_f32 v[66:67], v[66:67], v[88:89], v[84:85] op_sel_hi:[0,1,1]
	v_pk_fma_f32 v[88:89], v[68:69], v[90:91], v[64:65] op_sel_hi:[1,1,0] neg_lo:[0,0,1] neg_hi:[0,0,1]
	v_mul_f32_e32 v64, v69, v90
	v_pk_fma_f32 v[90:91], v[68:69], v[90:91], v[64:65] op_sel:[0,1,0] op_sel_hi:[1,0,0]
	v_sub_f32_e32 v66, v72, v84
	v_sub_f32_e32 v70, v74, v80
	v_mov_b32_e32 v68, v88
	v_mov_b32_e32 v69, v90
	v_mov_b32_e32 v72, v76
	v_mov_b32_e32 v73, v78
.LBB0_674:
	v_cvt_pk_bf16_f32 v74, v70, v71
	v_cvt_pk_bf16_f32 v75, v72, v73
	v_cvt_pk_bf16_f32 v76, v66, v67
	v_cvt_pk_bf16_f32 v77, v68, v69
	s_and_b64 vcc, exec, s[6:7]
	global_store_dwordx4 v[86:87], v[74:77], off offset:256
	s_cbranch_vccnz .LBB0_683
	s_lshl_b32 s25, s12, 2
	s_add_i32 s34, s25, s74
	s_ashr_i32 s35, s34, 31
	v_ashrrev_i32_e32 v83, 31, v82
	s_mov_b64 s[66:67], -1
	s_mov_b64 s[56:57], 0
	s_cmp_lt_i32 s0, 9
	s_mov_b64 s[76:77], 0
	s_cbranch_scc1 .LBB0_685
	s_cmp_eq_u32 s0, 9
	s_mov_b64 s[76:77], -1
	s_cbranch_scc0 .LBB0_678
	s_lshl_b64 s[66:67], s[34:35], 18
	s_add_u32 s66, s48, s66
	s_addc_u32 s67, s49, s67
	v_lshlrev_b64 v[74:75], 10, v[82:83]
	v_and_b32_e32 v76, 0xffffffe0, v140
	v_lshl_add_u64 v[74:75], s[66:67], 0, v[74:75]
	v_ashrrev_i32_e32 v77, 31, v76
	v_lshl_add_u64 v[74:75], v[76:77], 2, v[74:75]
	v_lshlrev_b32_e32 v64, 2, v169
	v_lshl_add_u64 v[78:79], v[74:75], 0, v[64:65]
	v_mov_b32_e32 v74, v70
	v_mov_b32_e32 v75, v72
	v_mov_b32_e32 v76, v66
	v_mov_b32_e32 v77, v68
	global_store_dwordx4 v[78:79], v[74:77], off
	s_mov_b64 s[76:77], 0
	s_nop 0
	v_mov_b32_e32 v74, v71
	v_mov_b32_e32 v75, v73
	v_mov_b32_e32 v76, v67
	v_mov_b32_e32 v77, v69
	global_store_dwordx4 v[78:79], v[74:77], off offset:64

.LBB0_683:
	s_nop 1
	v_add_u32_e32 v66, 0x90, v168
	v_ashrrev_i32_e32 v67, 31, v66
	v_lshlrev_b64 v[68:69], 6, v[66:67]
	v_lshl_add_u64 v[68:69], s[14:15], 0, v[68:69]
	v_lshl_add_u64 v[68:69], v[166:167], 2, v[68:69]
	global_load_dwordx4 v[68:71], v[68:69], off
	s_cmp_gt_i32 s23, 63
	s_waitcnt vmcnt(0) lgkmcnt(0)
	v_add_f32_e32 v64, v68, v69
	v_add_f32_e32 v67, v70, v71
	v_add_f32_e32 v64, v64, v67
	v_mov_b32_e32 v67, v64
	s_nop 1
	v_permlane16_swap_b32_e32 v64, v67
	v_add_f32_e32 v64, v64, v67
	v_mov_b32_e32 v67, v64
	s_nop 1
	v_permlane32_swap_b32_e32 v64, v67
	v_add_f32_e32 v64, v64, v67
	v_and_b32_e32 v67, 0x3ff, v66
	v_fmamk_f32 v68, v64, 0x3a800000, v229
	v_lshlrev_b32_e32 v64, 6, v67
	v_cmp_gt_f32_e32 vcc, s55, v68
	v_lshlrev_b32_e32 v64, 2, v64
	s_cbranch_scc0 .LBB0_689
	v_lshl_add_u64 v[70:71], s[16:17], 0, v[64:65]
	v_mov_b32_e32 v163, v65
	v_lshl_add_u64 v[70:71], v[70:71], 0, v[162:163]
	s_mov_b64 s[56:57], 0
	s_mov_b64 s[34:35], -1
	s_branch .LBB0_690

.LBB0_693:
	s_and_b64 vcc, exec, s[34:35]
	s_cbranch_vccz .LBB0_695
	global_load_dwordx4 v[74:77], v[70:71], off
	global_load_dwordx4 v[78:81], v[70:71], off offset:16
	s_waitcnt vmcnt(0) lgkmcnt(0)
	v_pk_mul_f32 v[82:83], v[60:61], v[74:75] op_sel:[1,1] op_sel_hi:[1,0]
	v_pk_mul_f32 v[70:71], v[60:61], v[74:75]
	v_pk_fma_f32 v[60:61], v[60:61], v[74:75], v[82:83] op_sel_hi:[0,1,1]
	v_mul_f32_e32 v60, v63, v77
	v_pk_fma_f32 v[74:75], v[62:63], v[76:77], v[60:61] op_sel_hi:[1,1,0] neg_lo:[0,0,1] neg_hi:[0,0,1]
	v_mul_f32_e32 v60, v63, v76
	v_pk_mul_f32 v[84:85], v[56:57], v[78:79] op_sel:[1,1] op_sel_hi:[1,0]
	v_pk_fma_f32 v[76:77], v[62:63], v[76:77], v[60:61] op_sel:[0,1,0] op_sel_hi:[1,0,0]
	v_pk_mul_f32 v[62:63], v[56:57], v[78:79]
	v_pk_fma_f32 v[56:57], v[56:57], v[78:79], v[84:85] op_sel_hi:[0,1,1]
	v_mul_f32_e32 v56, v59, v81
	v_pk_fma_f32 v[78:79], v[58:59], v[80:81], v[56:57] op_sel_hi:[1,1,0] neg_lo:[0,0,1] neg_hi:[0,0,1]
	v_mul_f32_e32 v56, v59, v80
	v_pk_fma_f32 v[80:81], v[58:59], v[80:81], v[56:57] op_sel:[0,1,0] op_sel_hi:[1,0,0]
	v_sub_f32_e32 v56, v62, v84
	v_sub_f32_e32 v60, v70, v82
	v_mov_b32_e32 v58, v78
	v_mov_b32_e32 v59, v80
	v_mov_b32_e32 v62, v74
	v_mov_b32_e32 v63, v76
.LBB0_695:
	v_mov_b64_e32 v[70:71], s[10:11]
	v_mad_i64_i32 v[70:71], s[34:35], v66, s93, v[70:71]
	v_cvt_pk_bf16_f32 v74, v60, v61
	v_cvt_pk_bf16_f32 v75, v62, v63
	v_cvt_pk_bf16_f32 v76, v56, v57
	v_cvt_pk_bf16_f32 v77, v58, v59
	v_lshl_add_u64 v[70:71], v[160:161], 1, v[70:71]
	s_and_b64 vcc, exec, s[6:7]
	v_subrev_u32_e32 v66, s13, v66
	global_store_dwordx4 v[70:71], v[74:77], off
	s_cbranch_vccnz .LBB0_706
	s_lshl_b32 s25, s12, 2
	s_add_i32 s34, s25, s74
	s_ashr_i32 s35, s34, 31
	s_mov_b64 s[76:77], -1
	s_mov_b64 s[56:57], 0
	s_cmp_lt_i32 s0, 9
	s_mov_b64 s[66:67], 0
	s_cbranch_scc1 .LBB0_702
	s_cmp_eq_u32 s0, 9
	s_mov_b64 s[66:67], -1
	s_cbranch_scc0 .LBB0_699
	s_lshl_b64 s[66:67], s[34:35], 18
	v_ashrrev_i32_e32 v67, 31, v66
	s_add_u32 s66, s48, s66
	s_addc_u32 s67, s49, s67
	v_lshlrev_b64 v[74:75], 10, v[66:67]
	v_and_b32_e32 v76, 0xffffffe0, v158
	v_lshl_add_u64 v[74:75], s[66:67], 0, v[74:75]
	v_ashrrev_i32_e32 v77, 31, v76
	v_lshl_add_u64 v[74:75], v[76:77], 2, v[74:75]
	v_lshlrev_b32_e32 v76, 2, v169
	v_mov_b32_e32 v77, v65
	v_lshl_add_u64 v[78:79], v[74:75], 0, v[76:77]
	v_mov_b32_e32 v74, v60
	v_mov_b32_e32 v75, v62
	v_mov_b32_e32 v76, v56
	v_mov_b32_e32 v77, v58
	global_store_dwordx4 v[78:79], v[74:77], off
	s_mov_b64 s[66:67], 0
	s_nop 0
	v_mov_b32_e32 v74, v61
	v_mov_b32_e32 v75, v63
	v_mov_b32_e32 v76, v57
	v_mov_b32_e32 v77, v59
	global_store_dwordx4 v[78:79], v[74:77], off offset:64

.LBB0_712:
	s_and_b64 vcc, exec, s[34:35]
	s_cbranch_vccz .LBB0_714
	global_load_dwordx4 v[58:61], v[56:57], off
	global_load_dwordx4 v[72:75], v[56:57], off offset:16
	s_waitcnt vmcnt(0) lgkmcnt(0)
	v_pk_mul_f32 v[62:63], v[52:53], v[58:59] op_sel:[1,1] op_sel_hi:[1,0]
	v_pk_mul_f32 v[56:57], v[52:53], v[58:59]
	v_pk_fma_f32 v[52:53], v[52:53], v[58:59], v[62:63] op_sel_hi:[0,1,1]
	v_mul_f32_e32 v52, v55, v61
	v_pk_fma_f32 v[58:59], v[54:55], v[60:61], v[52:53] op_sel_hi:[1,1,0] neg_lo:[0,0,1] neg_hi:[0,0,1]
	v_mul_f32_e32 v52, v55, v60
	v_pk_mul_f32 v[68:69], v[48:49], v[72:73] op_sel:[1,1] op_sel_hi:[1,0]
	v_pk_fma_f32 v[60:61], v[54:55], v[60:61], v[52:53] op_sel:[0,1,0] op_sel_hi:[1,0,0]
	v_pk_mul_f32 v[54:55], v[48:49], v[72:73]
	v_pk_fma_f32 v[48:49], v[48:49], v[72:73], v[68:69] op_sel_hi:[0,1,1]
	v_mul_f32_e32 v48, v51, v75
	v_pk_fma_f32 v[72:73], v[50:51], v[74:75], v[48:49] op_sel_hi:[1,1,0] neg_lo:[0,0,1] neg_hi:[0,0,1]
	v_mul_f32_e32 v48, v51, v74
	v_pk_fma_f32 v[74:75], v[50:51], v[74:75], v[48:49] op_sel:[0,1,0] op_sel_hi:[1,0,0]
	v_sub_f32_e32 v48, v54, v68
	v_sub_f32_e32 v52, v56, v62
	v_mov_b32_e32 v50, v72
	v_mov_b32_e32 v51, v74
	v_mov_b32_e32 v54, v58
	v_mov_b32_e32 v55, v60
.LBB0_714:
	v_cvt_pk_bf16_f32 v56, v52, v53
	v_cvt_pk_bf16_f32 v57, v54, v55
	v_cvt_pk_bf16_f32 v58, v48, v49
	v_cvt_pk_bf16_f32 v59, v50, v51
	s_and_b64 vcc, exec, s[6:7]
	global_store_dwordx4 v[70:71], v[56:59], off offset:256
	s_cbranch_vccnz .LBB0_723
	s_lshl_b32 s25, s12, 2
	s_add_i32 s34, s25, s74
	s_ashr_i32 s35, s34, 31
	v_ashrrev_i32_e32 v67, 31, v66
	s_mov_b64 s[66:67], -1
	s_mov_b64 s[56:57], 0
	s_cmp_lt_i32 s0, 9
	s_mov_b64 s[76:77], 0
	s_cbranch_scc1 .LBB0_725
	s_cmp_eq_u32 s0, 9
	s_mov_b64 s[76:77], -1
	s_cbranch_scc0 .LBB0_718
	s_lshl_b64 s[66:67], s[34:35], 18
	s_add_u32 s66, s48, s66
	s_addc_u32 s67, s49, s67
	v_lshlrev_b64 v[56:57], 10, v[66:67]
	v_and_b32_e32 v58, 0xffffffe0, v140
	v_lshl_add_u64 v[56:57], s[66:67], 0, v[56:57]
	v_ashrrev_i32_e32 v59, 31, v58
	v_lshl_add_u64 v[56:57], v[58:59], 2, v[56:57]
	v_lshlrev_b32_e32 v64, 2, v169
	v_lshl_add_u64 v[60:61], v[56:57], 0, v[64:65]
	v_mov_b32_e32 v56, v52
	v_mov_b32_e32 v57, v54
	v_mov_b32_e32 v58, v48
	v_mov_b32_e32 v59, v50
	global_store_dwordx4 v[60:61], v[56:59], off
	s_mov_b64 s[76:77], 0
	s_nop 0
	v_mov_b32_e32 v56, v53
	v_mov_b32_e32 v57, v55
	v_mov_b32_e32 v58, v49
	v_mov_b32_e32 v59, v51
	global_store_dwordx4 v[60:61], v[56:59], off offset:64

.LBB0_723:
	s_nop 1
	v_add_u32_e32 v48, 0xa0, v168
	v_ashrrev_i32_e32 v49, 31, v48
	v_lshlrev_b64 v[50:51], 6, v[48:49]
	v_lshl_add_u64 v[50:51], s[14:15], 0, v[50:51]
	v_lshl_add_u64 v[50:51], v[166:167], 2, v[50:51]
	global_load_dwordx4 v[50:53], v[50:51], off
	s_cmp_gt_i32 s23, 63
	s_waitcnt vmcnt(0) lgkmcnt(0)
	v_add_f32_e32 v49, v50, v51
	v_add_f32_e32 v50, v52, v53
	v_add_f32_e32 v49, v49, v50
	v_mov_b32_e32 v50, v49
	s_nop 1
	v_permlane16_swap_b32_e32 v49, v50
	v_add_f32_e32 v49, v49, v50
	v_mov_b32_e32 v50, v49
	s_nop 1
	v_permlane32_swap_b32_e32 v49, v50
	v_add_f32_e32 v49, v49, v50
	v_fmamk_f32 v50, v49, 0x3a800000, v229
	v_and_b32_e32 v49, 0x3ff, v48
	v_lshlrev_b32_e32 v51, 6, v49
	v_cmp_gt_f32_e32 vcc, s55, v50
	v_lshlrev_b32_e32 v64, 2, v51
	s_cbranch_scc0 .LBB0_729
	v_lshl_add_u64 v[52:53], s[16:17], 0, v[64:65]
	v_mov_b32_e32 v163, v65
	v_lshl_add_u64 v[52:53], v[52:53], 0, v[162:163]
	s_mov_b64 s[56:57], 0
	s_mov_b64 s[34:35], -1
	s_branch .LBB0_730

.LBB0_733:
	s_and_b64 vcc, exec, s[34:35]
	s_cbranch_vccz .LBB0_735
	global_load_dwordx4 v[56:59], v[52:53], off
	global_load_dwordx4 v[60:63], v[52:53], off offset:16
	s_waitcnt vmcnt(0) lgkmcnt(0)
	v_pk_mul_f32 v[66:67], v[44:45], v[56:57] op_sel:[1,1] op_sel_hi:[1,0]
	v_pk_mul_f32 v[52:53], v[44:45], v[56:57]
	v_pk_fma_f32 v[44:45], v[44:45], v[56:57], v[66:67] op_sel_hi:[0,1,1]
	v_mul_f32_e32 v44, v47, v59
	v_pk_fma_f32 v[56:57], v[46:47], v[58:59], v[44:45] op_sel_hi:[1,1,0] neg_lo:[0,0,1] neg_hi:[0,0,1]
	v_mul_f32_e32 v44, v47, v58
	v_pk_mul_f32 v[68:69], v[32:33], v[60:61] op_sel:[1,1] op_sel_hi:[1,0]
	v_pk_fma_f32 v[58:59], v[46:47], v[58:59], v[44:45] op_sel:[0,1,0] op_sel_hi:[1,0,0]
	v_pk_mul_f32 v[46:47], v[32:33], v[60:61]
	v_pk_fma_f32 v[32:33], v[32:33], v[60:61], v[68:69] op_sel_hi:[0,1,1]
	v_mul_f32_e32 v32, v35, v63
	v_pk_fma_f32 v[60:61], v[34:35], v[62:63], v[32:33] op_sel_hi:[1,1,0] neg_lo:[0,0,1] neg_hi:[0,0,1]
	v_mul_f32_e32 v32, v35, v62
	v_pk_fma_f32 v[62:63], v[34:35], v[62:63], v[32:33] op_sel:[0,1,0] op_sel_hi:[1,0,0]
	v_sub_f32_e32 v32, v46, v68
	v_sub_f32_e32 v44, v52, v66
	v_mov_b32_e32 v34, v60
	v_mov_b32_e32 v35, v62
	v_mov_b32_e32 v46, v56
	v_mov_b32_e32 v47, v58
.LBB0_735:
	v_mov_b64_e32 v[52:53], s[10:11]
	v_mad_i64_i32 v[52:53], s[34:35], v48, s93, v[52:53]
	v_cvt_pk_bf16_f32 v56, v44, v45
	v_cvt_pk_bf16_f32 v57, v46, v47
	v_cvt_pk_bf16_f32 v58, v32, v33
	v_cvt_pk_bf16_f32 v59, v34, v35
	v_lshl_add_u64 v[52:53], v[160:161], 1, v[52:53]
	s_and_b64 vcc, exec, s[6:7]
	v_subrev_u32_e32 v48, s13, v48
	global_store_dwordx4 v[52:53], v[56:59], off
	s_cbranch_vccnz .LBB0_746
	s_lshl_b32 s25, s12, 2
	s_add_i32 s34, s25, s74
	s_ashr_i32 s35, s34, 31
	s_mov_b64 s[76:77], -1
	s_mov_b64 s[56:57], 0
	s_cmp_lt_i32 s0, 9
	s_mov_b64 s[66:67], 0
	s_cbranch_scc1 .LBB0_742
	s_cmp_eq_u32 s0, 9
	s_mov_b64 s[66:67], -1
	s_cbranch_scc0 .LBB0_739
	s_lshl_b64 s[66:67], s[34:35], 18
	v_ashrrev_i32_e32 v49, 31, v48
	s_add_u32 s66, s48, s66
	s_addc_u32 s67, s49, s67
	v_lshlrev_b64 v[56:57], 10, v[48:49]
	v_and_b32_e32 v58, 0xffffffe0, v158
	v_lshl_add_u64 v[56:57], s[66:67], 0, v[56:57]
	v_ashrrev_i32_e32 v59, 31, v58
	v_lshl_add_u64 v[56:57], v[58:59], 2, v[56:57]
	v_lshlrev_b32_e32 v58, 2, v169
	v_mov_b32_e32 v59, v65
	v_lshl_add_u64 v[60:61], v[56:57], 0, v[58:59]
	v_mov_b32_e32 v56, v44
	v_mov_b32_e32 v57, v46
	v_mov_b32_e32 v58, v32
	v_mov_b32_e32 v59, v34
	global_store_dwordx4 v[60:61], v[56:59], off
	s_mov_b64 s[66:67], 0
	s_nop 0
	v_mov_b32_e32 v56, v45
	v_mov_b32_e32 v57, v47
	v_mov_b32_e32 v58, v33
	v_mov_b32_e32 v59, v35
	global_store_dwordx4 v[60:61], v[56:59], off offset:64

.LBB0_752:
	s_and_b64 vcc, exec, s[34:35]
	s_cbranch_vccz .LBB0_754
	global_load_dwordx4 v[44:47], v[32:33], off
	s_nop 0
	global_load_dwordx4 v[32:35], v[32:33], off offset:16
	s_waitcnt vmcnt(0) lgkmcnt(0)
	v_pk_mul_f32 v[54:55], v[20:21], v[44:45] op_sel:[1,1] op_sel_hi:[1,0]
	v_pk_mul_f32 v[50:51], v[20:21], v[44:45]
	v_pk_fma_f32 v[20:21], v[20:21], v[44:45], v[54:55] op_sel_hi:[0,1,1]
	v_mul_f32_e32 v20, v23, v47
	v_pk_fma_f32 v[44:45], v[22:23], v[46:47], v[20:21] op_sel_hi:[1,1,0] neg_lo:[0,0,1] neg_hi:[0,0,1]
	v_mul_f32_e32 v20, v23, v46
	v_pk_mul_f32 v[56:57], v[16:17], v[32:33] op_sel:[1,1] op_sel_hi:[1,0]
	v_pk_fma_f32 v[46:47], v[22:23], v[46:47], v[20:21] op_sel:[0,1,0] op_sel_hi:[1,0,0]
	v_pk_mul_f32 v[22:23], v[16:17], v[32:33]
	v_pk_fma_f32 v[16:17], v[16:17], v[32:33], v[56:57] op_sel_hi:[0,1,1]
	v_mul_f32_e32 v16, v19, v35
	v_pk_fma_f32 v[32:33], v[18:19], v[34:35], v[16:17] op_sel_hi:[1,1,0] neg_lo:[0,0,1] neg_hi:[0,0,1]
	v_mul_f32_e32 v16, v19, v34
	v_pk_fma_f32 v[34:35], v[18:19], v[34:35], v[16:17] op_sel:[0,1,0] op_sel_hi:[1,0,0]
	v_sub_f32_e32 v16, v22, v56
	v_sub_f32_e32 v20, v50, v54
	v_mov_b32_e32 v18, v32
	v_mov_b32_e32 v19, v34
	v_mov_b32_e32 v22, v44
	v_mov_b32_e32 v23, v46
.LBB0_754:
	v_cvt_pk_bf16_f32 v32, v20, v21
	v_cvt_pk_bf16_f32 v33, v22, v23
	v_cvt_pk_bf16_f32 v34, v16, v17
	v_cvt_pk_bf16_f32 v35, v18, v19
	s_and_b64 vcc, exec, s[6:7]
	global_store_dwordx4 v[52:53], v[32:35], off offset:256
	s_cbranch_vccnz .LBB0_763
	s_lshl_b32 s25, s12, 2
	s_add_i32 s34, s25, s74
	s_ashr_i32 s35, s34, 31
	v_ashrrev_i32_e32 v49, 31, v48
	s_mov_b64 s[66:67], -1
	s_mov_b64 s[56:57], 0
	s_cmp_lt_i32 s0, 9
	s_mov_b64 s[76:77], 0
	s_cbranch_scc1 .LBB0_765
	s_cmp_eq_u32 s0, 9
	s_mov_b64 s[76:77], -1
	s_cbranch_scc0 .LBB0_758
	s_lshl_b64 s[66:67], s[34:35], 18
	s_add_u32 s66, s48, s66
	s_addc_u32 s67, s49, s67
	v_lshlrev_b64 v[32:33], 10, v[48:49]
	v_and_b32_e32 v34, 0xffffffe0, v140
	v_lshl_add_u64 v[32:33], s[66:67], 0, v[32:33]
	v_ashrrev_i32_e32 v35, 31, v34
	v_lshl_add_u64 v[32:33], v[34:35], 2, v[32:33]
	v_lshlrev_b32_e32 v64, 2, v169
	v_lshl_add_u64 v[44:45], v[32:33], 0, v[64:65]
	v_mov_b32_e32 v32, v20
	v_mov_b32_e32 v33, v22
	v_mov_b32_e32 v34, v16
	v_mov_b32_e32 v35, v18
	global_store_dwordx4 v[44:45], v[32:35], off
	s_mov_b64 s[76:77], 0
	s_nop 0
	v_mov_b32_e32 v32, v21
	v_mov_b32_e32 v33, v23
	v_mov_b32_e32 v34, v17
	v_mov_b32_e32 v35, v19
	global_store_dwordx4 v[44:45], v[32:35], off offset:64

.LBB0_763:
	s_nop 1
	v_add_u32_e32 v16, 0xb0, v168
	v_ashrrev_i32_e32 v17, 31, v16
	v_lshlrev_b64 v[18:19], 6, v[16:17]
	v_lshl_add_u64 v[18:19], s[14:15], 0, v[18:19]
	v_lshl_add_u64 v[18:19], v[166:167], 2, v[18:19]
	global_load_dwordx4 v[18:21], v[18:19], off
	s_cmp_gt_i32 s23, 63
	s_waitcnt vmcnt(0) lgkmcnt(0)
	v_add_f32_e32 v17, v18, v19
	v_add_f32_e32 v18, v20, v21
	v_add_f32_e32 v17, v17, v18
	v_mov_b32_e32 v18, v17
	s_nop 1
	v_permlane16_swap_b32_e32 v17, v18
	v_add_f32_e32 v17, v17, v18
	v_mov_b32_e32 v18, v17
	s_nop 1
	v_permlane32_swap_b32_e32 v17, v18
	v_add_f32_e32 v17, v17, v18
	v_fmamk_f32 v18, v17, 0x3a800000, v229
	v_and_b32_e32 v17, 0x3ff, v16
	v_lshlrev_b32_e32 v19, 6, v17
	v_cmp_gt_f32_e32 vcc, s55, v18
	v_lshlrev_b32_e32 v64, 2, v19
	s_cbranch_scc0 .LBB0_769
	v_lshl_add_u64 v[20:21], s[16:17], 0, v[64:65]
	v_mov_b32_e32 v163, v65
	v_lshl_add_u64 v[20:21], v[20:21], 0, v[162:163]
	s_mov_b64 s[56:57], 0
	s_mov_b64 s[34:35], -1
	s_branch .LBB0_770

.LBB0_773:
	s_and_b64 vcc, exec, s[34:35]
	s_cbranch_vccz .LBB0_775
	global_load_dwordx4 v[32:35], v[20:21], off
	global_load_dwordx4 v[36:39], v[20:21], off offset:16
	s_waitcnt vmcnt(0) lgkmcnt(0)
	v_pk_mul_f32 v[40:41], v[12:13], v[32:33] op_sel:[1,1] op_sel_hi:[1,0]
	v_pk_mul_f32 v[20:21], v[12:13], v[32:33]
	v_pk_fma_f32 v[12:13], v[12:13], v[32:33], v[40:41] op_sel_hi:[0,1,1]
	v_mul_f32_e32 v12, v15, v35
	v_pk_fma_f32 v[32:33], v[14:15], v[34:35], v[12:13] op_sel_hi:[1,1,0] neg_lo:[0,0,1] neg_hi:[0,0,1]
	v_mul_f32_e32 v12, v15, v34
	v_pk_mul_f32 v[42:43], v[8:9], v[36:37] op_sel:[1,1] op_sel_hi:[1,0]
	v_pk_fma_f32 v[34:35], v[14:15], v[34:35], v[12:13] op_sel:[0,1,0] op_sel_hi:[1,0,0]
	v_pk_mul_f32 v[14:15], v[8:9], v[36:37]
	v_pk_fma_f32 v[8:9], v[8:9], v[36:37], v[42:43] op_sel_hi:[0,1,1]
	v_mul_f32_e32 v8, v11, v39
	v_pk_fma_f32 v[36:37], v[10:11], v[38:39], v[8:9] op_sel_hi:[1,1,0] neg_lo:[0,0,1] neg_hi:[0,0,1]
	v_mul_f32_e32 v8, v11, v38
	v_pk_fma_f32 v[38:39], v[10:11], v[38:39], v[8:9] op_sel:[0,1,0] op_sel_hi:[1,0,0]
	v_sub_f32_e32 v8, v14, v42
	v_sub_f32_e32 v12, v20, v40
	v_mov_b32_e32 v10, v36
	v_mov_b32_e32 v11, v38
	v_mov_b32_e32 v14, v32
	v_mov_b32_e32 v15, v34
.LBB0_775:
	v_mov_b64_e32 v[20:21], s[10:11]
	v_mad_i64_i32 v[20:21], s[34:35], v16, s93, v[20:21]
	v_cvt_pk_bf16_f32 v32, v12, v13
	v_cvt_pk_bf16_f32 v33, v14, v15
	v_cvt_pk_bf16_f32 v34, v8, v9
	v_cvt_pk_bf16_f32 v35, v10, v11
	v_lshl_add_u64 v[20:21], v[160:161], 1, v[20:21]
	s_and_b64 vcc, exec, s[6:7]
	v_subrev_u32_e32 v16, s13, v16
	global_store_dwordx4 v[20:21], v[32:35], off
	s_cbranch_vccnz .LBB0_786
	s_lshl_b32 s13, s12, 2
	s_add_i32 s34, s13, s74
	s_ashr_i32 s35, s34, 31
	s_mov_b64 s[76:77], -1
	s_mov_b64 s[56:57], 0
	s_cmp_lt_i32 s0, 9
	s_mov_b64 s[66:67], 0
	s_cbranch_scc1 .LBB0_782
	s_cmp_eq_u32 s0, 9
	s_mov_b64 s[66:67], -1
	s_cbranch_scc0 .LBB0_779
	s_lshl_b64 s[66:67], s[34:35], 18
	v_ashrrev_i32_e32 v17, 31, v16
	s_add_u32 s66, s48, s66
	s_addc_u32 s67, s49, s67
	v_lshlrev_b64 v[32:33], 10, v[16:17]
	v_and_b32_e32 v34, 0xffffffe0, v158
	v_lshl_add_u64 v[32:33], s[66:67], 0, v[32:33]
	v_ashrrev_i32_e32 v35, 31, v34
	v_lshl_add_u64 v[32:33], v[34:35], 2, v[32:33]
	v_lshlrev_b32_e32 v34, 2, v169
	v_mov_b32_e32 v35, v65
	v_lshl_add_u64 v[36:37], v[32:33], 0, v[34:35]
	v_mov_b32_e32 v32, v12
	v_mov_b32_e32 v33, v14
	v_mov_b32_e32 v34, v8
	v_mov_b32_e32 v35, v10
	global_store_dwordx4 v[36:37], v[32:35], off
	s_mov_b64 s[66:67], 0
	s_nop 0
	v_mov_b32_e32 v32, v13
	v_mov_b32_e32 v33, v15
	v_mov_b32_e32 v34, v9
	v_mov_b32_e32 v35, v11
	global_store_dwordx4 v[36:37], v[32:35], off offset:64

.LBB0_792:
	s_and_b64 vcc, exec, s[34:35]
	s_cbranch_vccz .LBB0_794
	global_load_dwordx4 v[10:13], v[8:9], off
	global_load_dwordx4 v[22:25], v[8:9], off offset:16
	s_waitcnt vmcnt(0) lgkmcnt(0)
	v_pk_mul_f32 v[14:15], v[4:5], v[10:11] op_sel:[1,1] op_sel_hi:[1,0]
	v_pk_mul_f32 v[8:9], v[4:5], v[10:11]
	v_pk_fma_f32 v[4:5], v[4:5], v[10:11], v[14:15] op_sel_hi:[0,1,1]
	v_mul_f32_e32 v4, v7, v13
	v_pk_fma_f32 v[10:11], v[6:7], v[12:13], v[4:5] op_sel_hi:[1,1,0] neg_lo:[0,0,1] neg_hi:[0,0,1]
	v_mul_f32_e32 v4, v7, v12
	v_pk_mul_f32 v[18:19], v[0:1], v[22:23] op_sel:[1,1] op_sel_hi:[1,0]
	v_pk_fma_f32 v[12:13], v[6:7], v[12:13], v[4:5] op_sel:[0,1,0] op_sel_hi:[1,0,0]
	v_pk_mul_f32 v[6:7], v[0:1], v[22:23]
	v_pk_fma_f32 v[0:1], v[0:1], v[22:23], v[18:19] op_sel_hi:[0,1,1]
	v_mul_f32_e32 v0, v3, v25
	v_pk_fma_f32 v[22:23], v[2:3], v[24:25], v[0:1] op_sel_hi:[1,1,0] neg_lo:[0,0,1] neg_hi:[0,0,1]
	v_mul_f32_e32 v0, v3, v24
	v_pk_fma_f32 v[24:25], v[2:3], v[24:25], v[0:1] op_sel:[0,1,0] op_sel_hi:[1,0,0]
	v_sub_f32_e32 v0, v6, v18
	v_sub_f32_e32 v4, v8, v14
	v_mov_b32_e32 v2, v22
	v_mov_b32_e32 v3, v24
	v_mov_b32_e32 v6, v10
	v_mov_b32_e32 v7, v12
.LBB0_794:
	v_cvt_pk_bf16_f32 v8, v4, v5
	v_cvt_pk_bf16_f32 v9, v6, v7
	v_cvt_pk_bf16_f32 v10, v0, v1
	v_cvt_pk_bf16_f32 v11, v2, v3
	s_and_b64 vcc, exec, s[6:7]
	global_store_dwordx4 v[20:21], v[8:11], off offset:256
	s_cbranch_vccnz .LBB0_805
	s_lshl_b32 s1, s12, 2
	s_add_i32 s6, s1, s74
	s_ashr_i32 s7, s6, 31
	v_ashrrev_i32_e32 v17, 31, v16
	s_mov_b64 s[56:57], -1
	s_mov_b64 s[12:13], 0
	s_cmp_lt_i32 s0, 9
	s_mov_b64 s[34:35], 0
	s_cbranch_scc1 .LBB0_799
	s_cmp_eq_u32 s0, 9
	s_mov_b64 s[34:35], -1
	s_cbranch_scc0 .LBB0_798
	s_lshl_b64 s[34:35], s[6:7], 18
	s_add_u32 s34, s48, s34
	s_addc_u32 s35, s49, s35
	v_lshlrev_b64 v[8:9], 10, v[16:17]
	v_and_b32_e32 v10, 0xffffffe0, v140
	v_lshl_add_u64 v[8:9], s[34:35], 0, v[8:9]
	v_ashrrev_i32_e32 v11, 31, v10
	v_lshl_add_u64 v[8:9], v[10:11], 2, v[8:9]
	v_lshlrev_b32_e32 v64, 2, v169
	v_lshl_add_u64 v[12:13], v[8:9], 0, v[64:65]
	v_mov_b32_e32 v8, v4
	v_mov_b32_e32 v9, v6
	v_mov_b32_e32 v10, v0
	v_mov_b32_e32 v11, v2
	global_store_dwordx4 v[12:13], v[8:11], off
	s_mov_b64 s[34:35], 0
	s_nop 0
	v_mov_b32_e32 v8, v5
	v_mov_b32_e32 v9, v7
	v_mov_b32_e32 v10, v1
	v_mov_b32_e32 v11, v3
	global_store_dwordx4 v[12:13], v[8:11], off offset:64

.LBB0_1887:
	s_add_i32 s0, s8, -16
	s_lshr_b32 s0, s0, 2
	s_add_i32 s0, s0, 1
	s_cmp_gt_i32 s8, 15
	s_cselect_b32 s96, s0, 0
	s_lshl_b32 s0, s91, 8
	v_mov_b32_e32 v164, v226
	v_mov_b32_e32 v165, v191
	s_or_b32 s0, s0, s87
	s_mul_hi_u32 s1, s96, 0x6000
	v_lshl_add_u32 v162, v165, 3, s0
	s_mul_i32 s0, s96, 0x6000
	s_add_u32 s0, s79, s0
	v_ashrrev_i32_e32 v163, 31, v162
	s_addc_u32 s1, s84, s1
	v_lshlrev_b64 v[56:57], 2, v[162:163]
	v_lshl_add_u64 v[60:61], s[0:1], 0, v[56:57]
	v_lshl_add_u64 v[56:57], s[18:19], 0, v[56:57]
	s_lshl_b64 s[0:1], s[96:97], 12
	v_lshl_add_u64 v[62:63], v[56:57], 0, s[0:1]
	s_lshl_b32 s0, s8, 8
	s_add_i32 s0, s0, s86
	v_add_u32_e32 v210, s0, v164
	v_lshlrev_b64 v[206:207], 1, v[162:163]
	v_ashrrev_i32_e32 v211, 31, v210
	v_lshl_add_u64 v[208:209], s[12:13], 0, v[206:207]
	v_lshlrev_b64 v[224:225], 11, v[210:211]
	v_lshl_add_u64 v[162:163], v[208:209], 0, v[224:225]
	global_load_dwordx4 v[86:89], v[60:61], off
	global_load_dwordx4 v[74:77], v[62:63], off
	global_load_dwordx4 v[82:85], v[60:61], off offset:16
	global_load_dwordx4 v[78:81], v[62:63], off offset:16
	global_load_dwordx4 v[70:73], v[60:61], off offset:512
	global_load_dwordx4 v[56:59], v[62:63], off offset:512
	global_load_dwordx4 v[66:69], v[60:61], off offset:528
	s_nop 0
	global_load_dwordx4 v[60:63], v[62:63], off offset:528
	s_nop 0
	global_load_dwordx4 v[242:245], v[162:163], off
	global_load_dwordx4 v[186:189], v[162:163], off offset:256
	v_add_u32_e32 v220, 16, v210
	v_ashrrev_i32_e32 v221, 31, v220
	v_add_u32_e32 v216, 32, v210
	v_lshlrev_b64 v[222:223], 11, v[220:221]
	v_ashrrev_i32_e32 v217, 31, v216
	v_add_u32_e32 v212, 48, v210
	v_lshl_add_u64 v[162:163], v[208:209], 0, v[222:223]
	v_lshlrev_b64 v[218:219], 11, v[216:217]
	v_ashrrev_i32_e32 v213, 31, v212
	global_load_dwordx4 v[182:185], v[162:163], off
	global_load_dwordx4 v[178:181], v[162:163], off offset:256
	v_lshl_add_u64 v[162:163], v[208:209], 0, v[218:219]
	v_lshlrev_b64 v[214:215], 11, v[212:213]
	global_load_dwordx4 v[174:177], v[162:163], off
	global_load_dwordx4 v[170:173], v[162:163], off offset:256
	v_lshl_add_u64 v[162:163], v[208:209], 0, v[214:215]
	v_cmp_eq_u32_e32 vcc, 0, v165
	global_load_dwordx4 v[166:169], v[162:163], off
	s_nop 0
	global_load_dwordx4 v[162:165], v[162:163], off offset:256
	s_waitcnt vmcnt(0) lgkmcnt(0)
	v_lshlrev_b32_e32 v246, 16, v242
	v_and_b32_e32 v247, 0xffff0000, v242
	v_lshlrev_b32_e32 v242, 16, v243
	v_and_b32_e32 v243, 0xffff0000, v243
	v_lshlrev_b32_e32 v248, 16, v244
	v_and_b32_e32 v249, 0xffff0000, v244
	v_lshlrev_b32_e32 v244, 16, v245
	v_and_b32_e32 v245, 0xffff0000, v245
	v_pk_fma_f32 v[160:161], v[160:161], v[88:89], v[242:243]
	v_pk_fma_f32 v[242:243], v[158:159], v[86:87], v[246:247]
	v_pk_fma_f32 v[244:245], v[156:157], v[84:85], v[244:245]
	v_pk_fma_f32 v[246:247], v[154:155], v[82:83], v[248:249]
	v_lshl_add_u64 v[154:155], s[12:13], 0, v[224:225]
	v_cvt_pk_bf16_f32 v156, v242, v243
	v_cvt_pk_bf16_f32 v157, v160, v161
	v_cvt_pk_bf16_f32 v158, v246, v247
	v_cvt_pk_bf16_f32 v159, v244, v245
	v_lshl_add_u64 v[154:155], v[154:155], 0, v[206:207]
	global_store_dwordx4 v[154:155], v[156:159], off
	s_nop 1
	v_mul_f32_e32 v156, v243, v243
	v_mul_f32_e32 v157, v161, v161
	v_fmac_f32_e32 v156, v242, v242
	v_fmac_f32_e32 v157, v160, v160
	v_add_f32_e32 v156, v156, v157
	v_mul_f32_e32 v157, v247, v247
	v_fmac_f32_e32 v157, v246, v246
	v_add_f32_e32 v156, v157, v156
	v_mul_f32_e32 v157, v245, v245
	v_fmac_f32_e32 v157, v244, v244
	v_add_f32_e32 v241, v157, v156
	v_pk_mul_f32 v[158:159], v[76:77], v[160:161]
	v_pk_mul_f32 v[156:157], v[74:75], v[242:243]
	v_pk_mul_f32 v[160:161], v[80:81], v[244:245]
	v_pk_mul_f32 v[242:243], v[78:79], v[246:247]
	v_cvt_pk_bf16_f32 v156, v156, v157
	v_cvt_pk_bf16_f32 v157, v158, v159
	v_cvt_pk_bf16_f32 v159, v160, v161
	v_lshl_add_u64 v[160:161], s[14:15], 0, v[224:225]
	v_cvt_pk_bf16_f32 v158, v242, v243
	v_lshl_add_u64 v[160:161], v[160:161], 0, v[206:207]
	global_store_dwordx4 v[160:161], v[156:159], off
	s_nop 1
	v_lshlrev_b32_e32 v156, 16, v186
	v_and_b32_e32 v157, 0xffff0000, v186
	v_lshlrev_b32_e32 v158, 16, v187
	v_and_b32_e32 v159, 0xffff0000, v187
	v_lshlrev_b32_e32 v186, 16, v188
	v_and_b32_e32 v187, 0xffff0000, v188
	v_lshlrev_b32_e32 v188, 16, v189
	v_and_b32_e32 v189, 0xffff0000, v189
	v_pk_fma_f32 v[152:153], v[152:153], v[72:73], v[158:159]
	v_pk_fma_f32 v[150:151], v[150:151], v[70:71], v[156:157]
	v_pk_fma_f32 v[156:157], v[148:149], v[68:69], v[188:189]
	v_pk_fma_f32 v[158:159], v[146:147], v[66:67], v[186:187]
	v_cvt_pk_bf16_f32 v146, v150, v151
	v_cvt_pk_bf16_f32 v147, v152, v153
	v_cvt_pk_bf16_f32 v148, v158, v159
	v_cvt_pk_bf16_f32 v149, v156, v157
	global_store_dwordx4 v[154:155], v[146:149], off offset:256
	s_nop 1
	v_mul_f32_e32 v146, v151, v151
	v_mul_f32_e32 v147, v153, v153
	v_fmac_f32_e32 v146, v150, v150
	v_fmac_f32_e32 v147, v152, v152
	v_add_f32_e32 v146, v146, v147
	v_mul_f32_e32 v147, v159, v159
	v_fmac_f32_e32 v147, v158, v158
	v_add_f32_e32 v146, v147, v146
	v_mul_f32_e32 v147, v157, v157
	v_fmac_f32_e32 v147, v156, v156
	v_add_f32_e32 v146, v147, v146
	v_add_f32_e32 v154, v241, v146
	v_pk_mul_f32 v[148:149], v[58:59], v[152:153]
	v_pk_mul_f32 v[146:147], v[56:57], v[150:151]
	v_pk_mul_f32 v[150:151], v[62:63], v[156:157]
	v_pk_mul_f32 v[152:153], v[60:61], v[158:159]
	v_cvt_pk_bf16_f32 v146, v146, v147
	v_cvt_pk_bf16_f32 v147, v148, v149
	v_cvt_pk_bf16_f32 v148, v152, v153
	v_cvt_pk_bf16_f32 v149, v150, v151
	global_store_dwordx4 v[160:161], v[146:149], off offset:256
	s_nop 1
	v_mov_b32_e32 v146, v154
	s_nop 1
	v_permlane16_swap_b32_e32 v154, v146
	v_add_f32_e32 v146, v154, v146
	v_mov_b32_e32 v147, v146
	s_nop 1
	v_permlane32_swap_b32_e32 v146, v147
	s_and_saveexec_b64 s[34:35], vcc
	s_cbranch_execz .LBB0_1889
	v_add_f32_e32 v148, v146, v147
	s_lshl_b32 s0, s91, 2
	v_lshlrev_b64 v[146:147], 6, v[210:211]
	s_ashr_i32 s1, s0, 31
	v_lshl_add_u64 v[146:147], s[16:17], 0, v[146:147]
	v_lshl_add_u64 v[146:147], s[0:1], 2, v[146:147]
	s_lshl_b32 s96, s85, 2
	v_lshl_add_u64 v[146:147], v[146:147], 0, s[96:97]
	global_store_dword v[146:147], v148, off
.LBB0_1889:
	s_or_b64 exec, exec, s[34:35]
	v_lshlrev_b32_e32 v146, 16, v182
	v_and_b32_e32 v147, 0xffff0000, v182
	v_lshlrev_b32_e32 v148, 16, v183
	v_and_b32_e32 v149, 0xffff0000, v183
	v_lshlrev_b32_e32 v150, 16, v184
	v_and_b32_e32 v151, 0xffff0000, v184
	v_lshlrev_b32_e32 v152, 16, v185
	v_and_b32_e32 v153, 0xffff0000, v185
	v_pk_fma_f32 v[144:145], v[144:145], v[88:89], v[148:149]
	v_pk_fma_f32 v[142:143], v[142:143], v[86:87], v[146:147]
	v_pk_fma_f32 v[146:147], v[140:141], v[84:85], v[152:153]
	v_pk_fma_f32 v[148:149], v[138:139], v[82:83], v[150:151]
	v_lshl_add_u64 v[150:151], s[12:13], 0, v[222:223]
	v_cvt_pk_bf16_f32 v138, v142, v143
	v_cvt_pk_bf16_f32 v139, v144, v145
	v_cvt_pk_bf16_f32 v140, v148, v149
	v_cvt_pk_bf16_f32 v141, v146, v147
	v_lshl_add_u64 v[150:151], v[150:151], 0, v[206:207]
	global_store_dwordx4 v[150:151], v[138:141], off
	s_nop 1
	v_mul_f32_e32 v138, v143, v143
	v_mul_f32_e32 v139, v145, v145
	v_fmac_f32_e32 v138, v142, v142
	v_fmac_f32_e32 v139, v144, v144
	v_add_f32_e32 v138, v138, v139
	v_mul_f32_e32 v139, v149, v149
	v_fmac_f32_e32 v139, v148, v148
	v_add_f32_e32 v138, v139, v138
	v_mul_f32_e32 v139, v147, v147
	v_fmac_f32_e32 v139, v146, v146
	v_add_f32_e32 v152, v139, v138
	v_pk_mul_f32 v[140:141], v[76:77], v[144:145]
	v_pk_mul_f32 v[138:139], v[74:75], v[142:143]
	v_pk_mul_f32 v[142:143], v[80:81], v[146:147]
	v_pk_mul_f32 v[144:145], v[78:79], v[148:149]
	v_cvt_pk_bf16_f32 v138, v138, v139
	v_cvt_pk_bf16_f32 v139, v140, v141
	v_cvt_pk_bf16_f32 v141, v142, v143
	v_lshl_add_u64 v[142:143], s[14:15], 0, v[222:223]
	v_cvt_pk_bf16_f32 v140, v144, v145
	v_lshl_add_u64 v[142:143], v[142:143], 0, v[206:207]
	global_store_dwordx4 v[142:143], v[138:141], off
	v_lshlrev_b32_e32 v144, 16, v180
	v_and_b32_e32 v145, 0xffff0000, v180
	v_lshlrev_b32_e32 v138, 16, v178
	v_and_b32_e32 v139, 0xffff0000, v178
	v_lshlrev_b32_e32 v140, 16, v179
	v_and_b32_e32 v141, 0xffff0000, v179
	v_lshlrev_b32_e32 v146, 16, v181
	v_and_b32_e32 v147, 0xffff0000, v181
	v_pk_fma_f32 v[136:137], v[136:137], v[72:73], v[140:141]
	v_pk_fma_f32 v[134:135], v[134:135], v[70:71], v[138:139]
	v_pk_fma_f32 v[138:139], v[132:133], v[68:69], v[146:147]
	v_pk_fma_f32 v[140:141], v[130:131], v[66:67], v[144:145]
	v_cvt_pk_bf16_f32 v130, v134, v135
	v_cvt_pk_bf16_f32 v131, v136, v137
	v_cvt_pk_bf16_f32 v132, v140, v141
	v_cvt_pk_bf16_f32 v133, v138, v139
	global_store_dwordx4 v[150:151], v[130:133], off offset:256
	s_nop 1
	v_mul_f32_e32 v130, v135, v135
	v_mul_f32_e32 v131, v137, v137
	v_fmac_f32_e32 v130, v134, v134
	v_fmac_f32_e32 v131, v136, v136
	v_add_f32_e32 v130, v130, v131
	v_mul_f32_e32 v131, v141, v141
	v_fmac_f32_e32 v131, v140, v140
	v_add_f32_e32 v130, v131, v130
	v_mul_f32_e32 v131, v139, v139
	v_fmac_f32_e32 v131, v138, v138
	v_add_f32_e32 v130, v131, v130
	v_add_f32_e32 v144, v152, v130
	v_pk_mul_f32 v[132:133], v[58:59], v[136:137]
	v_pk_mul_f32 v[130:131], v[56:57], v[134:135]
	v_pk_mul_f32 v[134:135], v[62:63], v[138:139]
	v_pk_mul_f32 v[136:137], v[60:61], v[140:141]
	v_cvt_pk_bf16_f32 v130, v130, v131
	v_cvt_pk_bf16_f32 v131, v132, v133
	v_cvt_pk_bf16_f32 v132, v136, v137
	v_cvt_pk_bf16_f32 v133, v134, v135
	global_store_dwordx4 v[142:143], v[130:133], off offset:256
	s_nop 1
	v_mov_b32_e32 v130, v144
	s_nop 1
	v_permlane16_swap_b32_e32 v144, v130
	v_add_f32_e32 v130, v144, v130
	v_mov_b32_e32 v131, v130
	s_nop 1
	v_permlane32_swap_b32_e32 v130, v131
	s_and_saveexec_b64 s[34:35], vcc
	s_cbranch_execz .LBB0_1891
	v_add_f32_e32 v132, v130, v131
	s_lshl_b32 s0, s91, 2
	v_lshlrev_b64 v[130:131], 6, v[220:221]
	s_ashr_i32 s1, s0, 31
	v_lshl_add_u64 v[130:131], s[16:17], 0, v[130:131]
	v_lshl_add_u64 v[130:131], s[0:1], 2, v[130:131]
	s_lshl_b32 s96, s85, 2
	v_lshl_add_u64 v[130:131], v[130:131], 0, s[96:97]
	global_store_dword v[130:131], v132, off
.LBB0_1891:
	s_or_b64 exec, exec, s[34:35]
	v_lshlrev_b32_e32 v130, 16, v174
	v_and_b32_e32 v131, 0xffff0000, v174
	v_lshlrev_b32_e32 v132, 16, v175
	v_and_b32_e32 v133, 0xffff0000, v175
	v_lshlrev_b32_e32 v134, 16, v176
	v_and_b32_e32 v135, 0xffff0000, v176
	v_lshlrev_b32_e32 v136, 16, v177
	v_and_b32_e32 v137, 0xffff0000, v177
	v_pk_fma_f32 v[128:129], v[128:129], v[88:89], v[132:133]
	v_pk_fma_f32 v[126:127], v[126:127], v[86:87], v[130:131]
	v_pk_fma_f32 v[130:131], v[124:125], v[84:85], v[136:137]
	v_pk_fma_f32 v[132:133], v[122:123], v[82:83], v[134:135]
	v_lshl_add_u64 v[134:135], s[12:13], 0, v[218:219]
	v_cvt_pk_bf16_f32 v122, v126, v127
	v_cvt_pk_bf16_f32 v123, v128, v129
	v_cvt_pk_bf16_f32 v124, v132, v133
	v_cvt_pk_bf16_f32 v125, v130, v131
	v_lshl_add_u64 v[134:135], v[134:135], 0, v[206:207]
	global_store_dwordx4 v[134:135], v[122:125], off
	s_nop 1
	v_mul_f32_e32 v122, v127, v127
	v_mul_f32_e32 v123, v129, v129
	v_fmac_f32_e32 v122, v126, v126
	v_fmac_f32_e32 v123, v128, v128
	v_add_f32_e32 v122, v122, v123
	v_mul_f32_e32 v123, v133, v133
	v_fmac_f32_e32 v123, v132, v132
	v_add_f32_e32 v122, v123, v122
	v_mul_f32_e32 v123, v131, v131
	v_fmac_f32_e32 v123, v130, v130
	v_add_f32_e32 v136, v123, v122
	v_pk_mul_f32 v[124:125], v[76:77], v[128:129]
	v_pk_mul_f32 v[122:123], v[74:75], v[126:127]
	v_pk_mul_f32 v[126:127], v[80:81], v[130:131]
	v_pk_mul_f32 v[128:129], v[78:79], v[132:133]
	v_cvt_pk_bf16_f32 v122, v122, v123
	v_cvt_pk_bf16_f32 v123, v124, v125
	v_cvt_pk_bf16_f32 v125, v126, v127
	v_lshl_add_u64 v[126:127], s[14:15], 0, v[218:219]
	v_cvt_pk_bf16_f32 v124, v128, v129
	v_lshl_add_u64 v[126:127], v[126:127], 0, v[206:207]
	global_store_dwordx4 v[126:127], v[122:125], off
	v_lshlrev_b32_e32 v128, 16, v172
	v_and_b32_e32 v129, 0xffff0000, v172
	v_lshlrev_b32_e32 v122, 16, v170
	v_and_b32_e32 v123, 0xffff0000, v170
	v_lshlrev_b32_e32 v124, 16, v171
	v_and_b32_e32 v125, 0xffff0000, v171
	v_lshlrev_b32_e32 v130, 16, v173
	v_and_b32_e32 v131, 0xffff0000, v173
	v_pk_fma_f32 v[120:121], v[120:121], v[72:73], v[124:125]
	v_pk_fma_f32 v[118:119], v[118:119], v[70:71], v[122:123]
	v_pk_fma_f32 v[122:123], v[116:117], v[68:69], v[130:131]
	v_pk_fma_f32 v[124:125], v[114:115], v[66:67], v[128:129]
	v_cvt_pk_bf16_f32 v114, v118, v119
	v_cvt_pk_bf16_f32 v115, v120, v121
	v_cvt_pk_bf16_f32 v116, v124, v125
	v_cvt_pk_bf16_f32 v117, v122, v123
	global_store_dwordx4 v[134:135], v[114:117], off offset:256
	s_nop 1
	v_mul_f32_e32 v114, v119, v119
	v_mul_f32_e32 v115, v121, v121
	v_fmac_f32_e32 v114, v118, v118
	v_fmac_f32_e32 v115, v120, v120
	v_add_f32_e32 v114, v114, v115
	v_mul_f32_e32 v115, v125, v125
	v_fmac_f32_e32 v115, v124, v124
	v_add_f32_e32 v114, v115, v114
	v_mul_f32_e32 v115, v123, v123
	v_fmac_f32_e32 v115, v122, v122
	v_add_f32_e32 v114, v115, v114
	v_add_f32_e32 v128, v136, v114
	v_pk_mul_f32 v[116:117], v[58:59], v[120:121]
	v_pk_mul_f32 v[114:115], v[56:57], v[118:119]
	v_pk_mul_f32 v[118:119], v[62:63], v[122:123]
	v_pk_mul_f32 v[120:121], v[60:61], v[124:125]
	v_cvt_pk_bf16_f32 v114, v114, v115
	v_cvt_pk_bf16_f32 v115, v116, v117
	v_cvt_pk_bf16_f32 v116, v120, v121
	v_cvt_pk_bf16_f32 v117, v118, v119
	global_store_dwordx4 v[126:127], v[114:117], off offset:256
	s_nop 1
	v_mov_b32_e32 v114, v128
	s_nop 1
	v_permlane16_swap_b32_e32 v128, v114
	v_add_f32_e32 v114, v128, v114
	v_mov_b32_e32 v115, v114
	s_nop 1
	v_permlane32_swap_b32_e32 v114, v115
	s_and_saveexec_b64 s[34:35], vcc
	s_cbranch_execz .LBB0_1893
	v_add_f32_e32 v116, v114, v115
	s_lshl_b32 s0, s91, 2
	v_lshlrev_b64 v[114:115], 6, v[216:217]
	s_ashr_i32 s1, s0, 31
	v_lshl_add_u64 v[114:115], s[16:17], 0, v[114:115]
	v_lshl_add_u64 v[114:115], s[0:1], 2, v[114:115]
	s_lshl_b32 s96, s85, 2
	v_lshl_add_u64 v[114:115], v[114:115], 0, s[96:97]
	global_store_dword v[114:115], v116, off
.LBB0_1893:
	s_or_b64 exec, exec, s[34:35]
	v_lshlrev_b32_e32 v114, 16, v166
	v_and_b32_e32 v115, 0xffff0000, v166
	v_lshlrev_b32_e32 v116, 16, v167
	v_and_b32_e32 v117, 0xffff0000, v167
	v_lshlrev_b32_e32 v118, 16, v168
	v_and_b32_e32 v119, 0xffff0000, v168
	v_lshlrev_b32_e32 v120, 16, v169
	v_and_b32_e32 v121, 0xffff0000, v169
	v_pk_fma_f32 v[112:113], v[112:113], v[88:89], v[116:117]
	v_pk_fma_f32 v[110:111], v[110:111], v[86:87], v[114:115]
	v_pk_fma_f32 v[114:115], v[108:109], v[84:85], v[120:121]
	v_pk_fma_f32 v[116:117], v[106:107], v[82:83], v[118:119]
	v_lshl_add_u64 v[118:119], s[12:13], 0, v[214:215]
	v_cvt_pk_bf16_f32 v106, v110, v111
	v_cvt_pk_bf16_f32 v107, v112, v113
	v_cvt_pk_bf16_f32 v108, v116, v117
	v_cvt_pk_bf16_f32 v109, v114, v115
	v_lshl_add_u64 v[118:119], v[118:119], 0, v[206:207]
	global_store_dwordx4 v[118:119], v[106:109], off
	s_nop 1
	v_mul_f32_e32 v106, v111, v111
	v_mul_f32_e32 v107, v113, v113
	v_fmac_f32_e32 v106, v110, v110
	v_fmac_f32_e32 v107, v112, v112
	v_add_f32_e32 v106, v106, v107
	v_mul_f32_e32 v107, v117, v117
	v_fmac_f32_e32 v107, v116, v116
	v_add_f32_e32 v106, v107, v106
	v_mul_f32_e32 v107, v115, v115
	v_fmac_f32_e32 v107, v114, v114
	v_add_f32_e32 v120, v107, v106
	v_pk_mul_f32 v[108:109], v[76:77], v[112:113]
	v_pk_mul_f32 v[106:107], v[74:75], v[110:111]
	v_pk_mul_f32 v[110:111], v[80:81], v[114:115]
	v_pk_mul_f32 v[112:113], v[78:79], v[116:117]
	v_cvt_pk_bf16_f32 v106, v106, v107
	v_cvt_pk_bf16_f32 v107, v108, v109
	v_cvt_pk_bf16_f32 v109, v110, v111
	v_lshl_add_u64 v[110:111], s[14:15], 0, v[214:215]
	v_cvt_pk_bf16_f32 v108, v112, v113
	v_lshl_add_u64 v[110:111], v[110:111], 0, v[206:207]
	global_store_dwordx4 v[110:111], v[106:109], off
	v_lshlrev_b32_e32 v112, 16, v164
	v_and_b32_e32 v113, 0xffff0000, v164
	v_lshlrev_b32_e32 v106, 16, v162
	v_and_b32_e32 v107, 0xffff0000, v162
	v_lshlrev_b32_e32 v108, 16, v163
	v_and_b32_e32 v109, 0xffff0000, v163
	v_lshlrev_b32_e32 v114, 16, v165
	v_and_b32_e32 v115, 0xffff0000, v165
	v_pk_fma_f32 v[104:105], v[104:105], v[72:73], v[108:109]
	v_pk_fma_f32 v[102:103], v[102:103], v[70:71], v[106:107]
	v_pk_fma_f32 v[106:107], v[100:101], v[68:69], v[114:115]
	v_pk_fma_f32 v[108:109], v[98:99], v[66:67], v[112:113]
	v_cvt_pk_bf16_f32 v98, v102, v103
	v_cvt_pk_bf16_f32 v99, v104, v105
	v_cvt_pk_bf16_f32 v100, v108, v109
	v_cvt_pk_bf16_f32 v101, v106, v107
	global_store_dwordx4 v[118:119], v[98:101], off offset:256
	s_nop 1
	v_mul_f32_e32 v98, v103, v103
	v_mul_f32_e32 v99, v105, v105
	v_fmac_f32_e32 v98, v102, v102
	v_fmac_f32_e32 v99, v104, v104
	v_add_f32_e32 v98, v98, v99
	v_mul_f32_e32 v99, v109, v109
	v_fmac_f32_e32 v99, v108, v108
	v_add_f32_e32 v98, v99, v98
	v_mul_f32_e32 v99, v107, v107
	v_fmac_f32_e32 v99, v106, v106
	v_add_f32_e32 v98, v99, v98
	v_add_f32_e32 v112, v120, v98
	v_pk_mul_f32 v[100:101], v[58:59], v[104:105]
	v_pk_mul_f32 v[98:99], v[56:57], v[102:103]
	v_pk_mul_f32 v[102:103], v[62:63], v[106:107]
	v_pk_mul_f32 v[104:105], v[60:61], v[108:109]
	v_cvt_pk_bf16_f32 v98, v98, v99
	v_cvt_pk_bf16_f32 v99, v100, v101
	v_cvt_pk_bf16_f32 v100, v104, v105
	v_cvt_pk_bf16_f32 v101, v102, v103
	global_store_dwordx4 v[110:111], v[98:101], off offset:256
	s_nop 1
	v_mov_b32_e32 v98, v112
	s_nop 1
	v_permlane16_swap_b32_e32 v112, v98
	v_add_f32_e32 v98, v112, v98
	v_mov_b32_e32 v99, v98
	s_nop 1
	v_permlane32_swap_b32_e32 v98, v99
	s_and_saveexec_b64 s[34:35], vcc
	s_cbranch_execz .LBB0_1895
	v_add_f32_e32 v100, v98, v99
	s_lshl_b32 s0, s91, 2
	v_lshlrev_b64 v[98:99], 6, v[212:213]
	s_ashr_i32 s1, s0, 31
	v_lshl_add_u64 v[98:99], s[16:17], 0, v[98:99]
	v_lshl_add_u64 v[98:99], s[0:1], 2, v[98:99]
	s_lshl_b32 s96, s85, 2
	v_lshl_add_u64 v[98:99], v[98:99], 0, s[96:97]
	global_store_dword v[98:99], v100, off
.LBB0_1895:
	s_or_b64 exec, exec, s[34:35]
	v_add_u32_e32 v138, 0x80, v210
	v_ashrrev_i32_e32 v139, 31, v138
	v_lshlrev_b64 v[140:141], 11, v[138:139]
	v_lshl_add_u64 v[98:99], v[208:209], 0, v[140:141]
	global_load_dwordx4 v[142:145], v[98:99], off
	global_load_dwordx4 v[122:125], v[98:99], off offset:256
	v_add_u32_e32 v134, 0x90, v210
	v_ashrrev_i32_e32 v135, 31, v134
	v_add_u32_e32 v130, 0xa0, v210
	v_lshlrev_b64 v[136:137], 11, v[134:135]
	v_ashrrev_i32_e32 v131, 31, v130
	v_add_u32_e32 v126, 0xb0, v210
	v_lshl_add_u64 v[98:99], v[208:209], 0, v[136:137]
	v_lshlrev_b64 v[132:133], 11, v[130:131]
	v_ashrrev_i32_e32 v127, 31, v126
	global_load_dwordx4 v[118:121], v[98:99], off
	global_load_dwordx4 v[114:117], v[98:99], off offset:256
	v_lshl_add_u64 v[98:99], v[208:209], 0, v[132:133]
	v_lshlrev_b64 v[128:129], 11, v[126:127]
	global_load_dwordx4 v[110:113], v[98:99], off
	global_load_dwordx4 v[106:109], v[98:99], off offset:256
	v_lshl_add_u64 v[98:99], v[208:209], 0, v[128:129]
	global_load_dwordx4 v[102:105], v[98:99], off
	s_nop 0
	global_load_dwordx4 v[98:101], v[98:99], off offset:256
	s_waitcnt vmcnt(0) lgkmcnt(0)
	v_lshlrev_b32_e32 v146, 16, v142
	v_and_b32_e32 v147, 0xffff0000, v142
	v_lshlrev_b32_e32 v142, 16, v143
	v_and_b32_e32 v143, 0xffff0000, v143
	v_lshlrev_b32_e32 v148, 16, v144
	v_and_b32_e32 v149, 0xffff0000, v144
	v_lshlrev_b32_e32 v144, 16, v145
	v_and_b32_e32 v145, 0xffff0000, v145
	v_pk_fma_f32 v[96:97], v[96:97], v[88:89], v[142:143]
	v_pk_fma_f32 v[142:143], v[94:95], v[86:87], v[146:147]
	v_pk_fma_f32 v[144:145], v[92:93], v[84:85], v[144:145]
	v_pk_fma_f32 v[146:147], v[90:91], v[82:83], v[148:149]
	v_lshl_add_u64 v[90:91], s[12:13], 0, v[140:141]
	v_cvt_pk_bf16_f32 v92, v142, v143
	v_cvt_pk_bf16_f32 v93, v96, v97
	v_cvt_pk_bf16_f32 v94, v146, v147
	v_cvt_pk_bf16_f32 v95, v144, v145
	v_lshl_add_u64 v[90:91], v[90:91], 0, v[206:207]
	global_store_dwordx4 v[90:91], v[92:95], off
	s_nop 1
	v_mul_f32_e32 v92, v143, v143
	v_mul_f32_e32 v93, v97, v97
	v_fmac_f32_e32 v92, v142, v142
	v_fmac_f32_e32 v93, v96, v96
	v_add_f32_e32 v92, v92, v93
	v_mul_f32_e32 v93, v147, v147
	v_fmac_f32_e32 v93, v146, v146
	v_add_f32_e32 v92, v93, v92
	v_mul_f32_e32 v93, v145, v145
	v_fmac_f32_e32 v93, v144, v144
	v_add_f32_e32 v148, v93, v92
	v_pk_mul_f32 v[92:93], v[76:77], v[96:97]
	v_pk_mul_f32 v[94:95], v[74:75], v[142:143]
	v_pk_mul_f32 v[142:143], v[80:81], v[144:145]
	v_pk_mul_f32 v[96:97], v[78:79], v[146:147]
	v_cvt_pk_bf16_f32 v94, v94, v95
	v_cvt_pk_bf16_f32 v95, v92, v93
	v_lshl_add_u64 v[92:93], s[14:15], 0, v[140:141]
	v_cvt_pk_bf16_f32 v96, v96, v97
	v_cvt_pk_bf16_f32 v97, v142, v143
	v_lshl_add_u64 v[92:93], v[92:93], 0, v[206:207]
	global_store_dwordx4 v[92:93], v[94:97], off
	s_nop 1
	v_lshlrev_b32_e32 v94, 16, v122
	v_and_b32_e32 v95, 0xffff0000, v122
	v_lshlrev_b32_e32 v96, 16, v123
	v_and_b32_e32 v97, 0xffff0000, v123
	v_lshlrev_b32_e32 v122, 16, v124
	v_and_b32_e32 v123, 0xffff0000, v124
	v_lshlrev_b32_e32 v124, 16, v125
	v_and_b32_e32 v125, 0xffff0000, v125
	v_pk_fma_f32 v[54:55], v[54:55], v[72:73], v[96:97]
	v_pk_fma_f32 v[52:53], v[52:53], v[70:71], v[94:95]
	v_pk_fma_f32 v[94:95], v[50:51], v[68:69], v[124:125]
	v_pk_fma_f32 v[96:97], v[48:49], v[66:67], v[122:123]
	v_cvt_pk_bf16_f32 v48, v52, v53
	v_cvt_pk_bf16_f32 v49, v54, v55
	v_cvt_pk_bf16_f32 v50, v96, v97
	v_cvt_pk_bf16_f32 v51, v94, v95
	global_store_dwordx4 v[90:91], v[48:51], off offset:256
	s_nop 1
	v_mul_f32_e32 v48, v53, v53
	v_mul_f32_e32 v49, v55, v55
	v_fmac_f32_e32 v48, v52, v52
	v_fmac_f32_e32 v49, v54, v54
	v_add_f32_e32 v48, v48, v49
	v_mul_f32_e32 v49, v97, v97
	v_fmac_f32_e32 v49, v96, v96
	v_add_f32_e32 v48, v49, v48
	v_mul_f32_e32 v49, v95, v95
	v_fmac_f32_e32 v49, v94, v94
	v_add_f32_e32 v48, v49, v48
	v_add_f32_e32 v90, v148, v48
	v_pk_mul_f32 v[50:51], v[58:59], v[54:55]
	v_pk_mul_f32 v[48:49], v[56:57], v[52:53]
	v_pk_mul_f32 v[52:53], v[62:63], v[94:95]
	v_pk_mul_f32 v[54:55], v[60:61], v[96:97]
	v_cvt_pk_bf16_f32 v48, v48, v49
	v_cvt_pk_bf16_f32 v49, v50, v51
	v_cvt_pk_bf16_f32 v50, v54, v55
	v_cvt_pk_bf16_f32 v51, v52, v53
	global_store_dwordx4 v[92:93], v[48:51], off offset:256
	s_nop 1
	v_mov_b32_e32 v48, v90
	s_nop 1
	v_permlane16_swap_b32_e32 v90, v48
	v_add_f32_e32 v48, v90, v48
	v_mov_b32_e32 v49, v48
	s_nop 1
	v_permlane32_swap_b32_e32 v48, v49
	s_and_saveexec_b64 s[34:35], vcc
	s_cbranch_execz .LBB0_1897
	v_add_f32_e32 v50, v48, v49
	s_lshl_b32 s0, s91, 2
	v_lshlrev_b64 v[48:49], 6, v[138:139]
	s_ashr_i32 s1, s0, 31
	v_lshl_add_u64 v[48:49], s[16:17], 0, v[48:49]
	v_lshl_add_u64 v[48:49], s[0:1], 2, v[48:49]
	s_lshl_b32 s96, s85, 2
	v_lshl_add_u64 v[48:49], v[48:49], 0, s[96:97]
	global_store_dword v[48:49], v50, off
.LBB0_1897:
	s_or_b64 exec, exec, s[34:35]
	v_lshlrev_b32_e32 v48, 16, v118
	v_and_b32_e32 v49, 0xffff0000, v118
	v_lshlrev_b32_e32 v50, 16, v119
	v_and_b32_e32 v51, 0xffff0000, v119
	v_lshlrev_b32_e32 v52, 16, v120
	v_and_b32_e32 v53, 0xffff0000, v120
	v_lshlrev_b32_e32 v54, 16, v121
	v_and_b32_e32 v55, 0xffff0000, v121
	v_pk_fma_f32 v[46:47], v[46:47], v[88:89], v[50:51]
	v_pk_fma_f32 v[44:45], v[44:45], v[86:87], v[48:49]
	v_pk_fma_f32 v[48:49], v[42:43], v[84:85], v[54:55]
	v_pk_fma_f32 v[50:51], v[40:41], v[82:83], v[52:53]
	v_lshl_add_u64 v[52:53], s[12:13], 0, v[136:137]
	v_cvt_pk_bf16_f32 v40, v44, v45
	v_cvt_pk_bf16_f32 v41, v46, v47
	v_cvt_pk_bf16_f32 v42, v50, v51
	v_cvt_pk_bf16_f32 v43, v48, v49
	v_lshl_add_u64 v[52:53], v[52:53], 0, v[206:207]
	global_store_dwordx4 v[52:53], v[40:43], off
	s_nop 1
	v_mul_f32_e32 v40, v45, v45
	v_mul_f32_e32 v41, v47, v47
	v_fmac_f32_e32 v40, v44, v44
	v_fmac_f32_e32 v41, v46, v46
	v_add_f32_e32 v40, v40, v41
	v_mul_f32_e32 v41, v51, v51
	v_fmac_f32_e32 v41, v50, v50
	v_add_f32_e32 v40, v41, v40
	v_mul_f32_e32 v41, v49, v49
	v_fmac_f32_e32 v41, v48, v48
	v_add_f32_e32 v54, v41, v40
	v_pk_mul_f32 v[42:43], v[76:77], v[46:47]
	v_pk_mul_f32 v[40:41], v[74:75], v[44:45]
	v_pk_mul_f32 v[44:45], v[80:81], v[48:49]
	v_pk_mul_f32 v[46:47], v[78:79], v[50:51]
	v_cvt_pk_bf16_f32 v40, v40, v41
	v_cvt_pk_bf16_f32 v41, v42, v43
	v_cvt_pk_bf16_f32 v43, v44, v45
	v_lshl_add_u64 v[44:45], s[14:15], 0, v[136:137]
	v_cvt_pk_bf16_f32 v42, v46, v47
	v_lshl_add_u64 v[44:45], v[44:45], 0, v[206:207]
	global_store_dwordx4 v[44:45], v[40:43], off
	v_lshlrev_b32_e32 v46, 16, v116
	v_and_b32_e32 v47, 0xffff0000, v116
	v_lshlrev_b32_e32 v40, 16, v114
	v_and_b32_e32 v41, 0xffff0000, v114
	v_lshlrev_b32_e32 v42, 16, v115
	v_and_b32_e32 v43, 0xffff0000, v115
	v_lshlrev_b32_e32 v48, 16, v117
	v_and_b32_e32 v49, 0xffff0000, v117
	v_pk_fma_f32 v[38:39], v[38:39], v[72:73], v[42:43]
	v_pk_fma_f32 v[36:37], v[36:37], v[70:71], v[40:41]
	v_pk_fma_f32 v[40:41], v[34:35], v[68:69], v[48:49]
	v_pk_fma_f32 v[42:43], v[32:33], v[66:67], v[46:47]
	v_cvt_pk_bf16_f32 v32, v36, v37
	v_cvt_pk_bf16_f32 v33, v38, v39
	v_cvt_pk_bf16_f32 v34, v42, v43
	v_cvt_pk_bf16_f32 v35, v40, v41
	global_store_dwordx4 v[52:53], v[32:35], off offset:256
	s_nop 1
	v_mul_f32_e32 v32, v37, v37
	v_mul_f32_e32 v33, v39, v39
	v_fmac_f32_e32 v32, v36, v36
	v_fmac_f32_e32 v33, v38, v38
	v_add_f32_e32 v32, v32, v33
	v_mul_f32_e32 v33, v43, v43
	v_fmac_f32_e32 v33, v42, v42
	v_add_f32_e32 v32, v33, v32
	v_mul_f32_e32 v33, v41, v41
	v_fmac_f32_e32 v33, v40, v40
	v_add_f32_e32 v32, v33, v32
	v_add_f32_e32 v46, v54, v32
	v_pk_mul_f32 v[34:35], v[58:59], v[38:39]
	v_pk_mul_f32 v[32:33], v[56:57], v[36:37]
	v_pk_mul_f32 v[36:37], v[62:63], v[40:41]
	v_pk_mul_f32 v[38:39], v[60:61], v[42:43]
	v_cvt_pk_bf16_f32 v32, v32, v33
	v_cvt_pk_bf16_f32 v33, v34, v35
	v_cvt_pk_bf16_f32 v34, v38, v39
	v_cvt_pk_bf16_f32 v35, v36, v37
	global_store_dwordx4 v[44:45], v[32:35], off offset:256
	s_nop 1
	v_mov_b32_e32 v32, v46
	s_nop 1
	v_permlane16_swap_b32_e32 v46, v32
	v_add_f32_e32 v32, v46, v32
	v_mov_b32_e32 v33, v32
	s_nop 1
	v_permlane32_swap_b32_e32 v32, v33
	s_and_saveexec_b64 s[34:35], vcc
	s_cbranch_execz .LBB0_1899
	v_add_f32_e32 v34, v32, v33
	s_lshl_b32 s0, s91, 2
	v_lshlrev_b64 v[32:33], 6, v[134:135]
	s_ashr_i32 s1, s0, 31
	v_lshl_add_u64 v[32:33], s[16:17], 0, v[32:33]
	v_lshl_add_u64 v[32:33], s[0:1], 2, v[32:33]
	s_lshl_b32 s96, s85, 2
	v_lshl_add_u64 v[32:33], v[32:33], 0, s[96:97]
	global_store_dword v[32:33], v34, off
.LBB0_1899:
	s_or_b64 exec, exec, s[34:35]
	v_lshlrev_b32_e32 v32, 16, v110
	v_and_b32_e32 v33, 0xffff0000, v110
	v_lshlrev_b32_e32 v34, 16, v111
	v_and_b32_e32 v35, 0xffff0000, v111
	v_lshlrev_b32_e32 v36, 16, v112
	v_and_b32_e32 v37, 0xffff0000, v112
	v_lshlrev_b32_e32 v38, 16, v113
	v_and_b32_e32 v39, 0xffff0000, v113
	v_pk_fma_f32 v[30:31], v[30:31], v[88:89], v[34:35]
	v_pk_fma_f32 v[28:29], v[28:29], v[86:87], v[32:33]
	v_pk_fma_f32 v[32:33], v[26:27], v[84:85], v[38:39]
	v_pk_fma_f32 v[34:35], v[24:25], v[82:83], v[36:37]
	v_lshl_add_u64 v[36:37], s[12:13], 0, v[132:133]
	v_cvt_pk_bf16_f32 v24, v28, v29
	v_cvt_pk_bf16_f32 v25, v30, v31
	v_cvt_pk_bf16_f32 v26, v34, v35
	v_cvt_pk_bf16_f32 v27, v32, v33
	v_lshl_add_u64 v[36:37], v[36:37], 0, v[206:207]
	global_store_dwordx4 v[36:37], v[24:27], off
	s_nop 1
	v_mul_f32_e32 v24, v29, v29
	v_mul_f32_e32 v25, v31, v31
	v_fmac_f32_e32 v24, v28, v28
	v_fmac_f32_e32 v25, v30, v30
	v_add_f32_e32 v24, v24, v25
	v_mul_f32_e32 v25, v35, v35
	v_fmac_f32_e32 v25, v34, v34
	v_add_f32_e32 v24, v25, v24
	v_mul_f32_e32 v25, v33, v33
	v_fmac_f32_e32 v25, v32, v32
	v_add_f32_e32 v38, v25, v24
	v_pk_mul_f32 v[26:27], v[76:77], v[30:31]
	v_pk_mul_f32 v[24:25], v[74:75], v[28:29]
	v_pk_mul_f32 v[28:29], v[80:81], v[32:33]
	v_pk_mul_f32 v[30:31], v[78:79], v[34:35]
	v_cvt_pk_bf16_f32 v24, v24, v25
	v_cvt_pk_bf16_f32 v25, v26, v27
	v_cvt_pk_bf16_f32 v27, v28, v29
	v_lshl_add_u64 v[28:29], s[14:15], 0, v[132:133]
	v_cvt_pk_bf16_f32 v26, v30, v31
	v_lshl_add_u64 v[28:29], v[28:29], 0, v[206:207]
	global_store_dwordx4 v[28:29], v[24:27], off
	v_lshlrev_b32_e32 v30, 16, v108
	v_and_b32_e32 v31, 0xffff0000, v108
	v_lshlrev_b32_e32 v24, 16, v106
	v_and_b32_e32 v25, 0xffff0000, v106
	v_lshlrev_b32_e32 v26, 16, v107
	v_and_b32_e32 v27, 0xffff0000, v107
	v_lshlrev_b32_e32 v32, 16, v109
	v_and_b32_e32 v33, 0xffff0000, v109
	v_pk_fma_f32 v[22:23], v[22:23], v[72:73], v[26:27]
	v_pk_fma_f32 v[20:21], v[20:21], v[70:71], v[24:25]
	v_pk_fma_f32 v[24:25], v[18:19], v[68:69], v[32:33]
	v_pk_fma_f32 v[26:27], v[16:17], v[66:67], v[30:31]
	v_cvt_pk_bf16_f32 v16, v20, v21
	v_cvt_pk_bf16_f32 v17, v22, v23
	v_cvt_pk_bf16_f32 v18, v26, v27
	v_cvt_pk_bf16_f32 v19, v24, v25
	global_store_dwordx4 v[36:37], v[16:19], off offset:256
	s_nop 1
	v_mul_f32_e32 v16, v21, v21
	v_mul_f32_e32 v17, v23, v23
	v_fmac_f32_e32 v16, v20, v20
	v_fmac_f32_e32 v17, v22, v22
	v_add_f32_e32 v16, v16, v17
	v_mul_f32_e32 v17, v27, v27
	v_fmac_f32_e32 v17, v26, v26
	v_add_f32_e32 v16, v17, v16
	v_mul_f32_e32 v17, v25, v25
	v_fmac_f32_e32 v17, v24, v24
	v_add_f32_e32 v16, v17, v16
	v_add_f32_e32 v30, v38, v16
	v_pk_mul_f32 v[18:19], v[58:59], v[22:23]
	v_pk_mul_f32 v[16:17], v[56:57], v[20:21]
	v_pk_mul_f32 v[20:21], v[62:63], v[24:25]
	v_pk_mul_f32 v[22:23], v[60:61], v[26:27]
	v_cvt_pk_bf16_f32 v16, v16, v17
	v_cvt_pk_bf16_f32 v17, v18, v19
	v_cvt_pk_bf16_f32 v18, v22, v23
	v_cvt_pk_bf16_f32 v19, v20, v21
	global_store_dwordx4 v[28:29], v[16:19], off offset:256
	s_nop 1
	v_mov_b32_e32 v16, v30
	s_nop 1
	v_permlane16_swap_b32_e32 v30, v16
	v_add_f32_e32 v16, v30, v16
	v_mov_b32_e32 v17, v16
	s_nop 1
	v_permlane32_swap_b32_e32 v16, v17
	s_and_saveexec_b64 s[34:35], vcc
	s_cbranch_execz .LBB0_1901
	v_add_f32_e32 v18, v16, v17
	s_lshl_b32 s0, s91, 2
	v_lshlrev_b64 v[16:17], 6, v[130:131]
	s_ashr_i32 s1, s0, 31
	v_lshl_add_u64 v[16:17], s[16:17], 0, v[16:17]
	v_lshl_add_u64 v[16:17], s[0:1], 2, v[16:17]
	s_lshl_b32 s96, s85, 2
	v_lshl_add_u64 v[16:17], v[16:17], 0, s[96:97]
	global_store_dword v[16:17], v18, off
.LBB0_1901:
	s_or_b64 exec, exec, s[34:35]
	v_lshlrev_b32_e32 v16, 16, v102
	v_and_b32_e32 v17, 0xffff0000, v102
	v_lshlrev_b32_e32 v18, 16, v103
	v_and_b32_e32 v19, 0xffff0000, v103
	v_lshlrev_b32_e32 v20, 16, v104
	v_and_b32_e32 v21, 0xffff0000, v104
	v_lshlrev_b32_e32 v22, 16, v105
	v_and_b32_e32 v23, 0xffff0000, v105
	v_pk_fma_f32 v[14:15], v[14:15], v[88:89], v[18:19]
	v_pk_fma_f32 v[12:13], v[12:13], v[86:87], v[16:17]
	v_pk_fma_f32 v[16:17], v[10:11], v[84:85], v[22:23]
	v_pk_fma_f32 v[18:19], v[8:9], v[82:83], v[20:21]
	v_lshl_add_u64 v[20:21], s[12:13], 0, v[128:129]
	v_cvt_pk_bf16_f32 v8, v12, v13
	v_cvt_pk_bf16_f32 v9, v14, v15
	v_cvt_pk_bf16_f32 v10, v18, v19
	v_cvt_pk_bf16_f32 v11, v16, v17
	v_lshl_add_u64 v[20:21], v[20:21], 0, v[206:207]
	global_store_dwordx4 v[20:21], v[8:11], off
	s_nop 1
	v_mul_f32_e32 v8, v13, v13
	v_mul_f32_e32 v9, v15, v15
	v_fmac_f32_e32 v8, v12, v12
	v_fmac_f32_e32 v9, v14, v14
	v_add_f32_e32 v8, v8, v9
	v_mul_f32_e32 v9, v19, v19
	v_fmac_f32_e32 v9, v18, v18
	v_add_f32_e32 v8, v9, v8
	v_mul_f32_e32 v9, v17, v17
	v_fmac_f32_e32 v9, v16, v16
	v_add_f32_e32 v22, v9, v8
	v_pk_mul_f32 v[10:11], v[76:77], v[14:15]
	v_pk_mul_f32 v[8:9], v[74:75], v[12:13]
	v_pk_mul_f32 v[12:13], v[80:81], v[16:17]
	v_pk_mul_f32 v[14:15], v[78:79], v[18:19]
	v_cvt_pk_bf16_f32 v8, v8, v9
	v_cvt_pk_bf16_f32 v9, v10, v11
	v_cvt_pk_bf16_f32 v11, v12, v13
	v_lshl_add_u64 v[12:13], s[14:15], 0, v[128:129]
	v_cvt_pk_bf16_f32 v10, v14, v15
	v_lshl_add_u64 v[12:13], v[12:13], 0, v[206:207]
	global_store_dwordx4 v[12:13], v[8:11], off
	v_lshlrev_b32_e32 v14, 16, v100
	v_and_b32_e32 v15, 0xffff0000, v100
	v_lshlrev_b32_e32 v8, 16, v98
	v_and_b32_e32 v9, 0xffff0000, v98
	v_lshlrev_b32_e32 v10, 16, v99
	v_and_b32_e32 v11, 0xffff0000, v99
	v_lshlrev_b32_e32 v16, 16, v101
	v_and_b32_e32 v17, 0xffff0000, v101
	v_pk_fma_f32 v[6:7], v[6:7], v[72:73], v[10:11]
	v_pk_fma_f32 v[4:5], v[4:5], v[70:71], v[8:9]
	v_pk_fma_f32 v[8:9], v[2:3], v[68:69], v[16:17]
	v_pk_fma_f32 v[10:11], v[0:1], v[66:67], v[14:15]
	v_cvt_pk_bf16_f32 v0, v4, v5
	v_cvt_pk_bf16_f32 v1, v6, v7
	v_cvt_pk_bf16_f32 v2, v10, v11
	v_cvt_pk_bf16_f32 v3, v8, v9
	global_store_dwordx4 v[20:21], v[0:3], off offset:256
	s_nop 1
	v_mul_f32_e32 v0, v5, v5
	v_mul_f32_e32 v1, v7, v7
	v_fmac_f32_e32 v0, v4, v4
	v_fmac_f32_e32 v1, v6, v6
	v_add_f32_e32 v0, v0, v1
	v_mul_f32_e32 v1, v11, v11
	v_fmac_f32_e32 v1, v10, v10
	v_add_f32_e32 v0, v1, v0
	v_mul_f32_e32 v1, v9, v9
	v_fmac_f32_e32 v1, v8, v8
	v_add_f32_e32 v0, v1, v0
	v_add_f32_e32 v14, v22, v0
	v_pk_mul_f32 v[2:3], v[58:59], v[6:7]
	v_pk_mul_f32 v[0:1], v[56:57], v[4:5]
	v_pk_mul_f32 v[4:5], v[62:63], v[8:9]
	v_pk_mul_f32 v[6:7], v[60:61], v[10:11]
	v_cvt_pk_bf16_f32 v0, v0, v1
	v_cvt_pk_bf16_f32 v1, v2, v3
	v_cvt_pk_bf16_f32 v2, v6, v7
	v_cvt_pk_bf16_f32 v3, v4, v5
	global_store_dwordx4 v[12:13], v[0:3], off offset:256
	s_nop 1
	v_mov_b32_e32 v0, v14
	s_nop 1
	v_permlane16_swap_b32_e32 v14, v0
	v_add_f32_e32 v0, v14, v0
	v_mov_b32_e32 v1, v0
	s_nop 1
	v_permlane32_swap_b32_e32 v0, v1
	s_and_saveexec_b64 s[34:35], vcc
	s_cbranch_execz .LBB0_1903
	v_add_f32_e32 v2, v0, v1
	s_lshl_b32 s0, s91, 2
	v_lshlrev_b64 v[0:1], 6, v[126:127]
	s_ashr_i32 s1, s0, 31
	v_lshl_add_u64 v[0:1], s[16:17], 0, v[0:1]
	v_lshl_add_u64 v[0:1], s[0:1], 2, v[0:1]
	s_lshl_b32 s96, s85, 2
	v_lshl_add_u64 v[0:1], v[0:1], 0, s[96:97]
	global_store_dword v[0:1], v2, off

.LBB0_2128:
	s_lshl_b32 s0, s8, 8
	s_add_i32 s13, s0, s90
	s_lshl_b32 s0, s9, 8
	v_mov_b32_e32 v156, v160
	v_mov_b32_e32 v157, v161
	s_or_b32 s0, s0, s91
	s_mov_b64 s[34:35], -1
	v_lshl_add_u32 v168, v157, 3, s0
	s_lshl_b32 s0, s8, 10
	s_and_b32 s0, s0, 0xfffff000
	s_addk_i32 s0, 0xd000
	s_cmp_gt_i32 s8, 15
	s_cselect_b32 s96, s0, 0
	v_add_u32_e32 v158, s13, v156
	s_lshl_b64 s[0:1], s[96:97], 2
	v_lshlrev_b32_e32 v156, 2, v157
	v_ashrrev_i32_e32 v159, 31, v158
	s_add_u32 s0, s88, s0
	v_ashrrev_i32_e32 v157, 31, v156
	v_lshlrev_b64 v[164:165], 6, v[158:159]
	s_addc_u32 s1, s89, s1
	v_ashrrev_i32_e32 v169, 31, v168
	v_lshl_add_u64 v[164:165], s[22:23], 0, v[164:165]
	v_lshlrev_b64 v[156:157], 2, v[156:157]
	v_lshl_add_u64 v[32:33], v[168:169], 2, s[0:1]
	v_lshl_add_u64 v[164:165], v[164:165], 0, v[156:157]
	global_load_dwordx4 v[44:47], v[32:33], off
	global_load_dwordx4 v[40:43], v[32:33], off offset:16
	global_load_dwordx4 v[36:39], v[32:33], off offset:512
	s_nop 0
	global_load_dwordx4 v[32:35], v[32:33], off offset:528
	s_nop 0
	global_load_dwordx4 v[164:167], v[164:165], off
	v_add_u32_e32 v172, 16, v158
	v_ashrrev_i32_e32 v173, 31, v172
	v_lshlrev_b64 v[172:173], 6, v[172:173]
	v_lshl_add_u64 v[172:173], s[22:23], 0, v[172:173]
	v_lshl_add_u64 v[172:173], v[172:173], 0, v[156:157]
	global_load_dwordx4 v[172:175], v[172:173], off
	v_add_u32_e32 v176, 32, v158
	v_ashrrev_i32_e32 v177, 31, v176
	v_lshlrev_b64 v[176:177], 6, v[176:177]
	v_lshl_add_u64 v[176:177], s[22:23], 0, v[176:177]
	v_lshl_add_u64 v[176:177], v[176:177], 0, v[156:157]
	global_load_dwordx4 v[176:179], v[176:177], off
	v_add_u32_e32 v184, 48, v158
	v_ashrrev_i32_e32 v185, 31, v184
	v_lshlrev_b64 v[184:185], 6, v[184:185]
	v_lshl_add_u64 v[184:185], s[22:23], 0, v[184:185]
	v_lshl_add_u64 v[184:185], v[184:185], 0, v[156:157]
	global_load_dwordx4 v[184:187], v[184:185], off
	v_add_u32_e32 v196, 0x80, v158
	v_ashrrev_i32_e32 v197, 31, v196
	v_lshlrev_b64 v[196:197], 6, v[196:197]
	v_lshl_add_u64 v[196:197], s[22:23], 0, v[196:197]
	v_lshl_add_u64 v[196:197], v[196:197], 0, v[156:157]
	global_load_dwordx4 v[196:199], v[196:197], off
	v_add_u32_e32 v200, 0x90, v158
	v_ashrrev_i32_e32 v201, 31, v200
	v_lshlrev_b64 v[200:201], 6, v[200:201]
	v_lshl_add_u64 v[200:201], s[22:23], 0, v[200:201]
	v_lshl_add_u64 v[200:201], v[200:201], 0, v[156:157]
	global_load_dwordx4 v[200:203], v[200:201], off
	v_add_u32_e32 v204, 0xa0, v158
	v_ashrrev_i32_e32 v205, 31, v204
	v_lshlrev_b64 v[204:205], 6, v[204:205]
	v_lshl_add_u64 v[204:205], s[22:23], 0, v[204:205]
	v_lshl_add_u64 v[204:205], v[204:205], 0, v[156:157]
	global_load_dwordx4 v[204:207], v[204:205], off
	v_add_u32_e32 v216, 0xb0, v158
	v_ashrrev_i32_e32 v217, 31, v216
	v_lshlrev_b64 v[216:217], 6, v[216:217]
	v_lshl_add_u64 v[216:217], s[22:23], 0, v[216:217]
	v_lshl_add_u64 v[216:217], v[216:217], 0, v[156:157]
	global_load_dwordx4 v[216:219], v[216:217], off
	s_waitcnt vmcnt(0) lgkmcnt(0)
	v_add_f32_e32 v164, v164, v165
	v_add_f32_e32 v165, v166, v167
	v_add_f32_e32 v164, v164, v165
	v_mov_b32_e32 v165, v164
	s_nop 1
	v_permlane16_swap_b32_e32 v164, v165
	v_add_f32_e32 v164, v164, v165
	v_mov_b32_e32 v165, v164
	s_nop 1
	v_permlane32_swap_b32_e32 v164, v165
	v_add_f32_e32 v164, v164, v165
	v_fmamk_f32 v164, v164, 0x3a800000, v229
	v_cmp_gt_f32_e32 vcc, s55, v164
	v_mul_f32_e32 v165, 0x4b800000, v164
	v_lshlrev_b64 v[166:167], 13, v[158:159]
	v_cndmask_b32_e32 v164, v164, v165, vcc
	v_rsq_f32_e32 v164, v164
	s_nop 0
	v_mul_f32_e32 v165, 0x45800000, v164
	v_cndmask_b32_e32 v164, v164, v165, vcc
	v_pk_fma_f32 v[144:145], v[144:145], v[164:165], v[46:47] op_sel_hi:[1,0,1]
	v_pk_fma_f32 v[142:143], v[142:143], v[164:165], v[44:45] op_sel_hi:[1,0,1]
	v_pk_fma_f32 v[138:139], v[138:139], v[164:165], v[40:41] op_sel_hi:[1,0,1]
	v_pk_fma_f32 v[140:141], v[140:141], v[164:165], v[42:43] op_sel_hi:[1,0,1]
	v_max_f32_e32 v142, 0, v142
	v_max_f32_e32 v138, 0, v138
	v_max_f32_e32 v143, 0, v143
	v_max_f32_e32 v139, 0, v139
	v_max_f32_e32 v144, 0, v144
	v_max_f32_e32 v145, 0, v145
	v_pk_mul_f32 v[142:143], v[142:143], v[142:143]
	v_pk_mul_f32 v[138:139], v[138:139], v[138:139]
	v_max_f32_e32 v140, 0, v140
	v_max_f32_e32 v141, 0, v141
	v_pk_mul_f32 v[144:145], v[144:145], v[144:145]
	v_pk_mul_f32 v[170:171], v[140:141], v[140:141]
	v_cvt_pk_bf16_f32 v140, v142, v143
	v_cvt_pk_bf16_f32 v141, v144, v145
	v_cvt_pk_bf16_f32 v142, v138, v139
	v_lshl_add_u64 v[144:145], s[20:21], 0, v[166:167]
	v_lshlrev_b64 v[138:139], 1, v[168:169]
	v_pk_fma_f32 v[130:131], v[130:131], v[164:165], v[32:33] op_sel_hi:[1,0,1]
	v_cvt_pk_bf16_f32 v143, v170, v171
	v_lshl_add_u64 v[144:145], v[144:145], 0, v[138:139]
	v_pk_fma_f32 v[136:137], v[136:137], v[164:165], v[38:39] op_sel_hi:[1,0,1]
	v_pk_fma_f32 v[134:135], v[134:135], v[164:165], v[36:37] op_sel_hi:[1,0,1]
	v_pk_fma_f32 v[132:133], v[132:133], v[164:165], v[34:35] op_sel_hi:[1,0,1]
	v_max_f32_e32 v130, 0, v130
	v_max_f32_e32 v131, 0, v131
	global_store_dwordx4 v[144:145], v[140:143], off
	v_max_f32_e32 v134, 0, v134
	v_max_f32_e32 v135, 0, v135
	v_pk_mul_f32 v[140:141], v[130:131], v[130:131]
	v_max_f32_e32 v130, 0, v136
	v_max_f32_e32 v132, 0, v132
	v_max_f32_e32 v131, 0, v137
	v_max_f32_e32 v133, 0, v133
	v_pk_mul_f32 v[134:135], v[134:135], v[134:135]
	v_pk_mul_f32 v[136:137], v[130:131], v[130:131]
	v_pk_mul_f32 v[142:143], v[132:133], v[132:133]
	v_cvt_pk_bf16_f32 v130, v134, v135
	v_cvt_pk_bf16_f32 v131, v136, v137
	v_cvt_pk_bf16_f32 v132, v140, v141
	v_cvt_pk_bf16_f32 v133, v142, v143
	global_store_dwordx4 v[144:145], v[130:133], off offset:256
	s_nop 1
	v_add_u32_e32 v130, 16, v158
	v_ashrrev_i32_e32 v131, 31, v130
	v_lshlrev_b64 v[130:131], 13, v[130:131]
	v_add_f32_e32 v132, v172, v173
	v_add_f32_e32 v133, v174, v175
	v_add_f32_e32 v132, v132, v133
	v_mov_b32_e32 v133, v132
	s_nop 1
	v_permlane16_swap_b32_e32 v132, v133
	v_add_f32_e32 v132, v132, v133
	v_mov_b32_e32 v133, v132
	s_nop 1
	v_permlane32_swap_b32_e32 v132, v133
	v_add_f32_e32 v132, v132, v133
	v_fmamk_f32 v132, v132, 0x3a800000, v229
	v_cmp_gt_f32_e32 vcc, s55, v132
	v_mul_f32_e32 v133, 0x4b800000, v132
	s_nop 0
	v_cndmask_b32_e32 v132, v132, v133, vcc
	v_rsq_f32_e32 v132, v132
	s_nop 0
	v_mul_f32_e32 v133, 0x45800000, v132
	v_cndmask_b32_e32 v132, v132, v133, vcc
	v_pk_fma_f32 v[126:127], v[126:127], v[132:133], v[44:45] op_sel_hi:[1,0,1]
	v_pk_fma_f32 v[122:123], v[122:123], v[132:133], v[40:41] op_sel_hi:[1,0,1]
	v_pk_fma_f32 v[128:129], v[128:129], v[132:133], v[46:47] op_sel_hi:[1,0,1]
	v_pk_fma_f32 v[124:125], v[124:125], v[132:133], v[42:43] op_sel_hi:[1,0,1]
	v_max_f32_e32 v126, 0, v126
	v_max_f32_e32 v122, 0, v122
	v_max_f32_e32 v127, 0, v127
	v_max_f32_e32 v123, 0, v123
	v_pk_mul_f32 v[126:127], v[126:127], v[126:127]
	v_pk_mul_f32 v[134:135], v[122:123], v[122:123]
	v_max_f32_e32 v122, 0, v128
	v_max_f32_e32 v124, 0, v124
	v_max_f32_e32 v123, 0, v129
	v_max_f32_e32 v125, 0, v125
	v_pk_mul_f32 v[128:129], v[122:123], v[122:123]
	v_pk_mul_f32 v[136:137], v[124:125], v[124:125]
	v_cvt_pk_bf16_f32 v122, v126, v127
	v_lshl_add_u64 v[126:127], s[20:21], 0, v[130:131]
	v_pk_fma_f32 v[114:115], v[114:115], v[132:133], v[32:33] op_sel_hi:[1,0,1]
	v_cvt_pk_bf16_f32 v123, v128, v129
	v_cvt_pk_bf16_f32 v124, v134, v135
	v_cvt_pk_bf16_f32 v125, v136, v137
	v_lshl_add_u64 v[126:127], v[126:127], 0, v[138:139]
	v_pk_fma_f32 v[120:121], v[120:121], v[132:133], v[38:39] op_sel_hi:[1,0,1]
	v_pk_fma_f32 v[118:119], v[118:119], v[132:133], v[36:37] op_sel_hi:[1,0,1]
	v_pk_fma_f32 v[116:117], v[116:117], v[132:133], v[34:35] op_sel_hi:[1,0,1]
	v_max_f32_e32 v114, 0, v114
	v_max_f32_e32 v115, 0, v115
	global_store_dwordx4 v[126:127], v[122:125], off
	v_max_f32_e32 v118, 0, v118
	v_max_f32_e32 v119, 0, v119
	v_pk_mul_f32 v[122:123], v[114:115], v[114:115]
	v_max_f32_e32 v114, 0, v120
	v_max_f32_e32 v116, 0, v116
	v_max_f32_e32 v115, 0, v121
	v_max_f32_e32 v117, 0, v117
	v_pk_mul_f32 v[118:119], v[118:119], v[118:119]
	v_pk_mul_f32 v[120:121], v[114:115], v[114:115]
	v_pk_mul_f32 v[124:125], v[116:117], v[116:117]
	v_cvt_pk_bf16_f32 v114, v118, v119
	v_cvt_pk_bf16_f32 v115, v120, v121
	v_cvt_pk_bf16_f32 v116, v122, v123
	v_cvt_pk_bf16_f32 v117, v124, v125
	global_store_dwordx4 v[126:127], v[114:117], off offset:256
	s_nop 1
	v_add_u32_e32 v114, 32, v158
	v_ashrrev_i32_e32 v115, 31, v114
	v_lshlrev_b64 v[114:115], 13, v[114:115]
	v_add_f32_e32 v116, v176, v177
	v_add_f32_e32 v117, v178, v179
	v_add_f32_e32 v116, v116, v117
	v_mov_b32_e32 v117, v116
	s_nop 1
	v_permlane16_swap_b32_e32 v116, v117
	v_add_f32_e32 v116, v116, v117
	v_mov_b32_e32 v117, v116
	s_nop 1
	v_permlane32_swap_b32_e32 v116, v117
	v_add_f32_e32 v116, v116, v117
	v_fmamk_f32 v116, v116, 0x3a800000, v229
	v_cmp_gt_f32_e32 vcc, s55, v116
	v_mul_f32_e32 v117, 0x4b800000, v116
	s_nop 0
	v_cndmask_b32_e32 v116, v116, v117, vcc
	v_rsq_f32_e32 v116, v116
	s_nop 0
	v_mul_f32_e32 v117, 0x45800000, v116
	v_cndmask_b32_e32 v116, v116, v117, vcc
	v_pk_fma_f32 v[110:111], v[110:111], v[116:117], v[44:45] op_sel_hi:[1,0,1]
	v_pk_fma_f32 v[106:107], v[106:107], v[116:117], v[40:41] op_sel_hi:[1,0,1]
	v_pk_fma_f32 v[112:113], v[112:113], v[116:117], v[46:47] op_sel_hi:[1,0,1]
	v_pk_fma_f32 v[108:109], v[108:109], v[116:117], v[42:43] op_sel_hi:[1,0,1]
	v_max_f32_e32 v110, 0, v110
	v_max_f32_e32 v106, 0, v106
	v_max_f32_e32 v111, 0, v111
	v_max_f32_e32 v107, 0, v107
	v_pk_mul_f32 v[110:111], v[110:111], v[110:111]
	v_pk_mul_f32 v[118:119], v[106:107], v[106:107]
	v_max_f32_e32 v106, 0, v112
	v_max_f32_e32 v108, 0, v108
	v_max_f32_e32 v107, 0, v113
	v_max_f32_e32 v109, 0, v109
	v_pk_mul_f32 v[112:113], v[106:107], v[106:107]
	v_pk_mul_f32 v[120:121], v[108:109], v[108:109]
	v_cvt_pk_bf16_f32 v106, v110, v111
	v_lshl_add_u64 v[110:111], s[20:21], 0, v[114:115]
	v_pk_fma_f32 v[98:99], v[98:99], v[116:117], v[32:33] op_sel_hi:[1,0,1]
	v_cvt_pk_bf16_f32 v107, v112, v113
	v_cvt_pk_bf16_f32 v108, v118, v119
	v_cvt_pk_bf16_f32 v109, v120, v121
	v_lshl_add_u64 v[110:111], v[110:111], 0, v[138:139]
	v_pk_fma_f32 v[104:105], v[104:105], v[116:117], v[38:39] op_sel_hi:[1,0,1]
	v_pk_fma_f32 v[102:103], v[102:103], v[116:117], v[36:37] op_sel_hi:[1,0,1]
	v_pk_fma_f32 v[100:101], v[100:101], v[116:117], v[34:35] op_sel_hi:[1,0,1]
	v_max_f32_e32 v98, 0, v98
	v_max_f32_e32 v99, 0, v99
	global_store_dwordx4 v[110:111], v[106:109], off
	v_max_f32_e32 v102, 0, v102
	v_max_f32_e32 v103, 0, v103
	v_pk_mul_f32 v[106:107], v[98:99], v[98:99]
	v_max_f32_e32 v98, 0, v104
	v_max_f32_e32 v100, 0, v100
	v_max_f32_e32 v99, 0, v105
	v_max_f32_e32 v101, 0, v101
	v_pk_mul_f32 v[102:103], v[102:103], v[102:103]
	v_pk_mul_f32 v[104:105], v[98:99], v[98:99]
	v_pk_mul_f32 v[108:109], v[100:101], v[100:101]
	v_cvt_pk_bf16_f32 v98, v102, v103
	v_cvt_pk_bf16_f32 v99, v104, v105
	v_cvt_pk_bf16_f32 v100, v106, v107
	v_cvt_pk_bf16_f32 v101, v108, v109
	global_store_dwordx4 v[110:111], v[98:101], off offset:256
	s_nop 1
	v_add_u32_e32 v98, 48, v158
	v_ashrrev_i32_e32 v99, 31, v98
	v_lshlrev_b64 v[98:99], 13, v[98:99]
	v_add_f32_e32 v100, v184, v185
	v_add_f32_e32 v101, v186, v187
	v_add_f32_e32 v100, v100, v101
	v_mov_b32_e32 v101, v100
	s_nop 1
	v_permlane16_swap_b32_e32 v100, v101
	v_add_f32_e32 v100, v100, v101
	v_mov_b32_e32 v101, v100
	s_nop 1
	v_permlane32_swap_b32_e32 v100, v101
	v_add_f32_e32 v100, v100, v101
	v_fmamk_f32 v100, v100, 0x3a800000, v229
	v_cmp_gt_f32_e32 vcc, s55, v100
	v_mul_f32_e32 v101, 0x4b800000, v100
	s_nop 0
	v_cndmask_b32_e32 v100, v100, v101, vcc
	v_rsq_f32_e32 v100, v100
	s_nop 0
	v_mul_f32_e32 v101, 0x45800000, v100
	v_cndmask_b32_e32 v100, v100, v101, vcc
	v_pk_fma_f32 v[94:95], v[94:95], v[100:101], v[44:45] op_sel_hi:[1,0,1]
	v_pk_fma_f32 v[90:91], v[90:91], v[100:101], v[40:41] op_sel_hi:[1,0,1]
	v_pk_fma_f32 v[96:97], v[96:97], v[100:101], v[46:47] op_sel_hi:[1,0,1]
	v_pk_fma_f32 v[92:93], v[92:93], v[100:101], v[42:43] op_sel_hi:[1,0,1]
	v_max_f32_e32 v94, 0, v94
	v_max_f32_e32 v90, 0, v90
	v_max_f32_e32 v95, 0, v95
	v_max_f32_e32 v91, 0, v91
	v_pk_mul_f32 v[94:95], v[94:95], v[94:95]
	v_pk_mul_f32 v[102:103], v[90:91], v[90:91]
	v_max_f32_e32 v90, 0, v96
	v_max_f32_e32 v92, 0, v92
	v_max_f32_e32 v91, 0, v97
	v_max_f32_e32 v93, 0, v93
	v_pk_mul_f32 v[96:97], v[90:91], v[90:91]
	v_pk_mul_f32 v[104:105], v[92:93], v[92:93]
	v_cvt_pk_bf16_f32 v90, v94, v95
	v_lshl_add_u64 v[94:95], s[20:21], 0, v[98:99]
	v_pk_fma_f32 v[82:83], v[82:83], v[100:101], v[32:33] op_sel_hi:[1,0,1]
	v_cvt_pk_bf16_f32 v91, v96, v97
	v_cvt_pk_bf16_f32 v92, v102, v103
	v_cvt_pk_bf16_f32 v93, v104, v105
	v_lshl_add_u64 v[94:95], v[94:95], 0, v[138:139]
	v_pk_fma_f32 v[88:89], v[88:89], v[100:101], v[38:39] op_sel_hi:[1,0,1]
	v_pk_fma_f32 v[86:87], v[86:87], v[100:101], v[36:37] op_sel_hi:[1,0,1]
	v_pk_fma_f32 v[84:85], v[84:85], v[100:101], v[34:35] op_sel_hi:[1,0,1]
	v_max_f32_e32 v82, 0, v82
	v_max_f32_e32 v83, 0, v83
	global_store_dwordx4 v[94:95], v[90:93], off
	v_max_f32_e32 v86, 0, v86
	v_max_f32_e32 v87, 0, v87
	v_pk_mul_f32 v[90:91], v[82:83], v[82:83]
	v_max_f32_e32 v82, 0, v88
	v_max_f32_e32 v84, 0, v84
	v_max_f32_e32 v83, 0, v89
	v_max_f32_e32 v85, 0, v85
	v_pk_mul_f32 v[86:87], v[86:87], v[86:87]
	v_pk_mul_f32 v[88:89], v[82:83], v[82:83]
	v_pk_mul_f32 v[92:93], v[84:85], v[84:85]
	v_cvt_pk_bf16_f32 v82, v86, v87
	v_cvt_pk_bf16_f32 v83, v88, v89
	v_cvt_pk_bf16_f32 v84, v90, v91
	v_cvt_pk_bf16_f32 v85, v92, v93
	global_store_dwordx4 v[94:95], v[82:85], off offset:256
	s_nop 1
	v_add_u32_e32 v82, 0x80, v158
	v_ashrrev_i32_e32 v83, 31, v82
	v_lshlrev_b64 v[82:83], 13, v[82:83]
	v_add_f32_e32 v84, v196, v197
	v_add_f32_e32 v85, v198, v199
	v_add_f32_e32 v84, v84, v85
	v_mov_b32_e32 v85, v84
	s_nop 1
	v_permlane16_swap_b32_e32 v84, v85
	v_add_f32_e32 v84, v84, v85
	v_mov_b32_e32 v85, v84
	s_nop 1
	v_permlane32_swap_b32_e32 v84, v85
	v_add_f32_e32 v84, v84, v85
	v_fmamk_f32 v84, v84, 0x3a800000, v229
	v_cmp_gt_f32_e32 vcc, s55, v84
	v_mul_f32_e32 v85, 0x4b800000, v84
	s_nop 0
	v_cndmask_b32_e32 v84, v84, v85, vcc
	v_rsq_f32_e32 v84, v84
	s_nop 0
	v_mul_f32_e32 v85, 0x45800000, v84
	v_cndmask_b32_e32 v84, v84, v85, vcc
	v_pk_fma_f32 v[78:79], v[78:79], v[84:85], v[44:45] op_sel_hi:[1,0,1]
	v_pk_fma_f32 v[74:75], v[74:75], v[84:85], v[40:41] op_sel_hi:[1,0,1]
	v_pk_fma_f32 v[80:81], v[80:81], v[84:85], v[46:47] op_sel_hi:[1,0,1]
	v_pk_fma_f32 v[76:77], v[76:77], v[84:85], v[42:43] op_sel_hi:[1,0,1]
	v_max_f32_e32 v78, 0, v78
	v_max_f32_e32 v74, 0, v74
	v_max_f32_e32 v79, 0, v79
	v_max_f32_e32 v75, 0, v75
	v_pk_mul_f32 v[78:79], v[78:79], v[78:79]
	v_pk_mul_f32 v[86:87], v[74:75], v[74:75]
	v_max_f32_e32 v74, 0, v80
	v_max_f32_e32 v76, 0, v76
	v_max_f32_e32 v75, 0, v81
	v_max_f32_e32 v77, 0, v77
	v_pk_mul_f32 v[80:81], v[74:75], v[74:75]
	v_pk_mul_f32 v[88:89], v[76:77], v[76:77]
	v_cvt_pk_bf16_f32 v74, v78, v79
	v_lshl_add_u64 v[78:79], s[20:21], 0, v[82:83]
	v_pk_fma_f32 v[66:67], v[66:67], v[84:85], v[32:33] op_sel_hi:[1,0,1]
	v_cvt_pk_bf16_f32 v75, v80, v81
	v_cvt_pk_bf16_f32 v76, v86, v87
	v_cvt_pk_bf16_f32 v77, v88, v89
	v_lshl_add_u64 v[78:79], v[78:79], 0, v[138:139]
	v_pk_fma_f32 v[72:73], v[72:73], v[84:85], v[38:39] op_sel_hi:[1,0,1]
	v_pk_fma_f32 v[70:71], v[70:71], v[84:85], v[36:37] op_sel_hi:[1,0,1]
	v_pk_fma_f32 v[68:69], v[68:69], v[84:85], v[34:35] op_sel_hi:[1,0,1]
	v_max_f32_e32 v66, 0, v66
	v_max_f32_e32 v67, 0, v67
	global_store_dwordx4 v[78:79], v[74:77], off
	v_max_f32_e32 v70, 0, v70
	v_max_f32_e32 v71, 0, v71
	v_pk_mul_f32 v[74:75], v[66:67], v[66:67]
	v_max_f32_e32 v66, 0, v72
	v_max_f32_e32 v68, 0, v68
	v_max_f32_e32 v67, 0, v73
	v_max_f32_e32 v69, 0, v69
	v_pk_mul_f32 v[70:71], v[70:71], v[70:71]
	v_pk_mul_f32 v[72:73], v[66:67], v[66:67]
	v_pk_mul_f32 v[76:77], v[68:69], v[68:69]
	v_cvt_pk_bf16_f32 v66, v70, v71
	v_cvt_pk_bf16_f32 v67, v72, v73
	v_cvt_pk_bf16_f32 v68, v74, v75
	v_cvt_pk_bf16_f32 v69, v76, v77
	global_store_dwordx4 v[78:79], v[66:69], off offset:256
	s_nop 1
	v_add_u32_e32 v66, 0x90, v158
	v_ashrrev_i32_e32 v67, 31, v66
	v_lshlrev_b64 v[66:67], 13, v[66:67]
	v_add_f32_e32 v68, v200, v201
	v_add_f32_e32 v69, v202, v203
	v_add_f32_e32 v68, v68, v69
	v_mov_b32_e32 v69, v68
	s_nop 1
	v_permlane16_swap_b32_e32 v68, v69
	v_add_f32_e32 v68, v68, v69
	v_mov_b32_e32 v69, v68
	s_nop 1
	v_permlane32_swap_b32_e32 v68, v69
	v_add_f32_e32 v68, v68, v69
	v_fmamk_f32 v68, v68, 0x3a800000, v229
	v_cmp_gt_f32_e32 vcc, s55, v68
	v_mul_f32_e32 v69, 0x4b800000, v68
	s_nop 0
	v_cndmask_b32_e32 v68, v68, v69, vcc
	v_rsq_f32_e32 v68, v68
	s_nop 0
	v_mul_f32_e32 v69, 0x45800000, v68
	v_cndmask_b32_e32 v68, v68, v69, vcc
	v_pk_fma_f32 v[60:61], v[60:61], v[68:69], v[44:45] op_sel_hi:[1,0,1]
	v_pk_fma_f32 v[56:57], v[56:57], v[68:69], v[40:41] op_sel_hi:[1,0,1]
	v_pk_fma_f32 v[62:63], v[62:63], v[68:69], v[46:47] op_sel_hi:[1,0,1]
	v_pk_fma_f32 v[58:59], v[58:59], v[68:69], v[42:43] op_sel_hi:[1,0,1]
	v_max_f32_e32 v60, 0, v60
	v_max_f32_e32 v56, 0, v56
	v_max_f32_e32 v61, 0, v61
	v_max_f32_e32 v57, 0, v57
	v_pk_mul_f32 v[60:61], v[60:61], v[60:61]
	v_pk_mul_f32 v[70:71], v[56:57], v[56:57]
	v_max_f32_e32 v56, 0, v62
	v_max_f32_e32 v58, 0, v58
	v_max_f32_e32 v57, 0, v63
	v_max_f32_e32 v59, 0, v59
	v_pk_mul_f32 v[62:63], v[56:57], v[56:57]
	v_pk_mul_f32 v[72:73], v[58:59], v[58:59]
	v_cvt_pk_bf16_f32 v56, v60, v61
	v_lshl_add_u64 v[60:61], s[20:21], 0, v[66:67]
	v_pk_fma_f32 v[48:49], v[48:49], v[68:69], v[32:33] op_sel_hi:[1,0,1]
	v_cvt_pk_bf16_f32 v57, v62, v63
	v_cvt_pk_bf16_f32 v58, v70, v71
	v_cvt_pk_bf16_f32 v59, v72, v73
	v_lshl_add_u64 v[60:61], v[60:61], 0, v[138:139]
	v_pk_fma_f32 v[54:55], v[54:55], v[68:69], v[38:39] op_sel_hi:[1,0,1]
	v_pk_fma_f32 v[52:53], v[52:53], v[68:69], v[36:37] op_sel_hi:[1,0,1]
	v_pk_fma_f32 v[50:51], v[50:51], v[68:69], v[34:35] op_sel_hi:[1,0,1]
	v_max_f32_e32 v48, 0, v48
	v_max_f32_e32 v49, 0, v49
	global_store_dwordx4 v[60:61], v[56:59], off
	v_max_f32_e32 v52, 0, v52
	v_max_f32_e32 v53, 0, v53
	v_pk_mul_f32 v[56:57], v[48:49], v[48:49]
	v_max_f32_e32 v48, 0, v54
	v_max_f32_e32 v50, 0, v50
	v_max_f32_e32 v49, 0, v55
	v_max_f32_e32 v51, 0, v51
	v_pk_mul_f32 v[52:53], v[52:53], v[52:53]
	v_pk_mul_f32 v[54:55], v[48:49], v[48:49]
	v_pk_mul_f32 v[58:59], v[50:51], v[50:51]
	v_cvt_pk_bf16_f32 v48, v52, v53
	v_cvt_pk_bf16_f32 v49, v54, v55
	v_cvt_pk_bf16_f32 v50, v56, v57
	v_cvt_pk_bf16_f32 v51, v58, v59
	global_store_dwordx4 v[60:61], v[48:51], off offset:256
	s_nop 1
	v_add_u32_e32 v48, 0xa0, v158
	v_ashrrev_i32_e32 v49, 31, v48
	v_lshlrev_b64 v[48:49], 13, v[48:49]
	v_add_f32_e32 v50, v204, v205
	v_add_f32_e32 v51, v206, v207
	v_add_f32_e32 v50, v50, v51
	v_mov_b32_e32 v51, v50
	s_nop 1
	v_permlane16_swap_b32_e32 v50, v51
	v_add_f32_e32 v50, v50, v51
	v_mov_b32_e32 v51, v50
	s_nop 1
	v_permlane32_swap_b32_e32 v50, v51
	v_add_f32_e32 v50, v50, v51
	v_fmamk_f32 v50, v50, 0x3a800000, v229
	v_cmp_gt_f32_e32 vcc, s55, v50
	v_mul_f32_e32 v51, 0x4b800000, v50
	s_nop 0
	v_cndmask_b32_e32 v50, v50, v51, vcc
	v_rsq_f32_e32 v50, v50
	s_nop 0
	v_mul_f32_e32 v51, 0x45800000, v50
	v_cndmask_b32_e32 v50, v50, v51, vcc
	v_pk_fma_f32 v[28:29], v[28:29], v[50:51], v[44:45] op_sel_hi:[1,0,1]
	v_pk_fma_f32 v[24:25], v[24:25], v[50:51], v[40:41] op_sel_hi:[1,0,1]
	v_pk_fma_f32 v[30:31], v[30:31], v[50:51], v[46:47] op_sel_hi:[1,0,1]
	v_pk_fma_f32 v[26:27], v[26:27], v[50:51], v[42:43] op_sel_hi:[1,0,1]
	v_max_f32_e32 v28, 0, v28
	v_max_f32_e32 v24, 0, v24
	v_max_f32_e32 v29, 0, v29
	v_max_f32_e32 v25, 0, v25
	v_pk_mul_f32 v[28:29], v[28:29], v[28:29]
	v_pk_mul_f32 v[52:53], v[24:25], v[24:25]
	v_max_f32_e32 v24, 0, v30
	v_max_f32_e32 v26, 0, v26
	v_max_f32_e32 v25, 0, v31
	v_max_f32_e32 v27, 0, v27
	v_pk_mul_f32 v[30:31], v[24:25], v[24:25]
	v_pk_mul_f32 v[54:55], v[26:27], v[26:27]
	v_cvt_pk_bf16_f32 v24, v28, v29
	v_lshl_add_u64 v[28:29], s[20:21], 0, v[48:49]
	v_pk_fma_f32 v[16:17], v[16:17], v[50:51], v[32:33] op_sel_hi:[1,0,1]
	v_cvt_pk_bf16_f32 v25, v30, v31
	v_cvt_pk_bf16_f32 v26, v52, v53
	v_cvt_pk_bf16_f32 v27, v54, v55
	v_lshl_add_u64 v[28:29], v[28:29], 0, v[138:139]
	v_pk_fma_f32 v[22:23], v[22:23], v[50:51], v[38:39] op_sel_hi:[1,0,1]
	v_pk_fma_f32 v[20:21], v[20:21], v[50:51], v[36:37] op_sel_hi:[1,0,1]
	v_pk_fma_f32 v[18:19], v[18:19], v[50:51], v[34:35] op_sel_hi:[1,0,1]
	v_max_f32_e32 v16, 0, v16
	v_max_f32_e32 v17, 0, v17
	global_store_dwordx4 v[28:29], v[24:27], off
	v_max_f32_e32 v20, 0, v20
	v_max_f32_e32 v21, 0, v21
	v_pk_mul_f32 v[24:25], v[16:17], v[16:17]
	v_max_f32_e32 v16, 0, v22
	v_max_f32_e32 v18, 0, v18
	v_max_f32_e32 v17, 0, v23
	v_max_f32_e32 v19, 0, v19
	v_pk_mul_f32 v[20:21], v[20:21], v[20:21]
	v_pk_mul_f32 v[22:23], v[16:17], v[16:17]
	v_pk_mul_f32 v[26:27], v[18:19], v[18:19]
	v_cvt_pk_bf16_f32 v16, v20, v21
	v_cvt_pk_bf16_f32 v17, v22, v23
	v_cvt_pk_bf16_f32 v18, v24, v25
	v_cvt_pk_bf16_f32 v19, v26, v27
	global_store_dwordx4 v[28:29], v[16:19], off offset:256
	s_nop 1
	v_add_u32_e32 v16, 0xb0, v158
	v_ashrrev_i32_e32 v17, 31, v16
	v_lshlrev_b64 v[16:17], 13, v[16:17]
	v_add_f32_e32 v18, v216, v217
	v_add_f32_e32 v19, v218, v219
	v_add_f32_e32 v18, v18, v19
	v_mov_b32_e32 v19, v18
	s_nop 1
	v_permlane16_swap_b32_e32 v18, v19
	v_add_f32_e32 v18, v18, v19
	v_mov_b32_e32 v19, v18
	s_nop 1
	v_permlane32_swap_b32_e32 v18, v19
	v_add_f32_e32 v18, v18, v19
	v_fmamk_f32 v18, v18, 0x3a800000, v229
	v_cmp_gt_f32_e32 vcc, s55, v18
	v_mul_f32_e32 v19, 0x4b800000, v18
	s_nop 0
	v_cndmask_b32_e32 v18, v18, v19, vcc
	v_rsq_f32_e32 v18, v18
	s_nop 0
	v_mul_f32_e32 v19, 0x45800000, v18
	v_cndmask_b32_e32 v18, v18, v19, vcc
	v_pk_fma_f32 v[12:13], v[12:13], v[18:19], v[44:45] op_sel_hi:[1,0,1]
	v_pk_fma_f32 v[8:9], v[8:9], v[18:19], v[40:41] op_sel_hi:[1,0,1]
	v_pk_fma_f32 v[14:15], v[14:15], v[18:19], v[46:47] op_sel_hi:[1,0,1]
	v_pk_fma_f32 v[10:11], v[10:11], v[18:19], v[42:43] op_sel_hi:[1,0,1]
	v_max_f32_e32 v12, 0, v12
	v_max_f32_e32 v8, 0, v8
	v_max_f32_e32 v13, 0, v13
	v_max_f32_e32 v9, 0, v9
	v_pk_mul_f32 v[12:13], v[12:13], v[12:13]
	v_pk_mul_f32 v[20:21], v[8:9], v[8:9]
	v_max_f32_e32 v8, 0, v14
	v_max_f32_e32 v10, 0, v10
	v_max_f32_e32 v9, 0, v15
	v_max_f32_e32 v11, 0, v11
	v_pk_mul_f32 v[14:15], v[8:9], v[8:9]
	v_pk_mul_f32 v[22:23], v[10:11], v[10:11]
	v_cvt_pk_bf16_f32 v8, v12, v13
	v_lshl_add_u64 v[12:13], s[20:21], 0, v[16:17]
	v_pk_fma_f32 v[0:1], v[0:1], v[18:19], v[32:33] op_sel_hi:[1,0,1]
	v_cvt_pk_bf16_f32 v9, v14, v15
	v_cvt_pk_bf16_f32 v10, v20, v21
	v_cvt_pk_bf16_f32 v11, v22, v23
	v_lshl_add_u64 v[12:13], v[12:13], 0, v[138:139]
	v_pk_fma_f32 v[6:7], v[6:7], v[18:19], v[38:39] op_sel_hi:[1,0,1]
	v_pk_fma_f32 v[4:5], v[4:5], v[18:19], v[36:37] op_sel_hi:[1,0,1]
	v_pk_fma_f32 v[2:3], v[2:3], v[18:19], v[34:35] op_sel_hi:[1,0,1]
	v_max_f32_e32 v0, 0, v0
	v_max_f32_e32 v1, 0, v1
	global_store_dwordx4 v[12:13], v[8:11], off
	v_max_f32_e32 v4, 0, v4
	v_max_f32_e32 v5, 0, v5
	v_pk_mul_f32 v[8:9], v[0:1], v[0:1]
	v_max_f32_e32 v0, 0, v6
	v_max_f32_e32 v2, 0, v2
	v_max_f32_e32 v1, 0, v7
	v_max_f32_e32 v3, 0, v3
	v_pk_mul_f32 v[4:5], v[4:5], v[4:5]
	v_pk_mul_f32 v[6:7], v[0:1], v[0:1]
	v_pk_mul_f32 v[10:11], v[2:3], v[2:3]
	v_cvt_pk_bf16_f32 v0, v4, v5
	v_cvt_pk_bf16_f32 v1, v6, v7
	v_cvt_pk_bf16_f32 v2, v8, v9
	v_cvt_pk_bf16_f32 v3, v10, v11
	s_andn2_b64 vcc, exec, s[6:7]
	global_store_dwordx4 v[12:13], v[0:3], off offset:256
	s_cbranch_vccnz .LBB0_2121
	s_andn2_b64 vcc, exec, s[18:19]
	s_cbranch_vccnz .LBB0_2120
	s_barrier
	s_branch .LBB0_2120

.LBB0_2181:
	s_add_i32 s6, s89, -16
	s_lshr_b32 s6, s6, 2
	s_add_i32 s6, s6, 1
	s_cmp_gt_i32 s89, 15
	s_cselect_b32 s96, s6, 0
	s_lshl_b32 s6, s88, 8
	v_mov_b32_e32 v164, v240
	v_mov_b32_e32 v243, v191
	s_or_b32 s6, s6, s85
	s_mul_hi_u32 s7, s96, 0x6000
	v_lshl_add_u32 v206, v243, 3, s6
	s_mul_i32 s6, s96, 0x6000
	s_add_u32 s6, s75, s6
	v_ashrrev_i32_e32 v207, 31, v206
	s_addc_u32 s7, s79, s7
	v_lshlrev_b64 v[66:67], 2, v[206:207]
	v_lshl_add_u64 v[68:69], s[6:7], 0, v[66:67]
	global_load_dwordx4 v[98:101], v[68:69], off
	v_lshl_add_u64 v[66:67], s[0:1], 0, v[66:67]
	s_lshl_b64 s[6:7], s[96:97], 12
	v_lshl_add_u64 v[162:163], v[66:67], 0, s[6:7]
	v_cndmask_b32_e64 v66, 0, 1, s[10:11]
	v_mov_b32_e32 v74, 0
	v_cmp_ne_u32_e64 s[6:7], 1, v66
	s_andn2_b64 vcc, exec, s[10:11]
	v_mov_b32_e32 v78, 0
	v_mov_b32_e32 v79, 0
	v_mov_b32_e32 v80, 0
	v_mov_b32_e32 v81, 0
	s_cbranch_vccnz .LBB0_2183
	global_load_dwordx4 v[78:81], v[162:163], off
.LBB0_2183:
	global_load_dwordx4 v[102:105], v[68:69], off offset:16
	s_and_b64 vcc, exec, s[6:7]
	v_mov_b32_e32 v75, 0
	v_mov_b32_e32 v76, 0
	v_mov_b32_e32 v77, 0
	s_cbranch_vccnz .LBB0_2185
	global_load_dwordx4 v[74:77], v[162:163], off offset:16
.LBB0_2185:
	global_load_dwordx4 v[82:85], v[68:69], off offset:512
	v_mov_b32_e32 v66, 0
	s_and_b64 vcc, exec, s[6:7]
	v_mov_b32_e32 v70, 0
	v_mov_b32_e32 v71, 0
	v_mov_b32_e32 v72, 0
	v_mov_b32_e32 v73, 0
	s_cbranch_vccnz .LBB0_2187
	global_load_dwordx4 v[70:73], v[162:163], off offset:512
.LBB0_2187:
	global_load_dwordx4 v[90:93], v[68:69], off offset:528
	s_and_b64 vcc, exec, s[6:7]
	v_mov_b32_e32 v67, 0
	v_mov_b32_e32 v68, 0
	v_mov_b32_e32 v69, 0
	s_cbranch_vccnz .LBB0_2189
	global_load_dwordx4 v[66:69], v[162:163], off offset:528
.LBB0_2189:
	s_lshl_b32 s8, s89, 8
	s_add_i32 s8, s8, s84
	v_add_u32_e32 v210, s8, v164
	v_lshlrev_b64 v[224:225], 1, v[206:207]
	v_ashrrev_i32_e32 v211, 31, v210
	v_add_u32_e32 v220, 16, v210
	v_lshl_add_u64 v[208:209], s[18:19], 0, v[224:225]
	v_lshlrev_b64 v[226:227], 11, v[210:211]
	v_ashrrev_i32_e32 v221, 31, v220
	v_add_u32_e32 v216, 32, v210
	v_lshl_add_u64 v[162:163], v[208:209], 0, v[226:227]
	v_lshlrev_b64 v[222:223], 11, v[220:221]
	v_ashrrev_i32_e32 v217, 31, v216
	v_add_u32_e32 v212, 48, v210
	global_load_dwordx4 v[244:247], v[162:163], off
	global_load_dwordx4 v[186:189], v[162:163], off offset:256
	v_lshl_add_u64 v[162:163], v[208:209], 0, v[222:223]
	v_lshlrev_b64 v[218:219], 11, v[216:217]
	v_ashrrev_i32_e32 v213, 31, v212
	global_load_dwordx4 v[182:185], v[162:163], off
	global_load_dwordx4 v[178:181], v[162:163], off offset:256
	v_lshl_add_u64 v[162:163], v[208:209], 0, v[218:219]
	v_lshlrev_b64 v[214:215], 11, v[212:213]
	global_load_dwordx4 v[174:177], v[162:163], off
	global_load_dwordx4 v[170:173], v[162:163], off offset:256
	v_lshl_add_u64 v[162:163], v[208:209], 0, v[214:215]
	global_load_dwordx4 v[166:169], v[162:163], off
	s_nop 0
	global_load_dwordx4 v[162:165], v[162:163], off offset:256
	v_lshl_add_u64 v[226:227], s[18:19], 0, v[226:227]
	v_lshl_add_u64 v[226:227], v[226:227], 0, v[224:225]
	v_lshlrev_b64 v[248:249], 10, v[210:211]
	s_and_b64 vcc, exec, s[6:7]
	s_waitcnt vmcnt(0) lgkmcnt(0)
	v_lshlrev_b32_e32 v224, 16, v244
	v_and_b32_e32 v225, 0xffff0000, v244
	v_lshlrev_b32_e32 v244, 16, v245
	v_and_b32_e32 v245, 0xffff0000, v245
	v_lshlrev_b32_e32 v250, 16, v246
	v_and_b32_e32 v251, 0xffff0000, v246
	v_lshlrev_b32_e32 v246, 16, v247
	v_and_b32_e32 v247, 0xffff0000, v247
	v_pk_fma_f32 v[160:161], v[160:161], v[100:101], v[244:245]
	v_pk_fma_f32 v[158:159], v[158:159], v[98:99], v[224:225]
	v_pk_fma_f32 v[156:157], v[156:157], v[104:105], v[246:247]
	v_pk_fma_f32 v[154:155], v[154:155], v[102:103], v[250:251]
	v_cvt_pk_bf16_f32 v244, v158, v159
	v_cvt_pk_bf16_f32 v245, v160, v161
	v_cvt_pk_bf16_f32 v246, v154, v155
	v_cvt_pk_bf16_f32 v247, v156, v157
	v_lshl_add_u64 v[224:225], v[248:249], 1, s[20:21]
	global_store_dwordx4 v[226:227], v[244:247], off
	s_cbranch_vccnz .LBB0_2191
	s_nop 0
	v_pk_mul_f32 v[246:247], v[80:81], v[160:161]
	v_pk_mul_f32 v[244:245], v[78:79], v[158:159]
	v_pk_mul_f32 v[248:249], v[76:77], v[156:157]
	v_pk_mul_f32 v[250:251], v[74:75], v[154:155]
	v_cvt_pk_bf16_f32 v244, v244, v245
	v_cvt_pk_bf16_f32 v245, v246, v247
	v_cvt_pk_bf16_f32 v246, v250, v251
	v_cvt_pk_bf16_f32 v247, v248, v249
	v_lshl_add_u64 v[248:249], v[206:207], 1, v[224:225]
	global_store_dwordx4 v[248:249], v[244:247], off
.LBB0_2191:
	s_nop 1
	v_lshlrev_b32_e32 v244, 16, v186
	v_and_b32_e32 v245, 0xffff0000, v186
	v_lshlrev_b32_e32 v186, 16, v187
	v_and_b32_e32 v187, 0xffff0000, v187
	v_lshlrev_b32_e32 v246, 16, v188
	v_and_b32_e32 v247, 0xffff0000, v188
	v_lshlrev_b32_e32 v188, 16, v189
	v_and_b32_e32 v189, 0xffff0000, v189
	v_pk_fma_f32 v[152:153], v[152:153], v[84:85], v[186:187]
	v_pk_fma_f32 v[150:151], v[150:151], v[82:83], v[244:245]
	v_pk_fma_f32 v[148:149], v[148:149], v[92:93], v[188:189]
	v_pk_fma_f32 v[146:147], v[146:147], v[90:91], v[246:247]
	v_cvt_pk_bf16_f32 v186, v150, v151
	v_cvt_pk_bf16_f32 v187, v152, v153
	v_cvt_pk_bf16_f32 v188, v146, v147
	v_cvt_pk_bf16_f32 v189, v148, v149
	s_and_b64 vcc, exec, s[6:7]
	global_store_dwordx4 v[226:227], v[186:189], off offset:256
	s_cbranch_vccnz .LBB0_2193
	s_nop 0
	v_pk_mul_f32 v[188:189], v[72:73], v[152:153]
	v_pk_mul_f32 v[186:187], v[70:71], v[150:151]
	v_pk_mul_f32 v[226:227], v[68:69], v[148:149]
	v_pk_mul_f32 v[244:245], v[66:67], v[146:147]
	v_cvt_pk_bf16_f32 v186, v186, v187
	v_cvt_pk_bf16_f32 v187, v188, v189
	v_cvt_pk_bf16_f32 v188, v244, v245
	v_cvt_pk_bf16_f32 v189, v226, v227
	v_lshl_add_u64 v[224:225], v[206:207], 1, v[224:225]
	global_store_dwordx4 v[224:225], v[186:189], off offset:256
.LBB0_2193:
	v_mul_f32_e32 v159, v159, v159
	v_mul_f32_e32 v151, v151, v151
	v_fmac_f32_e32 v159, v158, v158
	v_mul_f32_e32 v158, v161, v161
	v_fmac_f32_e32 v151, v150, v150
	v_mul_f32_e32 v150, v153, v153
	v_fmac_f32_e32 v158, v160, v160
	v_mul_f32_e32 v155, v155, v155
	v_fmac_f32_e32 v150, v152, v152
	v_mul_f32_e32 v147, v147, v147
	v_add_f32_e32 v158, v159, v158
	v_fmac_f32_e32 v155, v154, v154
	v_add_f32_e32 v150, v151, v150
	v_fmac_f32_e32 v147, v146, v146
	v_add_f32_e32 v154, v155, v158
	v_mul_f32_e32 v155, v157, v157
	v_add_f32_e32 v146, v147, v150
	v_mul_f32_e32 v147, v149, v149
	v_fmac_f32_e32 v155, v156, v156
	v_fmac_f32_e32 v147, v148, v148
	v_add_f32_e32 v154, v155, v154
	v_add_f32_e32 v146, v147, v146
	v_add_f32_e32 v146, v154, v146
	v_mov_b32_e32 v147, v146
	s_nop 1
	v_permlane16_swap_b32_e32 v146, v147
	v_add_f32_e32 v146, v146, v147
	v_mov_b32_e32 v147, v146
	v_cmp_eq_u32_e64 s[8:9], 0, v243
	s_nop 0
	v_permlane32_swap_b32_e32 v146, v147
	s_and_saveexec_b64 s[34:35], s[8:9]
	s_cbranch_execz .LBB0_2195
	v_add_f32_e32 v148, v146, v147
	s_lshl_b32 s58, s88, 2
	v_lshlrev_b64 v[146:147], 6, v[210:211]
	s_ashr_i32 s59, s58, 31
	v_lshl_add_u64 v[146:147], s[22:23], 0, v[146:147]
	v_lshl_add_u64 v[146:147], s[58:59], 2, v[146:147]
	s_lshl_b32 s96, s83, 2
	v_lshl_add_u64 v[146:147], v[146:147], 0, s[96:97]
	global_store_dword v[146:147], v148, off
.LBB0_2195:
	s_or_b64 exec, exec, s[34:35]
	v_lshlrev_b32_e32 v148, 16, v182
	v_and_b32_e32 v149, 0xffff0000, v182
	v_lshlrev_b32_e32 v150, 16, v183
	v_and_b32_e32 v151, 0xffff0000, v183
	v_lshlrev_b32_e32 v152, 16, v184
	v_and_b32_e32 v153, 0xffff0000, v184
	v_lshlrev_b32_e32 v154, 16, v185
	v_and_b32_e32 v155, 0xffff0000, v185
	v_lshlrev_b64 v[146:147], 10, v[220:221]
	v_pk_fma_f32 v[144:145], v[144:145], v[100:101], v[150:151]
	v_pk_fma_f32 v[142:143], v[142:143], v[98:99], v[148:149]
	v_pk_fma_f32 v[140:141], v[140:141], v[104:105], v[154:155]
	v_pk_fma_f32 v[138:139], v[138:139], v[102:103], v[152:153]
	v_lshl_add_u64 v[148:149], s[18:19], 0, v[222:223]
	v_cvt_pk_bf16_f32 v150, v142, v143
	v_cvt_pk_bf16_f32 v151, v144, v145
	v_cvt_pk_bf16_f32 v152, v138, v139
	v_cvt_pk_bf16_f32 v153, v140, v141
	v_lshl_add_u64 v[148:149], v[206:207], 1, v[148:149]
	s_and_b64 vcc, exec, s[6:7]
	v_lshl_add_u64 v[146:147], v[146:147], 1, s[20:21]
	global_store_dwordx4 v[148:149], v[150:153], off
	s_cbranch_vccnz .LBB0_2197
	s_nop 0
	v_pk_mul_f32 v[152:153], v[80:81], v[144:145]
	v_pk_mul_f32 v[150:151], v[78:79], v[142:143]
	v_pk_mul_f32 v[154:155], v[76:77], v[140:141]
	v_pk_mul_f32 v[156:157], v[74:75], v[138:139]
	v_cvt_pk_bf16_f32 v150, v150, v151
	v_cvt_pk_bf16_f32 v151, v152, v153
	v_cvt_pk_bf16_f32 v152, v156, v157
	v_cvt_pk_bf16_f32 v153, v154, v155
	v_lshl_add_u64 v[154:155], v[206:207], 1, v[146:147]
	global_store_dwordx4 v[154:155], v[150:153], off
.LBB0_2197:
	s_nop 1
	v_lshlrev_b32_e32 v150, 16, v178
	v_and_b32_e32 v151, 0xffff0000, v178
	v_lshlrev_b32_e32 v152, 16, v179
	v_and_b32_e32 v153, 0xffff0000, v179
	v_lshlrev_b32_e32 v154, 16, v180
	v_and_b32_e32 v155, 0xffff0000, v180
	v_lshlrev_b32_e32 v156, 16, v181
	v_and_b32_e32 v157, 0xffff0000, v181
	v_pk_fma_f32 v[136:137], v[136:137], v[84:85], v[152:153]
	v_pk_fma_f32 v[134:135], v[134:135], v[82:83], v[150:151]
	v_pk_fma_f32 v[132:133], v[132:133], v[92:93], v[156:157]
	v_pk_fma_f32 v[130:131], v[130:131], v[90:91], v[154:155]
	v_cvt_pk_bf16_f32 v150, v134, v135
	v_cvt_pk_bf16_f32 v151, v136, v137
	v_cvt_pk_bf16_f32 v152, v130, v131
	v_cvt_pk_bf16_f32 v153, v132, v133
	s_and_b64 vcc, exec, s[6:7]
	global_store_dwordx4 v[148:149], v[150:153], off offset:256
	s_cbranch_vccnz .LBB0_2199
	s_nop 0
	v_pk_mul_f32 v[150:151], v[72:73], v[136:137]
	v_pk_mul_f32 v[148:149], v[70:71], v[134:135]
	v_pk_mul_f32 v[152:153], v[68:69], v[132:133]
	v_pk_mul_f32 v[154:155], v[66:67], v[130:131]
	v_cvt_pk_bf16_f32 v148, v148, v149
	v_cvt_pk_bf16_f32 v149, v150, v151
	v_cvt_pk_bf16_f32 v150, v154, v155
	v_cvt_pk_bf16_f32 v151, v152, v153
	v_lshl_add_u64 v[146:147], v[206:207], 1, v[146:147]
	global_store_dwordx4 v[146:147], v[148:151], off offset:256
.LBB0_2199:
	v_mul_f32_e32 v143, v143, v143
	v_mul_f32_e32 v135, v135, v135
	v_fmac_f32_e32 v143, v142, v142
	v_mul_f32_e32 v142, v145, v145
	v_fmac_f32_e32 v135, v134, v134
	v_mul_f32_e32 v134, v137, v137
	v_fmac_f32_e32 v142, v144, v144
	v_mul_f32_e32 v139, v139, v139
	v_fmac_f32_e32 v134, v136, v136
	v_mul_f32_e32 v131, v131, v131
	v_add_f32_e32 v142, v143, v142
	v_fmac_f32_e32 v139, v138, v138
	v_add_f32_e32 v134, v135, v134
	v_fmac_f32_e32 v131, v130, v130
	v_add_f32_e32 v138, v139, v142
	v_mul_f32_e32 v139, v141, v141
	v_add_f32_e32 v130, v131, v134
	v_mul_f32_e32 v131, v133, v133
	v_fmac_f32_e32 v139, v140, v140
	v_fmac_f32_e32 v131, v132, v132
	v_add_f32_e32 v138, v139, v138
	v_add_f32_e32 v130, v131, v130
	v_add_f32_e32 v130, v138, v130
	v_mov_b32_e32 v131, v130
	s_nop 1
	v_permlane16_swap_b32_e32 v130, v131
	v_add_f32_e32 v130, v130, v131
	v_mov_b32_e32 v131, v130
	s_nop 1
	v_permlane32_swap_b32_e32 v130, v131
	s_and_saveexec_b64 s[34:35], s[8:9]
	s_cbranch_execz .LBB0_2201
	v_add_f32_e32 v132, v130, v131
	s_lshl_b32 s58, s88, 2
	v_lshlrev_b64 v[130:131], 6, v[220:221]
	s_ashr_i32 s59, s58, 31
	v_lshl_add_u64 v[130:131], s[22:23], 0, v[130:131]
	v_lshl_add_u64 v[130:131], s[58:59], 2, v[130:131]
	s_lshl_b32 s96, s83, 2
	v_lshl_add_u64 v[130:131], v[130:131], 0, s[96:97]
	global_store_dword v[130:131], v132, off
.LBB0_2201:
	s_or_b64 exec, exec, s[34:35]
	v_lshlrev_b32_e32 v132, 16, v174
	v_and_b32_e32 v133, 0xffff0000, v174
	v_lshlrev_b32_e32 v134, 16, v175
	v_and_b32_e32 v135, 0xffff0000, v175
	v_lshlrev_b32_e32 v136, 16, v176
	v_and_b32_e32 v137, 0xffff0000, v176
	v_lshlrev_b32_e32 v138, 16, v177
	v_and_b32_e32 v139, 0xffff0000, v177
	v_lshlrev_b64 v[130:131], 10, v[216:217]
	v_pk_fma_f32 v[128:129], v[128:129], v[100:101], v[134:135]
	v_pk_fma_f32 v[126:127], v[126:127], v[98:99], v[132:133]
	v_pk_fma_f32 v[124:125], v[124:125], v[104:105], v[138:139]
	v_pk_fma_f32 v[122:123], v[122:123], v[102:103], v[136:137]
	v_lshl_add_u64 v[132:133], s[18:19], 0, v[218:219]
	v_cvt_pk_bf16_f32 v134, v126, v127
	v_cvt_pk_bf16_f32 v135, v128, v129
	v_cvt_pk_bf16_f32 v136, v122, v123
	v_cvt_pk_bf16_f32 v137, v124, v125
	v_lshl_add_u64 v[132:133], v[206:207], 1, v[132:133]
	s_and_b64 vcc, exec, s[6:7]
	v_lshl_add_u64 v[130:131], v[130:131], 1, s[20:21]
	global_store_dwordx4 v[132:133], v[134:137], off
	s_cbranch_vccnz .LBB0_2203
	s_nop 0
	v_pk_mul_f32 v[136:137], v[80:81], v[128:129]
	v_pk_mul_f32 v[134:135], v[78:79], v[126:127]
	v_pk_mul_f32 v[138:139], v[76:77], v[124:125]
	v_pk_mul_f32 v[140:141], v[74:75], v[122:123]
	v_cvt_pk_bf16_f32 v134, v134, v135
	v_cvt_pk_bf16_f32 v135, v136, v137
	v_cvt_pk_bf16_f32 v136, v140, v141
	v_cvt_pk_bf16_f32 v137, v138, v139
	v_lshl_add_u64 v[138:139], v[206:207], 1, v[130:131]
	global_store_dwordx4 v[138:139], v[134:137], off
.LBB0_2203:
	s_nop 1
	v_lshlrev_b32_e32 v134, 16, v170
	v_and_b32_e32 v135, 0xffff0000, v170
	v_lshlrev_b32_e32 v136, 16, v171
	v_and_b32_e32 v137, 0xffff0000, v171
	v_lshlrev_b32_e32 v138, 16, v172
	v_and_b32_e32 v139, 0xffff0000, v172
	v_lshlrev_b32_e32 v140, 16, v173
	v_and_b32_e32 v141, 0xffff0000, v173
	v_pk_fma_f32 v[120:121], v[120:121], v[84:85], v[136:137]
	v_pk_fma_f32 v[118:119], v[118:119], v[82:83], v[134:135]
	v_pk_fma_f32 v[116:117], v[116:117], v[92:93], v[140:141]
	v_pk_fma_f32 v[114:115], v[114:115], v[90:91], v[138:139]
	v_cvt_pk_bf16_f32 v134, v118, v119
	v_cvt_pk_bf16_f32 v135, v120, v121
	v_cvt_pk_bf16_f32 v136, v114, v115
	v_cvt_pk_bf16_f32 v137, v116, v117
	s_and_b64 vcc, exec, s[6:7]
	global_store_dwordx4 v[132:133], v[134:137], off offset:256
	s_cbranch_vccnz .LBB0_2205
	s_nop 0
	v_pk_mul_f32 v[134:135], v[72:73], v[120:121]
	v_pk_mul_f32 v[132:133], v[70:71], v[118:119]
	v_pk_mul_f32 v[136:137], v[68:69], v[116:117]
	v_pk_mul_f32 v[138:139], v[66:67], v[114:115]
	v_cvt_pk_bf16_f32 v132, v132, v133
	v_cvt_pk_bf16_f32 v133, v134, v135
	v_cvt_pk_bf16_f32 v134, v138, v139
	v_cvt_pk_bf16_f32 v135, v136, v137
	v_lshl_add_u64 v[130:131], v[206:207], 1, v[130:131]
	global_store_dwordx4 v[130:131], v[132:135], off offset:256
.LBB0_2205:
	v_mul_f32_e32 v127, v127, v127
	v_mul_f32_e32 v119, v119, v119
	v_fmac_f32_e32 v127, v126, v126
	v_mul_f32_e32 v126, v129, v129
	v_fmac_f32_e32 v119, v118, v118
	v_mul_f32_e32 v118, v121, v121
	v_fmac_f32_e32 v126, v128, v128
	v_mul_f32_e32 v123, v123, v123
	v_fmac_f32_e32 v118, v120, v120
	v_mul_f32_e32 v115, v115, v115
	v_add_f32_e32 v126, v127, v126
	v_fmac_f32_e32 v123, v122, v122
	v_add_f32_e32 v118, v119, v118
	v_fmac_f32_e32 v115, v114, v114
	v_add_f32_e32 v122, v123, v126
	v_mul_f32_e32 v123, v125, v125
	v_add_f32_e32 v114, v115, v118
	v_mul_f32_e32 v115, v117, v117
	v_fmac_f32_e32 v123, v124, v124
	v_fmac_f32_e32 v115, v116, v116
	v_add_f32_e32 v122, v123, v122
	v_add_f32_e32 v114, v115, v114
	v_add_f32_e32 v114, v122, v114
	v_mov_b32_e32 v115, v114
	s_nop 1
	v_permlane16_swap_b32_e32 v114, v115
	v_add_f32_e32 v114, v114, v115
	v_mov_b32_e32 v115, v114
	s_nop 1
	v_permlane32_swap_b32_e32 v114, v115
	s_and_saveexec_b64 s[34:35], s[8:9]
	s_cbranch_execz .LBB0_2207
	v_add_f32_e32 v116, v114, v115
	s_lshl_b32 s58, s88, 2
	v_lshlrev_b64 v[114:115], 6, v[216:217]
	s_ashr_i32 s59, s58, 31
	v_lshl_add_u64 v[114:115], s[22:23], 0, v[114:115]
	v_lshl_add_u64 v[114:115], s[58:59], 2, v[114:115]
	s_lshl_b32 s96, s83, 2
	v_lshl_add_u64 v[114:115], v[114:115], 0, s[96:97]
	global_store_dword v[114:115], v116, off
.LBB0_2207:
	s_or_b64 exec, exec, s[34:35]
	v_lshlrev_b32_e32 v116, 16, v166
	v_and_b32_e32 v117, 0xffff0000, v166
	v_lshlrev_b32_e32 v118, 16, v167
	v_and_b32_e32 v119, 0xffff0000, v167
	v_lshlrev_b32_e32 v120, 16, v168
	v_and_b32_e32 v121, 0xffff0000, v168
	v_lshlrev_b32_e32 v122, 16, v169
	v_and_b32_e32 v123, 0xffff0000, v169
	v_lshlrev_b64 v[114:115], 10, v[212:213]
	v_pk_fma_f32 v[112:113], v[112:113], v[100:101], v[118:119]
	v_pk_fma_f32 v[110:111], v[110:111], v[98:99], v[116:117]
	v_pk_fma_f32 v[108:109], v[108:109], v[104:105], v[122:123]
	v_pk_fma_f32 v[106:107], v[106:107], v[102:103], v[120:121]
	v_lshl_add_u64 v[116:117], s[18:19], 0, v[214:215]
	v_cvt_pk_bf16_f32 v118, v110, v111
	v_cvt_pk_bf16_f32 v119, v112, v113
	v_cvt_pk_bf16_f32 v120, v106, v107
	v_cvt_pk_bf16_f32 v121, v108, v109
	v_lshl_add_u64 v[116:117], v[206:207], 1, v[116:117]
	s_and_b64 vcc, exec, s[6:7]
	v_lshl_add_u64 v[114:115], v[114:115], 1, s[20:21]
	global_store_dwordx4 v[116:117], v[118:121], off
	s_cbranch_vccnz .LBB0_2209
	s_nop 0
	v_pk_mul_f32 v[120:121], v[80:81], v[112:113]
	v_pk_mul_f32 v[118:119], v[78:79], v[110:111]
	v_pk_mul_f32 v[122:123], v[76:77], v[108:109]
	v_pk_mul_f32 v[124:125], v[74:75], v[106:107]
	v_cvt_pk_bf16_f32 v118, v118, v119
	v_cvt_pk_bf16_f32 v119, v120, v121
	v_cvt_pk_bf16_f32 v120, v124, v125
	v_cvt_pk_bf16_f32 v121, v122, v123
	v_lshl_add_u64 v[122:123], v[206:207], 1, v[114:115]
	global_store_dwordx4 v[122:123], v[118:121], off
.LBB0_2209:
	s_nop 1
	v_lshlrev_b32_e32 v118, 16, v162
	v_and_b32_e32 v119, 0xffff0000, v162
	v_lshlrev_b32_e32 v120, 16, v163
	v_and_b32_e32 v121, 0xffff0000, v163
	v_lshlrev_b32_e32 v122, 16, v164
	v_and_b32_e32 v123, 0xffff0000, v164
	v_lshlrev_b32_e32 v124, 16, v165
	v_and_b32_e32 v125, 0xffff0000, v165
	v_pk_fma_f32 v[96:97], v[96:97], v[84:85], v[120:121]
	v_pk_fma_f32 v[94:95], v[94:95], v[82:83], v[118:119]
	v_pk_fma_f32 v[88:89], v[88:89], v[92:93], v[124:125]
	v_pk_fma_f32 v[86:87], v[86:87], v[90:91], v[122:123]
	v_cvt_pk_bf16_f32 v118, v94, v95
	v_cvt_pk_bf16_f32 v119, v96, v97
	v_cvt_pk_bf16_f32 v120, v86, v87
	v_cvt_pk_bf16_f32 v121, v88, v89
	s_and_b64 vcc, exec, s[6:7]
	global_store_dwordx4 v[116:117], v[118:121], off offset:256
	s_cbranch_vccnz .LBB0_2211
	s_nop 0
	v_pk_mul_f32 v[118:119], v[72:73], v[96:97]
	v_pk_mul_f32 v[116:117], v[70:71], v[94:95]
	v_pk_mul_f32 v[120:121], v[68:69], v[88:89]
	v_pk_mul_f32 v[122:123], v[66:67], v[86:87]
	v_cvt_pk_bf16_f32 v116, v116, v117
	v_cvt_pk_bf16_f32 v117, v118, v119
	v_cvt_pk_bf16_f32 v118, v122, v123
	v_cvt_pk_bf16_f32 v119, v120, v121
	v_lshl_add_u64 v[114:115], v[206:207], 1, v[114:115]
	global_store_dwordx4 v[114:115], v[116:119], off offset:256
.LBB0_2211:
	v_mul_f32_e32 v111, v111, v111
	v_mul_f32_e32 v95, v95, v95
	v_fmac_f32_e32 v111, v110, v110
	v_mul_f32_e32 v110, v113, v113
	v_fmac_f32_e32 v95, v94, v94
	v_mul_f32_e32 v94, v97, v97
	v_fmac_f32_e32 v110, v112, v112
	v_mul_f32_e32 v107, v107, v107
	v_fmac_f32_e32 v94, v96, v96
	v_mul_f32_e32 v87, v87, v87
	v_add_f32_e32 v110, v111, v110
	v_fmac_f32_e32 v107, v106, v106
	v_add_f32_e32 v94, v95, v94
	v_fmac_f32_e32 v87, v86, v86
	v_add_f32_e32 v106, v107, v110
	v_mul_f32_e32 v107, v109, v109
	v_add_f32_e32 v86, v87, v94
	v_mul_f32_e32 v87, v89, v89
	v_fmac_f32_e32 v107, v108, v108
	v_fmac_f32_e32 v87, v88, v88
	v_add_f32_e32 v106, v107, v106
	v_add_f32_e32 v86, v87, v86
	v_add_f32_e32 v86, v106, v86
	v_mov_b32_e32 v87, v86
	s_nop 1
	v_permlane16_swap_b32_e32 v86, v87
	v_add_f32_e32 v86, v86, v87
	v_mov_b32_e32 v87, v86
	s_nop 1
	v_permlane32_swap_b32_e32 v86, v87
	s_and_saveexec_b64 s[34:35], s[8:9]
	s_cbranch_execz .LBB0_2213
	v_add_f32_e32 v88, v86, v87
	s_lshl_b32 s58, s88, 2
	v_lshlrev_b64 v[86:87], 6, v[212:213]
	s_ashr_i32 s59, s58, 31
	v_lshl_add_u64 v[86:87], s[22:23], 0, v[86:87]
	v_lshl_add_u64 v[86:87], s[58:59], 2, v[86:87]
	s_lshl_b32 s96, s83, 2
	v_lshl_add_u64 v[86:87], v[86:87], 0, s[96:97]
	global_store_dword v[86:87], v88, off
.LBB0_2213:
	s_or_b64 exec, exec, s[34:35]
	v_add_u32_e32 v138, 0x80, v210
	v_ashrrev_i32_e32 v139, 31, v138
	v_add_u32_e32 v134, 0x90, v210
	v_lshlrev_b64 v[140:141], 11, v[138:139]
	v_ashrrev_i32_e32 v135, 31, v134
	v_add_u32_e32 v130, 0xa0, v210
	v_lshl_add_u64 v[86:87], v[208:209], 0, v[140:141]
	v_lshlrev_b64 v[136:137], 11, v[134:135]
	v_ashrrev_i32_e32 v131, 31, v130
	v_add_u32_e32 v126, 0xb0, v210
	global_load_dwordx4 v[144:147], v[86:87], off
	global_load_dwordx4 v[122:125], v[86:87], off offset:256
	v_lshl_add_u64 v[86:87], v[208:209], 0, v[136:137]
	v_lshlrev_b64 v[132:133], 11, v[130:131]
	v_ashrrev_i32_e32 v127, 31, v126
	global_load_dwordx4 v[118:121], v[86:87], off
	global_load_dwordx4 v[114:117], v[86:87], off offset:256
	v_lshl_add_u64 v[86:87], v[208:209], 0, v[132:133]
	v_lshlrev_b64 v[128:129], 11, v[126:127]
	global_load_dwordx4 v[110:113], v[86:87], off
	global_load_dwordx4 v[106:109], v[86:87], off offset:256
	v_lshl_add_u64 v[86:87], v[208:209], 0, v[128:129]
	global_load_dwordx4 v[94:97], v[86:87], off
	s_nop 0
	global_load_dwordx4 v[86:89], v[86:87], off offset:256
	v_lshl_add_u64 v[140:141], s[18:19], 0, v[140:141]
	v_lshl_add_u64 v[142:143], v[206:207], 1, v[140:141]
	v_lshlrev_b64 v[148:149], 10, v[138:139]
	s_and_b64 vcc, exec, s[6:7]
	s_waitcnt vmcnt(0) lgkmcnt(0)
	v_lshlrev_b32_e32 v140, 16, v144
	v_and_b32_e32 v141, 0xffff0000, v144
	v_lshlrev_b32_e32 v144, 16, v145
	v_and_b32_e32 v145, 0xffff0000, v145
	v_lshlrev_b32_e32 v150, 16, v146
	v_and_b32_e32 v151, 0xffff0000, v146
	v_lshlrev_b32_e32 v146, 16, v147
	v_and_b32_e32 v147, 0xffff0000, v147
	v_pk_fma_f32 v[62:63], v[62:63], v[100:101], v[144:145]
	v_pk_fma_f32 v[60:61], v[60:61], v[98:99], v[140:141]
	v_pk_fma_f32 v[58:59], v[58:59], v[104:105], v[146:147]
	v_pk_fma_f32 v[56:57], v[56:57], v[102:103], v[150:151]
	v_cvt_pk_bf16_f32 v144, v60, v61
	v_cvt_pk_bf16_f32 v145, v62, v63
	v_cvt_pk_bf16_f32 v146, v56, v57
	v_cvt_pk_bf16_f32 v147, v58, v59
	v_lshl_add_u64 v[140:141], v[148:149], 1, s[20:21]
	global_store_dwordx4 v[142:143], v[144:147], off
	s_cbranch_vccnz .LBB0_2215
	s_nop 0
	v_pk_mul_f32 v[146:147], v[80:81], v[62:63]
	v_pk_mul_f32 v[144:145], v[78:79], v[60:61]
	v_pk_mul_f32 v[148:149], v[76:77], v[58:59]
	v_pk_mul_f32 v[150:151], v[74:75], v[56:57]
	v_cvt_pk_bf16_f32 v144, v144, v145
	v_cvt_pk_bf16_f32 v145, v146, v147
	v_cvt_pk_bf16_f32 v146, v150, v151
	v_cvt_pk_bf16_f32 v147, v148, v149
	v_lshl_add_u64 v[148:149], v[206:207], 1, v[140:141]
	global_store_dwordx4 v[148:149], v[144:147], off
.LBB0_2215:
	s_nop 1
	v_lshlrev_b32_e32 v144, 16, v122
	v_and_b32_e32 v145, 0xffff0000, v122
	v_lshlrev_b32_e32 v122, 16, v123
	v_and_b32_e32 v123, 0xffff0000, v123
	v_lshlrev_b32_e32 v146, 16, v124
	v_and_b32_e32 v147, 0xffff0000, v124
	v_lshlrev_b32_e32 v124, 16, v125
	v_and_b32_e32 v125, 0xffff0000, v125
	v_pk_fma_f32 v[54:55], v[54:55], v[84:85], v[122:123]
	v_pk_fma_f32 v[52:53], v[52:53], v[82:83], v[144:145]
	v_pk_fma_f32 v[50:51], v[50:51], v[92:93], v[124:125]
	v_pk_fma_f32 v[48:49], v[48:49], v[90:91], v[146:147]
	v_cvt_pk_bf16_f32 v122, v52, v53
	v_cvt_pk_bf16_f32 v123, v54, v55
	v_cvt_pk_bf16_f32 v124, v48, v49
	v_cvt_pk_bf16_f32 v125, v50, v51
	s_and_b64 vcc, exec, s[6:7]
	global_store_dwordx4 v[142:143], v[122:125], off offset:256
	s_cbranch_vccnz .LBB0_2217
	s_nop 0
	v_pk_mul_f32 v[124:125], v[72:73], v[54:55]
	v_pk_mul_f32 v[122:123], v[70:71], v[52:53]
	v_pk_mul_f32 v[142:143], v[68:69], v[50:51]
	v_pk_mul_f32 v[144:145], v[66:67], v[48:49]
	v_cvt_pk_bf16_f32 v122, v122, v123
	v_cvt_pk_bf16_f32 v123, v124, v125
	v_cvt_pk_bf16_f32 v124, v144, v145
	v_cvt_pk_bf16_f32 v125, v142, v143
	v_lshl_add_u64 v[140:141], v[206:207], 1, v[140:141]
	global_store_dwordx4 v[140:141], v[122:125], off offset:256
.LBB0_2217:
	v_mul_f32_e32 v61, v61, v61
	v_mul_f32_e32 v53, v53, v53
	v_fmac_f32_e32 v61, v60, v60
	v_mul_f32_e32 v60, v63, v63
	v_fmac_f32_e32 v53, v52, v52
	v_mul_f32_e32 v52, v55, v55
	v_fmac_f32_e32 v60, v62, v62
	v_mul_f32_e32 v57, v57, v57
	v_fmac_f32_e32 v52, v54, v54
	v_mul_f32_e32 v49, v49, v49
	v_add_f32_e32 v60, v61, v60
	v_fmac_f32_e32 v57, v56, v56
	v_add_f32_e32 v52, v53, v52
	v_fmac_f32_e32 v49, v48, v48
	v_add_f32_e32 v56, v57, v60
	v_mul_f32_e32 v57, v59, v59
	v_add_f32_e32 v48, v49, v52
	v_mul_f32_e32 v49, v51, v51
	v_fmac_f32_e32 v57, v58, v58
	v_fmac_f32_e32 v49, v50, v50
	v_add_f32_e32 v56, v57, v56
	v_add_f32_e32 v48, v49, v48
	v_add_f32_e32 v48, v56, v48
	v_mov_b32_e32 v49, v48
	s_nop 1
	v_permlane16_swap_b32_e32 v48, v49
	v_add_f32_e32 v48, v48, v49
	v_mov_b32_e32 v49, v48
	s_nop 1
	v_permlane32_swap_b32_e32 v48, v49
	s_and_saveexec_b64 s[34:35], s[8:9]
	s_cbranch_execz .LBB0_2219
	v_add_f32_e32 v50, v48, v49
	s_lshl_b32 s58, s88, 2
	v_lshlrev_b64 v[48:49], 6, v[138:139]
	s_ashr_i32 s59, s58, 31
	v_lshl_add_u64 v[48:49], s[22:23], 0, v[48:49]
	v_lshl_add_u64 v[48:49], s[58:59], 2, v[48:49]
	s_lshl_b32 s96, s83, 2
	v_lshl_add_u64 v[48:49], v[48:49], 0, s[96:97]
	global_store_dword v[48:49], v50, off
.LBB0_2219:
	s_or_b64 exec, exec, s[34:35]
	v_lshlrev_b32_e32 v50, 16, v118
	v_and_b32_e32 v51, 0xffff0000, v118
	v_lshlrev_b32_e32 v52, 16, v119
	v_and_b32_e32 v53, 0xffff0000, v119
	v_lshlrev_b32_e32 v54, 16, v120
	v_and_b32_e32 v55, 0xffff0000, v120
	v_lshlrev_b32_e32 v56, 16, v121
	v_and_b32_e32 v57, 0xffff0000, v121
	v_lshlrev_b64 v[48:49], 10, v[134:135]
	v_pk_fma_f32 v[46:47], v[46:47], v[100:101], v[52:53]
	v_pk_fma_f32 v[44:45], v[44:45], v[98:99], v[50:51]
	v_pk_fma_f32 v[42:43], v[42:43], v[104:105], v[56:57]
	v_pk_fma_f32 v[40:41], v[40:41], v[102:103], v[54:55]
	v_lshl_add_u64 v[50:51], s[18:19], 0, v[136:137]
	v_cvt_pk_bf16_f32 v52, v44, v45
	v_cvt_pk_bf16_f32 v53, v46, v47
	v_cvt_pk_bf16_f32 v54, v40, v41
	v_cvt_pk_bf16_f32 v55, v42, v43
	v_lshl_add_u64 v[50:51], v[206:207], 1, v[50:51]
	s_and_b64 vcc, exec, s[6:7]
	v_lshl_add_u64 v[48:49], v[48:49], 1, s[20:21]
	global_store_dwordx4 v[50:51], v[52:55], off
	s_cbranch_vccnz .LBB0_2221
	s_nop 0
	v_pk_mul_f32 v[54:55], v[80:81], v[46:47]
	v_pk_mul_f32 v[52:53], v[78:79], v[44:45]
	v_pk_mul_f32 v[56:57], v[76:77], v[42:43]
	v_pk_mul_f32 v[58:59], v[74:75], v[40:41]
	v_cvt_pk_bf16_f32 v52, v52, v53
	v_cvt_pk_bf16_f32 v53, v54, v55
	v_cvt_pk_bf16_f32 v54, v58, v59
	v_cvt_pk_bf16_f32 v55, v56, v57
	v_lshl_add_u64 v[56:57], v[206:207], 1, v[48:49]
	global_store_dwordx4 v[56:57], v[52:55], off
.LBB0_2221:
	s_nop 1
	v_lshlrev_b32_e32 v52, 16, v114
	v_and_b32_e32 v53, 0xffff0000, v114
	v_lshlrev_b32_e32 v54, 16, v115
	v_and_b32_e32 v55, 0xffff0000, v115
	v_lshlrev_b32_e32 v56, 16, v116
	v_and_b32_e32 v57, 0xffff0000, v116
	v_lshlrev_b32_e32 v58, 16, v117
	v_and_b32_e32 v59, 0xffff0000, v117
	v_pk_fma_f32 v[38:39], v[38:39], v[84:85], v[54:55]
	v_pk_fma_f32 v[36:37], v[36:37], v[82:83], v[52:53]
	v_pk_fma_f32 v[34:35], v[34:35], v[92:93], v[58:59]
	v_pk_fma_f32 v[32:33], v[32:33], v[90:91], v[56:57]
	v_cvt_pk_bf16_f32 v52, v36, v37
	v_cvt_pk_bf16_f32 v53, v38, v39
	v_cvt_pk_bf16_f32 v54, v32, v33
	v_cvt_pk_bf16_f32 v55, v34, v35
	s_and_b64 vcc, exec, s[6:7]
	global_store_dwordx4 v[50:51], v[52:55], off offset:256
	s_cbranch_vccnz .LBB0_2223
	s_nop 0
	v_pk_mul_f32 v[52:53], v[72:73], v[38:39]
	v_pk_mul_f32 v[50:51], v[70:71], v[36:37]
	v_pk_mul_f32 v[54:55], v[68:69], v[34:35]
	v_pk_mul_f32 v[56:57], v[66:67], v[32:33]
	v_cvt_pk_bf16_f32 v50, v50, v51
	v_cvt_pk_bf16_f32 v51, v52, v53
	v_cvt_pk_bf16_f32 v52, v56, v57
	v_cvt_pk_bf16_f32 v53, v54, v55
	v_lshl_add_u64 v[48:49], v[206:207], 1, v[48:49]
	global_store_dwordx4 v[48:49], v[50:53], off offset:256
.LBB0_2223:
	v_mul_f32_e32 v45, v45, v45
	v_mul_f32_e32 v37, v37, v37
	v_fmac_f32_e32 v45, v44, v44
	v_mul_f32_e32 v44, v47, v47
	v_fmac_f32_e32 v37, v36, v36
	v_mul_f32_e32 v36, v39, v39
	v_fmac_f32_e32 v44, v46, v46
	v_mul_f32_e32 v41, v41, v41
	v_fmac_f32_e32 v36, v38, v38
	v_mul_f32_e32 v33, v33, v33
	v_add_f32_e32 v44, v45, v44
	v_fmac_f32_e32 v41, v40, v40
	v_add_f32_e32 v36, v37, v36
	v_fmac_f32_e32 v33, v32, v32
	v_add_f32_e32 v40, v41, v44
	v_mul_f32_e32 v41, v43, v43
	v_add_f32_e32 v32, v33, v36
	v_mul_f32_e32 v33, v35, v35
	v_fmac_f32_e32 v41, v42, v42
	v_fmac_f32_e32 v33, v34, v34
	v_add_f32_e32 v40, v41, v40
	v_add_f32_e32 v32, v33, v32
	v_add_f32_e32 v32, v40, v32
	v_mov_b32_e32 v33, v32
	s_nop 1
	v_permlane16_swap_b32_e32 v32, v33
	v_add_f32_e32 v32, v32, v33
	v_mov_b32_e32 v33, v32
	s_nop 1
	v_permlane32_swap_b32_e32 v32, v33
	s_and_saveexec_b64 s[34:35], s[8:9]
	s_cbranch_execz .LBB0_2225
	v_add_f32_e32 v34, v32, v33
	s_lshl_b32 s58, s88, 2
	v_lshlrev_b64 v[32:33], 6, v[134:135]
	s_ashr_i32 s59, s58, 31
	v_lshl_add_u64 v[32:33], s[22:23], 0, v[32:33]
	v_lshl_add_u64 v[32:33], s[58:59], 2, v[32:33]
	s_lshl_b32 s96, s83, 2
	v_lshl_add_u64 v[32:33], v[32:33], 0, s[96:97]
	global_store_dword v[32:33], v34, off
.LBB0_2225:
	s_or_b64 exec, exec, s[34:35]
	v_lshlrev_b32_e32 v34, 16, v110
	v_and_b32_e32 v35, 0xffff0000, v110
	v_lshlrev_b32_e32 v36, 16, v111
	v_and_b32_e32 v37, 0xffff0000, v111
	v_lshlrev_b32_e32 v38, 16, v112
	v_and_b32_e32 v39, 0xffff0000, v112
	v_lshlrev_b32_e32 v40, 16, v113
	v_and_b32_e32 v41, 0xffff0000, v113
	v_lshlrev_b64 v[32:33], 10, v[130:131]
	v_pk_fma_f32 v[30:31], v[30:31], v[100:101], v[36:37]
	v_pk_fma_f32 v[28:29], v[28:29], v[98:99], v[34:35]
	v_pk_fma_f32 v[26:27], v[26:27], v[104:105], v[40:41]
	v_pk_fma_f32 v[24:25], v[24:25], v[102:103], v[38:39]
	v_lshl_add_u64 v[34:35], s[18:19], 0, v[132:133]
	v_cvt_pk_bf16_f32 v36, v28, v29
	v_cvt_pk_bf16_f32 v37, v30, v31
	v_cvt_pk_bf16_f32 v38, v24, v25
	v_cvt_pk_bf16_f32 v39, v26, v27
	v_lshl_add_u64 v[34:35], v[206:207], 1, v[34:35]
	s_and_b64 vcc, exec, s[6:7]
	v_lshl_add_u64 v[32:33], v[32:33], 1, s[20:21]
	global_store_dwordx4 v[34:35], v[36:39], off
	s_cbranch_vccnz .LBB0_2227
	s_nop 0
	v_pk_mul_f32 v[38:39], v[80:81], v[30:31]
	v_pk_mul_f32 v[36:37], v[78:79], v[28:29]
	v_pk_mul_f32 v[40:41], v[76:77], v[26:27]
	v_pk_mul_f32 v[42:43], v[74:75], v[24:25]
	v_cvt_pk_bf16_f32 v36, v36, v37
	v_cvt_pk_bf16_f32 v37, v38, v39
	v_cvt_pk_bf16_f32 v38, v42, v43
	v_cvt_pk_bf16_f32 v39, v40, v41
	v_lshl_add_u64 v[40:41], v[206:207], 1, v[32:33]
	global_store_dwordx4 v[40:41], v[36:39], off
.LBB0_2227:
	s_nop 1
	v_lshlrev_b32_e32 v36, 16, v106
	v_and_b32_e32 v37, 0xffff0000, v106
	v_lshlrev_b32_e32 v38, 16, v107
	v_and_b32_e32 v39, 0xffff0000, v107
	v_lshlrev_b32_e32 v40, 16, v108
	v_and_b32_e32 v41, 0xffff0000, v108
	v_lshlrev_b32_e32 v42, 16, v109
	v_and_b32_e32 v43, 0xffff0000, v109
	v_pk_fma_f32 v[22:23], v[22:23], v[84:85], v[38:39]
	v_pk_fma_f32 v[20:21], v[20:21], v[82:83], v[36:37]
	v_pk_fma_f32 v[18:19], v[18:19], v[92:93], v[42:43]
	v_pk_fma_f32 v[16:17], v[16:17], v[90:91], v[40:41]
	v_cvt_pk_bf16_f32 v36, v20, v21
	v_cvt_pk_bf16_f32 v37, v22, v23
	v_cvt_pk_bf16_f32 v38, v16, v17
	v_cvt_pk_bf16_f32 v39, v18, v19
	s_and_b64 vcc, exec, s[6:7]
	global_store_dwordx4 v[34:35], v[36:39], off offset:256
	s_cbranch_vccnz .LBB0_2229
	s_nop 0
	v_pk_mul_f32 v[36:37], v[72:73], v[22:23]
	v_pk_mul_f32 v[34:35], v[70:71], v[20:21]
	v_pk_mul_f32 v[38:39], v[68:69], v[18:19]
	v_pk_mul_f32 v[40:41], v[66:67], v[16:17]
	v_cvt_pk_bf16_f32 v34, v34, v35
	v_cvt_pk_bf16_f32 v35, v36, v37
	v_cvt_pk_bf16_f32 v36, v40, v41
	v_cvt_pk_bf16_f32 v37, v38, v39
	v_lshl_add_u64 v[32:33], v[206:207], 1, v[32:33]
	global_store_dwordx4 v[32:33], v[34:37], off offset:256
.LBB0_2229:
	v_mul_f32_e32 v29, v29, v29
	v_mul_f32_e32 v21, v21, v21
	v_fmac_f32_e32 v29, v28, v28
	v_mul_f32_e32 v28, v31, v31
	v_fmac_f32_e32 v21, v20, v20
	v_mul_f32_e32 v20, v23, v23
	v_fmac_f32_e32 v28, v30, v30
	v_mul_f32_e32 v25, v25, v25
	v_fmac_f32_e32 v20, v22, v22
	v_mul_f32_e32 v17, v17, v17
	v_add_f32_e32 v28, v29, v28
	v_fmac_f32_e32 v25, v24, v24
	v_add_f32_e32 v20, v21, v20
	v_fmac_f32_e32 v17, v16, v16
	v_add_f32_e32 v24, v25, v28
	v_mul_f32_e32 v25, v27, v27
	v_add_f32_e32 v16, v17, v20
	v_mul_f32_e32 v17, v19, v19
	v_fmac_f32_e32 v25, v26, v26
	v_fmac_f32_e32 v17, v18, v18
	v_add_f32_e32 v24, v25, v24
	v_add_f32_e32 v16, v17, v16
	v_add_f32_e32 v16, v24, v16
	v_mov_b32_e32 v17, v16
	s_nop 1
	v_permlane16_swap_b32_e32 v16, v17
	v_add_f32_e32 v16, v16, v17
	v_mov_b32_e32 v17, v16
	s_nop 1
	v_permlane32_swap_b32_e32 v16, v17
	s_and_saveexec_b64 s[34:35], s[8:9]
	s_cbranch_execz .LBB0_2231
	v_add_f32_e32 v18, v16, v17
	s_lshl_b32 s58, s88, 2
	v_lshlrev_b64 v[16:17], 6, v[130:131]
	s_ashr_i32 s59, s58, 31
	v_lshl_add_u64 v[16:17], s[22:23], 0, v[16:17]
	v_lshl_add_u64 v[16:17], s[58:59], 2, v[16:17]
	s_lshl_b32 s96, s83, 2
	v_lshl_add_u64 v[16:17], v[16:17], 0, s[96:97]
	global_store_dword v[16:17], v18, off
.LBB0_2231:
	s_or_b64 exec, exec, s[34:35]
	v_lshlrev_b32_e32 v18, 16, v94
	v_and_b32_e32 v19, 0xffff0000, v94
	v_lshlrev_b32_e32 v20, 16, v95
	v_and_b32_e32 v21, 0xffff0000, v95
	v_lshlrev_b32_e32 v22, 16, v96
	v_and_b32_e32 v23, 0xffff0000, v96
	v_lshlrev_b32_e32 v24, 16, v97
	v_and_b32_e32 v25, 0xffff0000, v97
	v_lshlrev_b64 v[16:17], 10, v[126:127]
	v_pk_fma_f32 v[14:15], v[14:15], v[100:101], v[20:21]
	v_pk_fma_f32 v[12:13], v[12:13], v[98:99], v[18:19]
	v_pk_fma_f32 v[10:11], v[10:11], v[104:105], v[24:25]
	v_pk_fma_f32 v[8:9], v[8:9], v[102:103], v[22:23]
	v_lshl_add_u64 v[18:19], s[18:19], 0, v[128:129]
	v_cvt_pk_bf16_f32 v20, v12, v13
	v_cvt_pk_bf16_f32 v21, v14, v15
	v_cvt_pk_bf16_f32 v22, v8, v9
	v_cvt_pk_bf16_f32 v23, v10, v11
	v_lshl_add_u64 v[18:19], v[206:207], 1, v[18:19]
	s_and_b64 vcc, exec, s[6:7]
	v_lshl_add_u64 v[16:17], v[16:17], 1, s[20:21]
	global_store_dwordx4 v[18:19], v[20:23], off
	s_cbranch_vccnz .LBB0_2233
	s_nop 0
	v_pk_mul_f32 v[22:23], v[80:81], v[14:15]
	v_pk_mul_f32 v[20:21], v[78:79], v[12:13]
	v_pk_mul_f32 v[24:25], v[76:77], v[10:11]
	v_pk_mul_f32 v[26:27], v[74:75], v[8:9]
	v_cvt_pk_bf16_f32 v20, v20, v21
	v_cvt_pk_bf16_f32 v21, v22, v23
	v_cvt_pk_bf16_f32 v22, v26, v27
	v_cvt_pk_bf16_f32 v23, v24, v25
	v_lshl_add_u64 v[24:25], v[206:207], 1, v[16:17]
	global_store_dwordx4 v[24:25], v[20:23], off
.LBB0_2233:
	s_nop 1
	v_lshlrev_b32_e32 v20, 16, v86
	v_and_b32_e32 v21, 0xffff0000, v86
	v_lshlrev_b32_e32 v22, 16, v87
	v_and_b32_e32 v23, 0xffff0000, v87
	v_lshlrev_b32_e32 v24, 16, v88
	v_and_b32_e32 v25, 0xffff0000, v88
	v_lshlrev_b32_e32 v26, 16, v89
	v_and_b32_e32 v27, 0xffff0000, v89
	v_pk_fma_f32 v[6:7], v[6:7], v[84:85], v[22:23]
	v_pk_fma_f32 v[4:5], v[4:5], v[82:83], v[20:21]
	v_pk_fma_f32 v[2:3], v[2:3], v[92:93], v[26:27]
	v_pk_fma_f32 v[0:1], v[0:1], v[90:91], v[24:25]
	v_cvt_pk_bf16_f32 v20, v4, v5
	v_cvt_pk_bf16_f32 v21, v6, v7
	v_cvt_pk_bf16_f32 v22, v0, v1
	v_cvt_pk_bf16_f32 v23, v2, v3
	s_and_b64 vcc, exec, s[6:7]
	global_store_dwordx4 v[18:19], v[20:23], off offset:256
	s_cbranch_vccnz .LBB0_2235
	s_nop 0
	v_pk_mul_f32 v[20:21], v[72:73], v[6:7]
	v_pk_mul_f32 v[18:19], v[70:71], v[4:5]
	v_pk_mul_f32 v[22:23], v[68:69], v[2:3]
	v_pk_mul_f32 v[24:25], v[66:67], v[0:1]
	v_cvt_pk_bf16_f32 v18, v18, v19
	v_cvt_pk_bf16_f32 v19, v20, v21
	v_cvt_pk_bf16_f32 v20, v24, v25
	v_cvt_pk_bf16_f32 v21, v22, v23
	v_lshl_add_u64 v[16:17], v[206:207], 1, v[16:17]
	global_store_dwordx4 v[16:17], v[18:21], off offset:256
.LBB0_2235:
	v_mul_f32_e32 v13, v13, v13
	v_mul_f32_e32 v5, v5, v5
	v_fmac_f32_e32 v13, v12, v12
	v_mul_f32_e32 v12, v15, v15
	v_fmac_f32_e32 v5, v4, v4
	v_mul_f32_e32 v4, v7, v7
	v_fmac_f32_e32 v12, v14, v14
	v_mul_f32_e32 v9, v9, v9
	v_fmac_f32_e32 v4, v6, v6
	v_mul_f32_e32 v1, v1, v1
	v_add_f32_e32 v12, v13, v12
	v_fmac_f32_e32 v9, v8, v8
	v_add_f32_e32 v4, v5, v4
	v_fmac_f32_e32 v1, v0, v0
	v_add_f32_e32 v8, v9, v12
	v_mul_f32_e32 v9, v11, v11
	v_add_f32_e32 v0, v1, v4
	v_mul_f32_e32 v1, v3, v3
	v_fmac_f32_e32 v9, v10, v10
	v_fmac_f32_e32 v1, v2, v2
	v_add_f32_e32 v8, v9, v8
	v_add_f32_e32 v0, v1, v0
	v_add_f32_e32 v0, v8, v0
	v_mov_b32_e32 v1, v0
	s_nop 1
	v_permlane16_swap_b32_e32 v0, v1
	v_add_f32_e32 v0, v0, v1
	v_mov_b32_e32 v1, v0
	s_nop 1
	v_permlane32_swap_b32_e32 v0, v1
	s_and_saveexec_b64 s[6:7], s[8:9]
	s_cbranch_execz .LBB0_2237
	v_add_f32_e32 v2, v0, v1
	s_lshl_b32 s8, s88, 2
	v_lshlrev_b64 v[0:1], 6, v[126:127]
	s_ashr_i32 s9, s8, 31
	v_lshl_add_u64 v[0:1], s[22:23], 0, v[0:1]
	v_lshl_add_u64 v[0:1], s[8:9], 2, v[0:1]
	s_lshl_b32 s96, s83, 2
	v_lshl_add_u64 v[0:1], v[0:1], 0, s[96:97]
	global_store_dword v[0:1], v2, off

.LBB0_2312:
	v_lshl_add_u64 v[26:27], s[40:41], 0, v[4:5]
	global_load_dwordx4 v[10:13], v[0:1], off
	global_load_dwordx4 v[14:17], v[0:1], off offset:1024
	global_load_dwordx4 v[18:21], v[0:1], off offset:2048
	global_load_dwordx4 v[22:25], v[26:27], off
	v_lshl_add_u64 v[28:29], s[40:41], 0, v[2:3]
	v_add_co_u32_e32 v30, vcc, 0x6600000, v28
	v_add_u32_e32 v8, s10, v8
	s_nop 0
	v_addc_co_u32_e32 v31, vcc, 0, v29, vcc
	global_load_dwordx2 v[32:33], v[30:31], off
	global_load_dwordx2 v[34:35], v[30:31], off offset:512
	global_load_dwordx2 v[36:37], v[30:31], off offset:1024
	global_load_dwordx2 v[38:39], v[30:31], off offset:1536
	global_load_dwordx4 v[26:29], v[0:1], off offset:3072
	v_cmp_lt_i32_e32 vcc, s9, v8
	s_or_b64 s[6:7], vcc, s[6:7]
	v_lshl_add_u64 v[2:3], v[2:3], 0, s[0:1]
	v_lshl_add_u64 v[4:5], v[4:5], 0, s[2:3]
	s_waitcnt vmcnt(0) lgkmcnt(0)
	v_mov_b32_e32 v30, v23
	v_mov_b32_e32 v31, v24
	v_mov_b32_e32 v23, v25
	v_pk_add_f32 v[22:23], v[30:31], v[22:23]
	v_lshlrev_b32_e32 v24, 16, v33
	v_add_f32_e32 v42, v22, v23
	v_lshlrev_b32_e32 v22, 16, v32
	v_and_b32_e32 v23, 0xffff0000, v32
	v_add_f32_dpp v42, v42, v42 quad_perm:[1,0,3,2] row_mask:0xf bank_mask:0xf bound_ctrl:1
	v_and_b32_e32 v25, 0xffff0000, v33
	v_lshlrev_b32_e32 v30, 16, v34
	v_add_f32_dpp v42, v42, v42 quad_perm:[2,3,0,1] row_mask:0xf bank_mask:0xf bound_ctrl:1
	v_fmamk_f32 v42, v42, 0x3a800000, v9
	v_mul_f32_e32 v43, 0x4b800000, v42
	v_cmp_gt_f32_e32 vcc, s8, v42
	v_and_b32_e32 v31, 0xffff0000, v34
	v_lshlrev_b32_e32 v32, 16, v35
	v_cndmask_b32_e32 v42, v42, v43, vcc
	v_rsq_f32_e32 v42, v42
	v_and_b32_e32 v33, 0xffff0000, v35
	v_lshlrev_b32_e32 v34, 16, v36
	v_and_b32_e32 v35, 0xffff0000, v36
	v_mul_f32_e32 v43, 0x45800000, v42
	v_cndmask_b32_e32 v42, v42, v43, vcc
	v_lshlrev_b32_e32 v36, 16, v37
	v_and_b32_e32 v37, 0xffff0000, v37
	v_lshlrev_b32_e32 v40, 16, v38
	v_and_b32_e32 v41, 0xffff0000, v38
	v_lshlrev_b32_e32 v38, 16, v39
	v_and_b32_e32 v39, 0xffff0000, v39
	v_pk_mul_f32 v[22:23], v[42:43], v[22:23] op_sel_hi:[0,1]
	v_pk_mul_f32 v[24:25], v[42:43], v[24:25] op_sel_hi:[0,1]
	v_pk_mul_f32 v[30:31], v[42:43], v[30:31] op_sel_hi:[0,1]
	v_pk_mul_f32 v[32:33], v[42:43], v[32:33] op_sel_hi:[0,1]
	v_pk_mul_f32 v[34:35], v[42:43], v[34:35] op_sel_hi:[0,1]
	v_pk_mul_f32 v[36:37], v[42:43], v[36:37] op_sel_hi:[0,1]
	v_pk_mul_f32 v[40:41], v[42:43], v[40:41] op_sel_hi:[0,1]
	v_pk_mul_f32 v[38:39], v[42:43], v[38:39] op_sel_hi:[0,1]
	v_pk_mul_f32 v[12:13], v[12:13], v[24:25]
	v_pk_mul_f32 v[10:11], v[10:11], v[22:23]
	v_pk_mul_f32 v[16:17], v[16:17], v[32:33]
	v_pk_mul_f32 v[14:15], v[14:15], v[30:31]
	v_pk_mul_f32 v[20:21], v[20:21], v[36:37]
	v_pk_mul_f32 v[18:19], v[18:19], v[34:35]
	v_pk_mul_f32 v[24:25], v[28:29], v[38:39]
	v_pk_mul_f32 v[22:23], v[26:27], v[40:41]
	global_store_dwordx4 v[6:7], v[10:13], off offset:-3072
	global_store_dwordx4 v[6:7], v[14:17], off offset:-2048
	global_store_dwordx4 v[6:7], v[18:21], off offset:-1024
	global_store_dwordx4 v[6:7], v[22:25], off
	v_lshl_add_u64 v[6:7], v[6:7], 0, s[4:5]
	s_andn2_b64 exec, exec, s[6:7]
	s_cbranch_execnz .LBB0_2312
